# GEMM K-loops: adjacent s_setprio 0/1 pairs inside each 32-MFMA super-phase removed (on v6)
# speedup vs baseline: 1.0025x; 1.0025x over previous
; #define PG8_STAGE(bufoff, gbase, voff) do { _Pragma("unroll") for (int _i = 0; _i < 2; ++_i) \
;         __builtin_amdgcn_global_load_lds((const unsigned*)((const char*)(gbase) + (voff)[_i]), (PG8_LAS unsigned*)(lds + (bufoff) + ldsw + _i * 8192), 16, 0, 0); } while (0)
; #define PG8_LDA(dst, b, h) do { _Pragma("unroll") for (int m = 0; m < 4; ++m) _Pragma("unroll") for (int k = 0; k < 2; ++k) dst[m][k] = *(const PG8_LAS bf16x8*)(lds + PG8_SA(b, h) + aoff + m * 2048 + k * 1024); } while (0)
; #define PG8_LDB(dst, b, h) do { _Pragma("unroll") for (int n = 0; n < 2; ++n) _Pragma("unroll") for (int k = 0; k < 2; ++k) dst[n][k] = *(const PG8_LAS bf16x8*)(lds + PG8_SB(b, h) + boff + n * 2048 + k * 1024); } while (0)
; #define PG8_MMA(ai, bj, At, Bt) do { __builtin_amdgcn_s_setprio(1); _Pragma("unroll") for (int m = 0; m < 4; ++m) _Pragma("unroll") for (int n = 0; n < 2; ++n) _Pragma("unroll") for (int k = 0; k < 2; ++k) \
;         acc[ai][bj][m][n] = __builtin_amdgcn_mfma_f32_16x16x32_bf16(Bt[n][k], At[m][k], acc[ai][bj][m][n], 0, 0, 0); __builtin_amdgcn_s_setprio(0); } while (0)
; #define PG8_WAIT_V(n) asm volatile("s_waitcnt vmcnt(" #n ")" ::: "memory")
; #define PG8_WAIT_L(n) asm volatile("s_waitcnt lgkmcnt(" #n ")" ::: "memory")
; #define PG8_BAR __builtin_amdgcn_s_barrier()
; #define PG8_SCHED __builtin_amdgcn_sched_barrier(0)
; template <class Epi, class Sched, bool ALIGN_EPI = false, bool SP2 = false>
; __device__ __forceinline__ void gemm_phase(PG8_LAS unsigned char* lds, const Gemm g, const Sched& S, const Epi& E) {
;     ...
;             PG8_LDB(B0, 0, 0); PG8_LDB(B1, 0, 1); PG8_SCHED; PG8_LDA(At, 0, 0); PG8_STAGE(PG8_SA(1, 1), a1 + hstep, voffA);
;             PG8_WAIT_V(8); PG8_WAIT_L(0); PG8_BAR; PG8_MMA(0, 0, At, B0); PG8_MMA(0, 1, At, B1); PG8_BAR; PG8_SCHED;
;             PG8_LDA(At, 0, 1); PG8_STAGE(PG8_SB(0, 0), b2, voffB); PG8_STAGE(PG8_SB(0, 1), b2 + hstep, voffB); PG8_STAGE(PG8_SA(0, 0), a2, voffA);
;             PG8_WAIT_V(8); PG8_WAIT_L(0); PG8_BAR; PG8_MMA(1, 0, At, B0); PG8_MMA(1, 1, At, B1); PG8_BAR; PG8_SCHED;
.LBB0_1643:
	ds_read_b128 v[144:147], v178
	ds_read_b128 v[150:153], v178 offset:1024
	ds_read_b128 v[156:159], v178 offset:2048
	ds_read_b128 v[182:185], v178 offset:3072
	ds_read_b128 v[186:189], v179
	ds_read_b128 v[190:193], v179 offset:1024
	ds_read_b128 v[194:197], v179 offset:2048
	ds_read_b128 v[198:201], v179 offset:3072
	s_add_i32 s60, s26, 2
	s_add_u32 s61, s24, 0x80
	s_addc_u32 s27, s25, 0
	s_cmp_eq_u32 s49, s26
	s_cselect_b32 s26, s0, s61
	s_cselect_b32 s27, s1, s27
	s_cselect_b32 s63, s23, s59
	s_cselect_b32 s62, s22, s58
	v_lshl_add_u64 v[162:163], s[24:25], 0, v[140:141]
	s_add_i32 m0, s41, 0xc000
	ds_read_b128 v[202:205], v180
	ds_read_b128 v[206:209], v180 offset:1024
	ds_read_b128 v[210:213], v180 offset:2048
	ds_read_b128 v[214:217], v180 offset:3072
	ds_read_b128 v[222:225], v180 offset:4096
	ds_read_b128 v[226:229], v180 offset:5120
	ds_read_b128 v[230:233], v180 offset:6144
	ds_read_b128 v[234:237], v180 offset:7168
	global_load_lds_dwordx4 v[162:163], off
	v_lshl_add_u64 v[162:163], s[24:25], 0, v[138:139]
	s_add_i32 m0, s41, 0xe000
	s_nop 0
	global_load_lds_dwordx4 v[162:163], off
	s_waitcnt vmcnt(8)
	s_waitcnt lgkmcnt(0)
	s_barrier
	s_setprio 1
	s_waitcnt lgkmcnt(0)
	v_mfma_f32_16x16x32_bf16 v[124:127], v[144:147], v[202:205], v[124:127]
	v_mfma_f32_16x16x32_bf16 v[120:123], v[156:159], v[202:205], v[120:123]
	v_mfma_f32_16x16x32_bf16 v[108:111], v[144:147], v[210:213], v[108:111]
	v_mfma_f32_16x16x32_bf16 v[104:107], v[156:159], v[210:213], v[104:107]
	v_mfma_f32_16x16x32_bf16 v[92:95], v[144:147], v[222:225], v[92:95]
	v_mfma_f32_16x16x32_bf16 v[88:91], v[156:159], v[222:225], v[88:91]
	v_mfma_f32_16x16x32_bf16 v[76:79], v[144:147], v[230:233], v[76:79]
	v_mfma_f32_16x16x32_bf16 v[72:75], v[156:159], v[230:233], v[72:75]
	v_mfma_f32_16x16x32_bf16 v[124:127], v[150:153], v[206:209], v[124:127]
	v_mfma_f32_16x16x32_bf16 v[120:123], v[182:185], v[206:209], v[120:123]
	v_mfma_f32_16x16x32_bf16 v[108:111], v[150:153], v[214:217], v[108:111]
	v_mfma_f32_16x16x32_bf16 v[104:107], v[182:185], v[214:217], v[104:107]
	v_mfma_f32_16x16x32_bf16 v[92:95], v[150:153], v[226:229], v[92:95]
	v_mfma_f32_16x16x32_bf16 v[88:91], v[182:185], v[226:229], v[88:91]
	v_mfma_f32_16x16x32_bf16 v[76:79], v[150:153], v[234:237], v[76:79]
	v_mfma_f32_16x16x32_bf16 v[72:75], v[182:185], v[234:237], v[72:75]
	v_mfma_f32_16x16x32_bf16 v[116:119], v[186:189], v[202:205], v[116:119]
	v_mfma_f32_16x16x32_bf16 v[112:115], v[194:197], v[202:205], v[112:115]
	v_mfma_f32_16x16x32_bf16 v[100:103], v[186:189], v[210:213], v[100:103]
	v_mfma_f32_16x16x32_bf16 v[96:99], v[194:197], v[210:213], v[96:99]
	v_mfma_f32_16x16x32_bf16 v[84:87], v[186:189], v[222:225], v[84:87]
	v_mfma_f32_16x16x32_bf16 v[80:83], v[194:197], v[222:225], v[80:83]
	v_mfma_f32_16x16x32_bf16 v[68:71], v[186:189], v[230:233], v[68:71]
	v_mfma_f32_16x16x32_bf16 v[64:67], v[194:197], v[230:233], v[64:67]
	v_mfma_f32_16x16x32_bf16 v[116:119], v[190:193], v[206:209], v[116:119]
	v_mfma_f32_16x16x32_bf16 v[112:115], v[198:201], v[206:209], v[112:115]
	v_mfma_f32_16x16x32_bf16 v[100:103], v[190:193], v[214:217], v[100:103]
	v_mfma_f32_16x16x32_bf16 v[96:99], v[198:201], v[214:217], v[96:99]
	v_mfma_f32_16x16x32_bf16 v[84:87], v[190:193], v[226:229], v[84:87]
	v_mfma_f32_16x16x32_bf16 v[80:83], v[198:201], v[226:229], v[80:83]
	v_mfma_f32_16x16x32_bf16 v[68:71], v[190:193], v[234:237], v[68:71]
	v_mfma_f32_16x16x32_bf16 v[64:67], v[198:201], v[234:237], v[64:67]
	s_setprio 0
	s_barrier
	s_add_i32 s61, s52, s38
	v_lshl_add_u64 v[162:163], s[62:63], 0, v[130:131]
	s_mov_b32 m0, s61
	ds_read_b128 v[202:205], v180 offset:16384
	ds_read_b128 v[206:209], v180 offset:17408
	ds_read_b128 v[210:213], v180 offset:18432
	ds_read_b128 v[214:217], v180 offset:19456
	ds_read_b128 v[222:225], v180 offset:20480
	ds_read_b128 v[226:229], v180 offset:21504
	ds_read_b128 v[230:233], v180 offset:22528
	ds_read_b128 v[234:237], v180 offset:23552
	global_load_lds_dwordx4 v[162:163], off
	s_add_i32 m0, s61, 0x2000
	v_lshl_add_u64 v[166:167], s[62:63], 0, v[134:135]
	s_add_u32 s62, s62, s8
	s_addc_u32 s63, s63, s9
	s_add_i32 s61, s53, s38
	global_load_lds_dwordx4 v[166:167], off
	v_lshl_add_u64 v[218:219], s[62:63], 0, v[130:131]
	s_mov_b32 m0, s61
	v_lshl_add_u64 v[238:239], s[62:63], 0, v[134:135]
	global_load_lds_dwordx4 v[218:219], off
	s_add_i32 m0, s61, 0x2000
	v_lshl_add_u64 v[240:241], s[26:27], 0, v[128:129]
	global_load_lds_dwordx4 v[238:239], off
	s_mov_b32 m0, s41
	v_lshl_add_u64 v[242:243], s[26:27], 0, v[132:133]
	global_load_lds_dwordx4 v[240:241], off
	s_mov_b32 m0, s42
	s_nop 0
	global_load_lds_dwordx4 v[242:243], off
	s_waitcnt vmcnt(8)
	s_waitcnt lgkmcnt(0)
	s_barrier
; #define PG8_STAGE(bufoff, gbase, voff) do { _Pragma("unroll") for (int _i = 0; _i < 2; ++_i) \
;         __builtin_amdgcn_global_load_lds((const unsigned*)((const char*)(gbase) + (voff)[_i]), (PG8_LAS unsigned*)(lds + (bufoff) + ldsw + _i * 8192), 16, 0, 0); } while (0)
; #define PG8_LDA(dst, b, h) do { _Pragma("unroll") for (int m = 0; m < 4; ++m) _Pragma("unroll") for (int k = 0; k < 2; ++k) dst[m][k] = *(const PG8_LAS bf16x8*)(lds + PG8_SA(b, h) + aoff + m * 2048 + k * 1024); } while (0)
; #define PG8_LDB(dst, b, h) do { _Pragma("unroll") for (int n = 0; n < 2; ++n) _Pragma("unroll") for (int k = 0; k < 2; ++k) dst[n][k] = *(const PG8_LAS bf16x8*)(lds + PG8_SB(b, h) + boff + n * 2048 + k * 1024); } while (0)
; #define PG8_MMA(ai, bj, At, Bt) do { __builtin_amdgcn_s_setprio(1); _Pragma("unroll") for (int m = 0; m < 4; ++m) _Pragma("unroll") for (int n = 0; n < 2; ++n) _Pragma("unroll") for (int k = 0; k < 2; ++k) \
;         acc[ai][bj][m][n] = __builtin_amdgcn_mfma_f32_16x16x32_bf16(Bt[n][k], At[m][k], acc[ai][bj][m][n], 0, 0, 0); __builtin_amdgcn_s_setprio(0); } while (0)
; #define PG8_WAIT_V(n) asm volatile("s_waitcnt vmcnt(" #n ")" ::: "memory")
; #define PG8_WAIT_L(n) asm volatile("s_waitcnt lgkmcnt(" #n ")" ::: "memory")
; #define PG8_BAR __builtin_amdgcn_s_barrier()
; #define PG8_SCHED __builtin_amdgcn_sched_barrier(0)
; template <class Epi, class Sched, bool ALIGN_EPI = false, bool SP2 = false>
; __device__ __forceinline__ void gemm_phase(PG8_LAS unsigned char* lds, const Gemm g, const Sched& S, const Epi& E) {
;     ...
;             PG8_WAIT_V(8); PG8_WAIT_L(0); PG8_BAR; PG8_MMA(1, 0, At, B0); PG8_MMA(1, 1, At, B1); PG8_BAR; PG8_SCHED;
;             PG8_LDB(B0, 1, 0); PG8_LDB(B1, 1, 1); PG8_SCHED; PG8_LDA(At, 1, 0); PG8_STAGE(PG8_SA(0, 1), a2 + hstep, voffA);
;             PG8_WAIT_V(8); PG8_WAIT_L(0); PG8_BAR; PG8_MMA(0, 0, At, B0); PG8_MMA(0, 1, At, B1); PG8_BAR; PG8_SCHED;
	s_setprio 1
	s_waitcnt lgkmcnt(0)
	v_mfma_f32_16x16x32_bf16 v[60:63], v[144:147], v[202:205], v[60:63]
	v_mfma_f32_16x16x32_bf16 v[56:59], v[156:159], v[202:205], v[56:59]
	v_mfma_f32_16x16x32_bf16 v[44:47], v[144:147], v[210:213], v[44:47]
	v_mfma_f32_16x16x32_bf16 v[40:43], v[156:159], v[210:213], v[40:43]
	v_mfma_f32_16x16x32_bf16 v[28:31], v[144:147], v[222:225], v[28:31]
	v_mfma_f32_16x16x32_bf16 v[24:27], v[156:159], v[222:225], v[24:27]
	v_mfma_f32_16x16x32_bf16 v[12:15], v[144:147], v[230:233], v[12:15]
	v_mfma_f32_16x16x32_bf16 v[8:11], v[156:159], v[230:233], v[8:11]
	v_mfma_f32_16x16x32_bf16 v[60:63], v[150:153], v[206:209], v[60:63]
	v_mfma_f32_16x16x32_bf16 v[56:59], v[182:185], v[206:209], v[56:59]
	v_mfma_f32_16x16x32_bf16 v[44:47], v[150:153], v[214:217], v[44:47]
	v_mfma_f32_16x16x32_bf16 v[40:43], v[182:185], v[214:217], v[40:43]
	v_mfma_f32_16x16x32_bf16 v[28:31], v[150:153], v[226:229], v[28:31]
	v_mfma_f32_16x16x32_bf16 v[24:27], v[182:185], v[226:229], v[24:27]
	v_mfma_f32_16x16x32_bf16 v[12:15], v[150:153], v[234:237], v[12:15]
	v_mfma_f32_16x16x32_bf16 v[8:11], v[182:185], v[234:237], v[8:11]
	v_mfma_f32_16x16x32_bf16 v[52:55], v[186:189], v[202:205], v[52:55]
	v_mfma_f32_16x16x32_bf16 v[48:51], v[194:197], v[202:205], v[48:51]
	v_mfma_f32_16x16x32_bf16 v[36:39], v[186:189], v[210:213], v[36:39]
	v_mfma_f32_16x16x32_bf16 v[32:35], v[194:197], v[210:213], v[32:35]
	v_mfma_f32_16x16x32_bf16 v[20:23], v[186:189], v[222:225], v[20:23]
	v_mfma_f32_16x16x32_bf16 v[16:19], v[194:197], v[222:225], v[16:19]
	v_mfma_f32_16x16x32_bf16 v[4:7], v[186:189], v[230:233], v[4:7]
	v_mfma_f32_16x16x32_bf16 v[0:3], v[194:197], v[230:233], v[0:3]
	v_mfma_f32_16x16x32_bf16 v[52:55], v[190:193], v[206:209], v[52:55]
	v_mfma_f32_16x16x32_bf16 v[48:51], v[198:201], v[206:209], v[48:51]
	v_mfma_f32_16x16x32_bf16 v[36:39], v[190:193], v[214:217], v[36:39]
	v_mfma_f32_16x16x32_bf16 v[32:35], v[198:201], v[214:217], v[32:35]
	v_mfma_f32_16x16x32_bf16 v[20:23], v[190:193], v[226:229], v[20:23]
	v_mfma_f32_16x16x32_bf16 v[16:19], v[198:201], v[226:229], v[16:19]
	v_mfma_f32_16x16x32_bf16 v[4:7], v[190:193], v[234:237], v[4:7]
	v_mfma_f32_16x16x32_bf16 v[0:3], v[198:201], v[234:237], v[0:3]
	s_setprio 0
	s_barrier
	s_add_i32 s61, 0, 0x18000
	v_add_u32_e32 v148, s61, v174
	s_add_i32 s62, 0, 0x1c000
	ds_read_b128 v[144:147], v148
	ds_read_b128 v[150:153], v148 offset:1024
	ds_read_b128 v[156:159], v148 offset:2048
	ds_read_b128 v[182:185], v148 offset:3072
	v_add_u32_e32 v148, s62, v174
	ds_read_b128 v[186:189], v148
	ds_read_b128 v[190:193], v148 offset:1024
	ds_read_b128 v[194:197], v148 offset:2048
	ds_read_b128 v[198:201], v148 offset:3072
	s_add_u32 s26, s26, s8
	s_addc_u32 s27, s27, s9
	s_mov_b32 m0, s43
	v_lshl_add_u64 v[244:245], s[26:27], 0, v[128:129]
	ds_read_b128 v[202:205], v180 offset:32768
	ds_read_b128 v[206:209], v180 offset:33792
	ds_read_b128 v[210:213], v180 offset:34816
	ds_read_b128 v[214:217], v180 offset:35840
	ds_read_b128 v[222:225], v180 offset:36864
	ds_read_b128 v[226:229], v180 offset:37888
	ds_read_b128 v[230:233], v180 offset:38912
	ds_read_b128 v[234:237], v180 offset:39936
	global_load_lds_dwordx4 v[244:245], off
	v_lshl_add_u64 v[244:245], s[26:27], 0, v[132:133]
	s_mov_b32 m0, s44
	s_nop 0
	global_load_lds_dwordx4 v[244:245], off
	s_waitcnt vmcnt(8)
	s_waitcnt lgkmcnt(0)
	s_barrier
	s_setprio 1
	s_waitcnt lgkmcnt(0)
	v_mfma_f32_16x16x32_bf16 v[124:127], v[144:147], v[202:205], v[124:127]
	v_mfma_f32_16x16x32_bf16 v[120:123], v[156:159], v[202:205], v[120:123]
	v_mfma_f32_16x16x32_bf16 v[108:111], v[144:147], v[210:213], v[108:111]
	v_mfma_f32_16x16x32_bf16 v[104:107], v[156:159], v[210:213], v[104:107]
	v_mfma_f32_16x16x32_bf16 v[92:95], v[144:147], v[222:225], v[92:95]
	v_mfma_f32_16x16x32_bf16 v[88:91], v[156:159], v[222:225], v[88:91]
	v_mfma_f32_16x16x32_bf16 v[76:79], v[144:147], v[230:233], v[76:79]
	v_mfma_f32_16x16x32_bf16 v[72:75], v[156:159], v[230:233], v[72:75]
	v_mfma_f32_16x16x32_bf16 v[124:127], v[150:153], v[206:209], v[124:127]
	v_mfma_f32_16x16x32_bf16 v[120:123], v[182:185], v[206:209], v[120:123]
	v_mfma_f32_16x16x32_bf16 v[108:111], v[150:153], v[214:217], v[108:111]
	v_mfma_f32_16x16x32_bf16 v[104:107], v[182:185], v[214:217], v[104:107]
	v_mfma_f32_16x16x32_bf16 v[92:95], v[150:153], v[226:229], v[92:95]
	v_mfma_f32_16x16x32_bf16 v[88:91], v[182:185], v[226:229], v[88:91]
	v_mfma_f32_16x16x32_bf16 v[76:79], v[150:153], v[234:237], v[76:79]
	v_mfma_f32_16x16x32_bf16 v[72:75], v[182:185], v[234:237], v[72:75]
	v_mfma_f32_16x16x32_bf16 v[116:119], v[186:189], v[202:205], v[116:119]
	v_mfma_f32_16x16x32_bf16 v[112:115], v[194:197], v[202:205], v[112:115]
	v_mfma_f32_16x16x32_bf16 v[100:103], v[186:189], v[210:213], v[100:103]
	v_mfma_f32_16x16x32_bf16 v[96:99], v[194:197], v[210:213], v[96:99]
	v_mfma_f32_16x16x32_bf16 v[84:87], v[186:189], v[222:225], v[84:87]
	v_mfma_f32_16x16x32_bf16 v[80:83], v[194:197], v[222:225], v[80:83]
	v_mfma_f32_16x16x32_bf16 v[68:71], v[186:189], v[230:233], v[68:71]
	v_mfma_f32_16x16x32_bf16 v[64:67], v[194:197], v[230:233], v[64:67]
	v_mfma_f32_16x16x32_bf16 v[116:119], v[190:193], v[206:209], v[116:119]
	v_mfma_f32_16x16x32_bf16 v[112:115], v[198:201], v[206:209], v[112:115]
	v_mfma_f32_16x16x32_bf16 v[100:103], v[190:193], v[214:217], v[100:103]
	v_mfma_f32_16x16x32_bf16 v[96:99], v[198:201], v[214:217], v[96:99]
	v_mfma_f32_16x16x32_bf16 v[84:87], v[190:193], v[226:229], v[84:87]
	v_mfma_f32_16x16x32_bf16 v[80:83], v[198:201], v[226:229], v[80:83]
	v_mfma_f32_16x16x32_bf16 v[68:71], v[190:193], v[234:237], v[68:71]
	v_mfma_f32_16x16x32_bf16 v[64:67], v[198:201], v[234:237], v[64:67]
	s_setprio 0
	s_barrier
; #define PG8_STAGE(bufoff, gbase, voff) do { _Pragma("unroll") for (int _i = 0; _i < 2; ++_i) \
;         __builtin_amdgcn_global_load_lds((const unsigned*)((const char*)(gbase) + (voff)[_i]), (PG8_LAS unsigned*)(lds + (bufoff) + ldsw + _i * 8192), 16, 0, 0); } while (0)
; #define PG8_LDA(dst, b, h) do { _Pragma("unroll") for (int m = 0; m < 4; ++m) _Pragma("unroll") for (int k = 0; k < 2; ++k) dst[m][k] = *(const PG8_LAS bf16x8*)(lds + PG8_SA(b, h) + aoff + m * 2048 + k * 1024); } while (0)
; #define PG8_MMA(ai, bj, At, Bt) do { __builtin_amdgcn_s_setprio(1); _Pragma("unroll") for (int m = 0; m < 4; ++m) _Pragma("unroll") for (int n = 0; n < 2; ++n) _Pragma("unroll") for (int k = 0; k < 2; ++k) \
;         acc[ai][bj][m][n] = __builtin_amdgcn_mfma_f32_16x16x32_bf16(Bt[n][k], At[m][k], acc[ai][bj][m][n], 0, 0, 0); __builtin_amdgcn_s_setprio(0); } while (0)
; #define PG8_WAIT_V(n) asm volatile("s_waitcnt vmcnt(" #n ")" ::: "memory")
; #define PG8_WAIT_L(n) asm volatile("s_waitcnt lgkmcnt(" #n ")" ::: "memory")
; #define PG8_BAR __builtin_amdgcn_s_barrier()
; #define PG8_SCHED __builtin_amdgcn_sched_barrier(0)
; template <class Epi, class Sched, bool ALIGN_EPI = false, bool SP2 = false>
; __device__ __forceinline__ void gemm_phase(PG8_LAS unsigned char* lds, const Gemm g, const Sched& S, const Epi& E) {
;     ...
;         for (int t = 0; t < nt; t += 2) {
;             const bool last = (t == nt - 2);
;             const char* a1 = cA + (size_t)(t + 1) * kstep;
;             const char* a2 = last ? nA : cA + (size_t)(t + 2) * kstep; const char* b2 = last ? nB : cB + (size_t)(t + 2) * kstep;
;     ...
;             PG8_LDA(At, 1, 1); PG8_STAGE(PG8_SB(1, 0), b3, voffB); PG8_STAGE(PG8_SB(1, 1), b3 + hstep, voffB); PG8_STAGE(PG8_SA(1, 0), a3, voffA);
;             PG8_WAIT_V(8); PG8_WAIT_L(0); PG8_BAR; PG8_MMA(1, 0, At, B0); PG8_MMA(1, 1, At, B1); PG8_BAR; PG8_SCHED;
	s_add_i32 s26, s61, s38
	v_lshl_add_u64 v[162:163], v[162:163], 0, s[16:17]
	s_mov_b32 m0, s26
	ds_read_b128 v[202:205], v180 offset:49152
	ds_read_b128 v[206:209], v180 offset:50176
	ds_read_b128 v[210:213], v180 offset:51200
	ds_read_b128 v[214:217], v180 offset:52224
	ds_read_b128 v[222:225], v180 offset:53248
	ds_read_b128 v[226:229], v180 offset:54272
	ds_read_b128 v[230:233], v180 offset:55296
	ds_read_b128 v[234:237], v180 offset:56320
	global_load_lds_dwordx4 v[162:163], off
	v_lshl_add_u64 v[162:163], v[166:167], 0, s[16:17]
	s_add_i32 m0, s26, 0x2000
	s_add_i32 s26, s62, s38
	global_load_lds_dwordx4 v[162:163], off
	v_lshl_add_u64 v[162:163], v[218:219], 0, s[16:17]
	s_mov_b32 m0, s26
	s_nop 0
	global_load_lds_dwordx4 v[162:163], off
	v_lshl_add_u64 v[162:163], v[238:239], 0, s[16:17]
	s_add_i32 m0, s26, 0x2000
	s_nop 0
	global_load_lds_dwordx4 v[162:163], off
	v_lshl_add_u64 v[162:163], v[240:241], 0, s[16:17]
	s_mov_b32 m0, s46
	s_nop 0
	global_load_lds_dwordx4 v[162:163], off
	v_lshl_add_u64 v[162:163], v[242:243], 0, s[16:17]
	s_mov_b32 m0, s47
	s_nop 0
	global_load_lds_dwordx4 v[162:163], off
	s_waitcnt vmcnt(8)
	s_waitcnt lgkmcnt(0)
	s_barrier
	s_setprio 1
	s_waitcnt lgkmcnt(0)
	v_mfma_f32_16x16x32_bf16 v[60:63], v[144:147], v[202:205], v[60:63]
	v_mfma_f32_16x16x32_bf16 v[56:59], v[156:159], v[202:205], v[56:59]
	v_mfma_f32_16x16x32_bf16 v[44:47], v[144:147], v[210:213], v[44:47]
	v_mfma_f32_16x16x32_bf16 v[40:43], v[156:159], v[210:213], v[40:43]
	v_mfma_f32_16x16x32_bf16 v[28:31], v[144:147], v[222:225], v[28:31]
	v_mfma_f32_16x16x32_bf16 v[24:27], v[156:159], v[222:225], v[24:27]
	v_mfma_f32_16x16x32_bf16 v[12:15], v[144:147], v[230:233], v[12:15]
	v_mfma_f32_16x16x32_bf16 v[8:11], v[156:159], v[230:233], v[8:11]
	v_mfma_f32_16x16x32_bf16 v[60:63], v[150:153], v[206:209], v[60:63]
	v_mfma_f32_16x16x32_bf16 v[56:59], v[182:185], v[206:209], v[56:59]
	v_mfma_f32_16x16x32_bf16 v[44:47], v[150:153], v[214:217], v[44:47]
	v_mfma_f32_16x16x32_bf16 v[40:43], v[182:185], v[214:217], v[40:43]
	v_mfma_f32_16x16x32_bf16 v[28:31], v[150:153], v[226:229], v[28:31]
	v_mfma_f32_16x16x32_bf16 v[24:27], v[182:185], v[226:229], v[24:27]
	v_mfma_f32_16x16x32_bf16 v[12:15], v[150:153], v[234:237], v[12:15]
	v_mfma_f32_16x16x32_bf16 v[8:11], v[182:185], v[234:237], v[8:11]
	v_mfma_f32_16x16x32_bf16 v[52:55], v[186:189], v[202:205], v[52:55]
	v_mfma_f32_16x16x32_bf16 v[48:51], v[194:197], v[202:205], v[48:51]
	v_mfma_f32_16x16x32_bf16 v[36:39], v[186:189], v[210:213], v[36:39]
	v_mfma_f32_16x16x32_bf16 v[32:35], v[194:197], v[210:213], v[32:35]
	v_mfma_f32_16x16x32_bf16 v[20:23], v[186:189], v[222:225], v[20:23]
	v_mfma_f32_16x16x32_bf16 v[16:19], v[194:197], v[222:225], v[16:19]
	v_mfma_f32_16x16x32_bf16 v[4:7], v[186:189], v[230:233], v[4:7]
	v_mfma_f32_16x16x32_bf16 v[0:3], v[194:197], v[230:233], v[0:3]
	v_mfma_f32_16x16x32_bf16 v[52:55], v[190:193], v[206:209], v[52:55]
	v_mfma_f32_16x16x32_bf16 v[48:51], v[198:201], v[206:209], v[48:51]
	v_mfma_f32_16x16x32_bf16 v[36:39], v[190:193], v[214:217], v[36:39]
	v_mfma_f32_16x16x32_bf16 v[32:35], v[198:201], v[214:217], v[32:35]
	v_mfma_f32_16x16x32_bf16 v[20:23], v[190:193], v[226:229], v[20:23]
	v_mfma_f32_16x16x32_bf16 v[16:19], v[198:201], v[226:229], v[16:19]
	v_mfma_f32_16x16x32_bf16 v[4:7], v[190:193], v[234:237], v[4:7]
	v_mfma_f32_16x16x32_bf16 v[0:3], v[198:201], v[234:237], v[0:3]
	s_setprio 0
	s_barrier
	s_add_u32 s58, s58, 0x100
	s_addc_u32 s59, s59, 0
	s_add_u32 s24, s24, 0x100
	s_addc_u32 s25, s25, 0
	s_cmp_ge_i32 s60, s48
	s_mov_b32 s26, s60
	s_cbranch_scc0 .LBB0_1643

; #define PG8_STAGE(bufoff, gbase, voff) do { _Pragma("unroll") for (int _i = 0; _i < 2; ++_i) \
;         __builtin_amdgcn_global_load_lds((const unsigned*)((const char*)(gbase) + (voff)[_i]), (PG8_LAS unsigned*)(lds + (bufoff) + ldsw + _i * 8192), 16, 0, 0); } while (0)
; #define PG8_LDA(dst, b, h) do { _Pragma("unroll") for (int m = 0; m < 4; ++m) _Pragma("unroll") for (int k = 0; k < 2; ++k) dst[m][k] = *(const PG8_LAS bf16x8*)(lds + PG8_SA(b, h) + aoff + m * 2048 + k * 1024); } while (0)
; #define PG8_LDB(dst, b, h) do { _Pragma("unroll") for (int n = 0; n < 2; ++n) _Pragma("unroll") for (int k = 0; k < 2; ++k) dst[n][k] = *(const PG8_LAS bf16x8*)(lds + PG8_SB(b, h) + boff + n * 2048 + k * 1024); } while (0)
; #define PG8_MMA(ai, bj, At, Bt) do { __builtin_amdgcn_s_setprio(1); _Pragma("unroll") for (int m = 0; m < 4; ++m) _Pragma("unroll") for (int n = 0; n < 2; ++n) _Pragma("unroll") for (int k = 0; k < 2; ++k) \
;         acc[ai][bj][m][n] = __builtin_amdgcn_mfma_f32_16x16x32_bf16(Bt[n][k], At[m][k], acc[ai][bj][m][n], 0, 0, 0); __builtin_amdgcn_s_setprio(0); } while (0)
; #define PG8_WAIT_V(n) asm volatile("s_waitcnt vmcnt(" #n ")" ::: "memory")
; #define PG8_BAR __builtin_amdgcn_s_barrier()
; template <class Epi, class Sched, bool ALIGN_EPI = false, bool SP2 = false>
; __device__ __forceinline__ void gemm_phase(PG8_LAS unsigned char* lds, const Gemm g, const Sched& S, const Epi& E) {
;     ...
;         for (int t = 0; t < nt; t += 2) {
;             const bool last = (t == nt - 2);
;             const char* a1 = cA + (size_t)(t + 1) * kstep;
;             const char* a2 = last ? nA : cA + (size_t)(t + 2) * kstep; const char* b2 = last ? nB : cB + (size_t)(t + 2) * kstep;
;             const char* a3 = a2 + kstep; const char* b3 = b2 + kstep;
;             if (last && has_next) S.a_ready(nxt);
;             if constexpr (SP2) {
;             PG8_LDB(B0, 0, 0); PG8_LDB(B1, 0, 1); PG8_SCHED; PG8_LDA(At, 0, 0); PG8_STAGE(PG8_SA(1, 1), a1 + hstep, voffA);
;             PG8_WAIT_V(8); PG8_WAIT_L(0); PG8_BAR; PG8_MMA(0, 0, At, B0); PG8_MMA(0, 1, At, B1); PG8_BAR; PG8_SCHED;
;             PG8_LDA(At, 0, 1); PG8_STAGE(PG8_SB(0, 0), b2, voffB); PG8_STAGE(PG8_SB(0, 1), b2 + hstep, voffB); PG8_STAGE(PG8_SA(0, 0), a2, voffA);
;             PG8_WAIT_V(8); PG8_WAIT_L(0); PG8_BAR; PG8_MMA(1, 0, At, B0); PG8_MMA(1, 1, At, B1); PG8_BAR; PG8_SCHED;
.LBB0_3165:
	s_add_i32 s61, s34, 2
	s_add_u32 s62, s30, 0x80
	s_addc_u32 s35, s31, 0
	s_add_i32 s64, 0, 0x10000
	s_cmp_eq_u32 s53, s34
	s_cselect_b32 s35, s1, s35
	s_cselect_b32 s34, s0, s62
	v_add_u32_e32 v148, s64, v151
	s_cselect_b32 s63, s29, s60
	s_cselect_b32 s62, s28, s59
	s_add_i32 s65, 0, 0x14000
	ds_read_b128 v[130:133], v148
	ds_read_b128 v[156:159], v148 offset:1024
	ds_read_b128 v[162:165], v148 offset:2048
	ds_read_b128 v[166:169], v148 offset:3072
	v_add_u32_e32 v148, s65, v151
	ds_read_b128 v[170:173], v148
	ds_read_b128 v[174:177], v148 offset:1024
	ds_read_b128 v[178:181], v148 offset:2048
	ds_read_b128 v[182:185], v148 offset:3072
	v_lshl_add_u64 v[148:149], s[30:31], 0, v[146:147]
	s_add_i32 m0, s46, 0xc000
	ds_read_b128 v[186:189], v161
	ds_read_b128 v[190:193], v161 offset:1024
	ds_read_b128 v[194:197], v161 offset:2048
	ds_read_b128 v[198:201], v161 offset:3072
	ds_read_b128 v[202:205], v161 offset:4096
	ds_read_b128 v[206:209], v161 offset:5120
	ds_read_b128 v[210:213], v161 offset:6144
	ds_read_b128 v[214:217], v161 offset:7168
	global_load_lds_dwordx4 v[148:149], off
	v_lshl_add_u64 v[148:149], s[30:31], 0, v[144:145]
	s_add_i32 m0, s46, 0xe000
	s_nop 0
	global_load_lds_dwordx4 v[148:149], off
	s_waitcnt vmcnt(8)
	s_waitcnt lgkmcnt(0)
	s_barrier
	s_setprio 1
	s_waitcnt lgkmcnt(0)
	v_mfma_f32_16x16x32_bf16 v[122:125], v[130:133], v[186:189], v[122:125]
	v_mfma_f32_16x16x32_bf16 v[126:129], v[162:165], v[186:189], v[126:129]
	v_mfma_f32_16x16x32_bf16 v[110:113], v[130:133], v[194:197], v[110:113]
	v_mfma_f32_16x16x32_bf16 v[106:109], v[162:165], v[194:197], v[106:109]
	v_mfma_f32_16x16x32_bf16 v[94:97], v[130:133], v[202:205], v[94:97]
	v_mfma_f32_16x16x32_bf16 v[90:93], v[162:165], v[202:205], v[90:93]
	v_mfma_f32_16x16x32_bf16 v[78:81], v[130:133], v[210:213], v[78:81]
	v_mfma_f32_16x16x32_bf16 v[74:77], v[162:165], v[210:213], v[74:77]
	v_mfma_f32_16x16x32_bf16 v[122:125], v[156:159], v[190:193], v[122:125]
	v_mfma_f32_16x16x32_bf16 v[126:129], v[166:169], v[190:193], v[126:129]
	v_mfma_f32_16x16x32_bf16 v[110:113], v[156:159], v[198:201], v[110:113]
	v_mfma_f32_16x16x32_bf16 v[106:109], v[166:169], v[198:201], v[106:109]
	v_mfma_f32_16x16x32_bf16 v[94:97], v[156:159], v[206:209], v[94:97]
	v_mfma_f32_16x16x32_bf16 v[90:93], v[166:169], v[206:209], v[90:93]
	v_mfma_f32_16x16x32_bf16 v[78:81], v[156:159], v[214:217], v[78:81]
	v_mfma_f32_16x16x32_bf16 v[74:77], v[166:169], v[214:217], v[74:77]
	v_mfma_f32_16x16x32_bf16 v[118:121], v[170:173], v[186:189], v[118:121]
	v_mfma_f32_16x16x32_bf16 v[114:117], v[178:181], v[186:189], v[114:117]
	v_mfma_f32_16x16x32_bf16 v[102:105], v[170:173], v[194:197], v[102:105]
	v_mfma_f32_16x16x32_bf16 v[98:101], v[178:181], v[194:197], v[98:101]
	v_mfma_f32_16x16x32_bf16 v[86:89], v[170:173], v[202:205], v[86:89]
	v_mfma_f32_16x16x32_bf16 v[82:85], v[178:181], v[202:205], v[82:85]
	v_mfma_f32_16x16x32_bf16 v[70:73], v[170:173], v[210:213], v[70:73]
	v_mfma_f32_16x16x32_bf16 v[66:69], v[178:181], v[210:213], v[66:69]
	v_mfma_f32_16x16x32_bf16 v[118:121], v[174:177], v[190:193], v[118:121]
	v_mfma_f32_16x16x32_bf16 v[114:117], v[182:185], v[190:193], v[114:117]
	v_mfma_f32_16x16x32_bf16 v[102:105], v[174:177], v[198:201], v[102:105]
	v_mfma_f32_16x16x32_bf16 v[98:101], v[182:185], v[198:201], v[98:101]
	v_mfma_f32_16x16x32_bf16 v[86:89], v[174:177], v[206:209], v[86:89]
	v_mfma_f32_16x16x32_bf16 v[82:85], v[182:185], v[206:209], v[82:85]
	v_mfma_f32_16x16x32_bf16 v[70:73], v[174:177], v[214:217], v[70:73]
	v_mfma_f32_16x16x32_bf16 v[66:69], v[182:185], v[214:217], v[66:69]
	s_setprio 0
	s_barrier
	s_add_i32 s64, s64, s41
	v_lshl_add_u64 v[148:149], s[62:63], 0, v[136:137]
	s_mov_b32 m0, s64
	ds_read_b128 v[186:189], v161 offset:16384
	ds_read_b128 v[190:193], v161 offset:17408
	ds_read_b128 v[194:197], v161 offset:18432
	ds_read_b128 v[198:201], v161 offset:19456
	ds_read_b128 v[202:205], v161 offset:20480
	ds_read_b128 v[206:209], v161 offset:21504
	ds_read_b128 v[210:213], v161 offset:22528
	ds_read_b128 v[214:217], v161 offset:23552
	global_load_lds_dwordx4 v[148:149], off
	s_add_i32 m0, s64, 0x2000
	v_lshl_add_u64 v[152:153], s[62:63], 0, v[140:141]
	s_add_u32 s62, s62, s16
	s_addc_u32 s63, s63, s17
	s_add_i32 s64, s65, s41
	global_load_lds_dwordx4 v[152:153], off
	v_lshl_add_u64 v[218:219], s[62:63], 0, v[136:137]
	s_mov_b32 m0, s64
	v_lshl_add_u64 v[242:243], s[62:63], 0, v[140:141]
	global_load_lds_dwordx4 v[218:219], off
	s_add_i32 m0, s64, 0x2000
	v_lshl_add_u64 v[244:245], s[34:35], 0, v[134:135]
	global_load_lds_dwordx4 v[242:243], off
	s_mov_b32 m0, s46
	v_lshl_add_u64 v[246:247], s[34:35], 0, v[138:139]
	global_load_lds_dwordx4 v[244:245], off
	s_mov_b32 m0, s47
	s_nop 0
	global_load_lds_dwordx4 v[246:247], off
	s_waitcnt vmcnt(8)
	s_waitcnt lgkmcnt(0)
	s_barrier
; #define PG8_STAGE(bufoff, gbase, voff) do { _Pragma("unroll") for (int _i = 0; _i < 2; ++_i) \
;         __builtin_amdgcn_global_load_lds((const unsigned*)((const char*)(gbase) + (voff)[_i]), (PG8_LAS unsigned*)(lds + (bufoff) + ldsw + _i * 8192), 16, 0, 0); } while (0)
; #define PG8_LDA(dst, b, h) do { _Pragma("unroll") for (int m = 0; m < 4; ++m) _Pragma("unroll") for (int k = 0; k < 2; ++k) dst[m][k] = *(const PG8_LAS bf16x8*)(lds + PG8_SA(b, h) + aoff + m * 2048 + k * 1024); } while (0)
; #define PG8_LDB(dst, b, h) do { _Pragma("unroll") for (int n = 0; n < 2; ++n) _Pragma("unroll") for (int k = 0; k < 2; ++k) dst[n][k] = *(const PG8_LAS bf16x8*)(lds + PG8_SB(b, h) + boff + n * 2048 + k * 1024); } while (0)
; #define PG8_MMA(ai, bj, At, Bt) do { __builtin_amdgcn_s_setprio(1); _Pragma("unroll") for (int m = 0; m < 4; ++m) _Pragma("unroll") for (int n = 0; n < 2; ++n) _Pragma("unroll") for (int k = 0; k < 2; ++k) \
;         acc[ai][bj][m][n] = __builtin_amdgcn_mfma_f32_16x16x32_bf16(Bt[n][k], At[m][k], acc[ai][bj][m][n], 0, 0, 0); __builtin_amdgcn_s_setprio(0); } while (0)
; #define PG8_WAIT_V(n) asm volatile("s_waitcnt vmcnt(" #n ")" ::: "memory")
; #define PG8_WAIT_L(n) asm volatile("s_waitcnt lgkmcnt(" #n ")" ::: "memory")
; #define PG8_BAR __builtin_amdgcn_s_barrier()
; #define PG8_SCHED __builtin_amdgcn_sched_barrier(0)
; template <class Epi, class Sched, bool ALIGN_EPI = false, bool SP2 = false>
; __device__ __forceinline__ void gemm_phase(PG8_LAS unsigned char* lds, const Gemm g, const Sched& S, const Epi& E) {
;     ...
;             PG8_WAIT_V(8); PG8_WAIT_L(0); PG8_BAR; PG8_MMA(1, 0, At, B0); PG8_MMA(1, 1, At, B1); PG8_BAR; PG8_SCHED;
;             PG8_LDB(B0, 1, 0); PG8_LDB(B1, 1, 1); PG8_SCHED; PG8_LDA(At, 1, 0); PG8_STAGE(PG8_SA(0, 1), a2 + hstep, voffA);
;             PG8_WAIT_V(8); PG8_WAIT_L(0); PG8_BAR; PG8_MMA(0, 0, At, B0); PG8_MMA(0, 1, At, B1); PG8_BAR; PG8_SCHED;
	s_setprio 1
	s_waitcnt lgkmcnt(0)
	v_mfma_f32_16x16x32_bf16 v[62:65], v[130:133], v[186:189], v[62:65]
	v_mfma_f32_16x16x32_bf16 v[58:61], v[162:165], v[186:189], v[58:61]
	v_mfma_f32_16x16x32_bf16 v[46:49], v[130:133], v[194:197], v[46:49]
	v_mfma_f32_16x16x32_bf16 v[42:45], v[162:165], v[194:197], v[42:45]
	v_mfma_f32_16x16x32_bf16 v[30:33], v[130:133], v[202:205], v[30:33]
	v_mfma_f32_16x16x32_bf16 v[26:29], v[162:165], v[202:205], v[26:29]
	v_mfma_f32_16x16x32_bf16 v[14:17], v[130:133], v[210:213], v[14:17]
	v_mfma_f32_16x16x32_bf16 v[10:13], v[162:165], v[210:213], v[10:13]
	v_mfma_f32_16x16x32_bf16 v[62:65], v[156:159], v[190:193], v[62:65]
	v_mfma_f32_16x16x32_bf16 v[58:61], v[166:169], v[190:193], v[58:61]
	v_mfma_f32_16x16x32_bf16 v[46:49], v[156:159], v[198:201], v[46:49]
	v_mfma_f32_16x16x32_bf16 v[42:45], v[166:169], v[198:201], v[42:45]
	v_mfma_f32_16x16x32_bf16 v[30:33], v[156:159], v[206:209], v[30:33]
	v_mfma_f32_16x16x32_bf16 v[26:29], v[166:169], v[206:209], v[26:29]
	v_mfma_f32_16x16x32_bf16 v[14:17], v[156:159], v[214:217], v[14:17]
	v_mfma_f32_16x16x32_bf16 v[10:13], v[166:169], v[214:217], v[10:13]
	v_mfma_f32_16x16x32_bf16 v[54:57], v[170:173], v[186:189], v[54:57]
	v_mfma_f32_16x16x32_bf16 v[50:53], v[178:181], v[186:189], v[50:53]
	v_mfma_f32_16x16x32_bf16 v[38:41], v[170:173], v[194:197], v[38:41]
	v_mfma_f32_16x16x32_bf16 v[34:37], v[178:181], v[194:197], v[34:37]
	v_mfma_f32_16x16x32_bf16 v[22:25], v[170:173], v[202:205], v[22:25]
	v_mfma_f32_16x16x32_bf16 v[18:21], v[178:181], v[202:205], v[18:21]
	v_mfma_f32_16x16x32_bf16 v[6:9], v[170:173], v[210:213], v[6:9]
	v_mfma_f32_16x16x32_bf16 v[2:5], v[178:181], v[210:213], v[2:5]
	v_mfma_f32_16x16x32_bf16 v[54:57], v[174:177], v[190:193], v[54:57]
	v_mfma_f32_16x16x32_bf16 v[50:53], v[182:185], v[190:193], v[50:53]
	v_mfma_f32_16x16x32_bf16 v[38:41], v[174:177], v[198:201], v[38:41]
	v_mfma_f32_16x16x32_bf16 v[34:37], v[182:185], v[198:201], v[34:37]
	v_mfma_f32_16x16x32_bf16 v[22:25], v[174:177], v[206:209], v[22:25]
	v_mfma_f32_16x16x32_bf16 v[18:21], v[182:185], v[206:209], v[18:21]
	v_mfma_f32_16x16x32_bf16 v[6:9], v[174:177], v[214:217], v[6:9]
	v_mfma_f32_16x16x32_bf16 v[2:5], v[182:185], v[214:217], v[2:5]
	s_setprio 0
	s_barrier
	s_add_i32 s62, 0, 0x18000
	v_add_u32_e32 v150, s62, v151
	s_add_i32 s63, 0, 0x1c000
	ds_read_b128 v[130:133], v150
	ds_read_b128 v[156:159], v150 offset:1024
	ds_read_b128 v[162:165], v150 offset:2048
	ds_read_b128 v[166:169], v150 offset:3072
	v_add_u32_e32 v150, s63, v151
	ds_read_b128 v[170:173], v150
	ds_read_b128 v[174:177], v150 offset:1024
	ds_read_b128 v[178:181], v150 offset:2048
	ds_read_b128 v[182:185], v150 offset:3072
	s_add_u32 s34, s34, s16
	s_addc_u32 s35, s35, s17
	s_mov_b32 m0, s48
	v_lshl_add_u64 v[248:249], s[34:35], 0, v[134:135]
	ds_read_b128 v[186:189], v161 offset:32768
	ds_read_b128 v[190:193], v161 offset:33792
	ds_read_b128 v[194:197], v161 offset:34816
	ds_read_b128 v[198:201], v161 offset:35840
	ds_read_b128 v[202:205], v161 offset:36864
	ds_read_b128 v[206:209], v161 offset:37888
	ds_read_b128 v[210:213], v161 offset:38912
	ds_read_b128 v[214:217], v161 offset:39936
	global_load_lds_dwordx4 v[248:249], off
	v_lshl_add_u64 v[248:249], s[34:35], 0, v[138:139]
	s_mov_b32 m0, s49
	s_nop 0
	global_load_lds_dwordx4 v[248:249], off
	s_waitcnt vmcnt(8)
	s_waitcnt lgkmcnt(0)
	s_barrier
	s_setprio 1
	s_waitcnt lgkmcnt(0)
	v_mfma_f32_16x16x32_bf16 v[122:125], v[130:133], v[186:189], v[122:125]
	v_mfma_f32_16x16x32_bf16 v[126:129], v[162:165], v[186:189], v[126:129]
	v_mfma_f32_16x16x32_bf16 v[110:113], v[130:133], v[194:197], v[110:113]
	v_mfma_f32_16x16x32_bf16 v[106:109], v[162:165], v[194:197], v[106:109]
	v_mfma_f32_16x16x32_bf16 v[94:97], v[130:133], v[202:205], v[94:97]
	v_mfma_f32_16x16x32_bf16 v[90:93], v[162:165], v[202:205], v[90:93]
	v_mfma_f32_16x16x32_bf16 v[78:81], v[130:133], v[210:213], v[78:81]
	v_mfma_f32_16x16x32_bf16 v[74:77], v[162:165], v[210:213], v[74:77]
	v_mfma_f32_16x16x32_bf16 v[122:125], v[156:159], v[190:193], v[122:125]
	v_mfma_f32_16x16x32_bf16 v[126:129], v[166:169], v[190:193], v[126:129]
	v_mfma_f32_16x16x32_bf16 v[110:113], v[156:159], v[198:201], v[110:113]
	v_mfma_f32_16x16x32_bf16 v[106:109], v[166:169], v[198:201], v[106:109]
	v_mfma_f32_16x16x32_bf16 v[94:97], v[156:159], v[206:209], v[94:97]
	v_mfma_f32_16x16x32_bf16 v[90:93], v[166:169], v[206:209], v[90:93]
	v_mfma_f32_16x16x32_bf16 v[78:81], v[156:159], v[214:217], v[78:81]
	v_mfma_f32_16x16x32_bf16 v[74:77], v[166:169], v[214:217], v[74:77]
	v_mfma_f32_16x16x32_bf16 v[118:121], v[170:173], v[186:189], v[118:121]
	v_mfma_f32_16x16x32_bf16 v[114:117], v[178:181], v[186:189], v[114:117]
	v_mfma_f32_16x16x32_bf16 v[102:105], v[170:173], v[194:197], v[102:105]
	v_mfma_f32_16x16x32_bf16 v[98:101], v[178:181], v[194:197], v[98:101]
	v_mfma_f32_16x16x32_bf16 v[86:89], v[170:173], v[202:205], v[86:89]
	v_mfma_f32_16x16x32_bf16 v[82:85], v[178:181], v[202:205], v[82:85]
	v_mfma_f32_16x16x32_bf16 v[70:73], v[170:173], v[210:213], v[70:73]
	v_mfma_f32_16x16x32_bf16 v[66:69], v[178:181], v[210:213], v[66:69]
	v_mfma_f32_16x16x32_bf16 v[118:121], v[174:177], v[190:193], v[118:121]
	v_mfma_f32_16x16x32_bf16 v[114:117], v[182:185], v[190:193], v[114:117]
	v_mfma_f32_16x16x32_bf16 v[102:105], v[174:177], v[198:201], v[102:105]
	v_mfma_f32_16x16x32_bf16 v[98:101], v[182:185], v[198:201], v[98:101]
	v_mfma_f32_16x16x32_bf16 v[86:89], v[174:177], v[206:209], v[86:89]
	v_mfma_f32_16x16x32_bf16 v[82:85], v[182:185], v[206:209], v[82:85]
	v_mfma_f32_16x16x32_bf16 v[70:73], v[174:177], v[214:217], v[70:73]
	v_mfma_f32_16x16x32_bf16 v[66:69], v[182:185], v[214:217], v[66:69]
	s_setprio 0
	s_barrier
; #define PG8_STAGE(bufoff, gbase, voff) do { _Pragma("unroll") for (int _i = 0; _i < 2; ++_i) \
;         __builtin_amdgcn_global_load_lds((const unsigned*)((const char*)(gbase) + (voff)[_i]), (PG8_LAS unsigned*)(lds + (bufoff) + ldsw + _i * 8192), 16, 0, 0); } while (0)
; #define PG8_LDA(dst, b, h) do { _Pragma("unroll") for (int m = 0; m < 4; ++m) _Pragma("unroll") for (int k = 0; k < 2; ++k) dst[m][k] = *(const PG8_LAS bf16x8*)(lds + PG8_SA(b, h) + aoff + m * 2048 + k * 1024); } while (0)
; #define PG8_MMA(ai, bj, At, Bt) do { __builtin_amdgcn_s_setprio(1); _Pragma("unroll") for (int m = 0; m < 4; ++m) _Pragma("unroll") for (int n = 0; n < 2; ++n) _Pragma("unroll") for (int k = 0; k < 2; ++k) \
;         acc[ai][bj][m][n] = __builtin_amdgcn_mfma_f32_16x16x32_bf16(Bt[n][k], At[m][k], acc[ai][bj][m][n], 0, 0, 0); __builtin_amdgcn_s_setprio(0); } while (0)
; #define PG8_WAIT_V(n) asm volatile("s_waitcnt vmcnt(" #n ")" ::: "memory")
; #define PG8_WAIT_L(n) asm volatile("s_waitcnt lgkmcnt(" #n ")" ::: "memory")
; #define PG8_BAR __builtin_amdgcn_s_barrier()
; #define PG8_SCHED __builtin_amdgcn_sched_barrier(0)
; template <class Epi, class Sched, bool ALIGN_EPI = false, bool SP2 = false>
; __device__ __forceinline__ void gemm_phase(PG8_LAS unsigned char* lds, const Gemm g, const Sched& S, const Epi& E) {
;     ...
;         for (int t = 0; t < nt; t += 2) {
;             const bool last = (t == nt - 2);
;             const char* a1 = cA + (size_t)(t + 1) * kstep;
;             const char* a2 = last ? nA : cA + (size_t)(t + 2) * kstep; const char* b2 = last ? nB : cB + (size_t)(t + 2) * kstep;
;     ...
;             PG8_LDA(At, 1, 1); PG8_STAGE(PG8_SB(1, 0), b3, voffB); PG8_STAGE(PG8_SB(1, 1), b3 + hstep, voffB); PG8_STAGE(PG8_SA(1, 0), a3, voffA);
;             PG8_WAIT_V(8); PG8_WAIT_L(0); PG8_BAR; PG8_MMA(1, 0, At, B0); PG8_MMA(1, 1, At, B1); PG8_BAR; PG8_SCHED;
	s_add_i32 s34, s62, s41
	v_lshl_add_u64 v[148:149], v[148:149], 0, s[92:93]
	s_mov_b32 m0, s34
	ds_read_b128 v[186:189], v161 offset:49152
	ds_read_b128 v[190:193], v161 offset:50176
	ds_read_b128 v[194:197], v161 offset:51200
	ds_read_b128 v[198:201], v161 offset:52224
	ds_read_b128 v[202:205], v161 offset:53248
	ds_read_b128 v[206:209], v161 offset:54272
	ds_read_b128 v[210:213], v161 offset:55296
	ds_read_b128 v[214:217], v161 offset:56320
	global_load_lds_dwordx4 v[148:149], off
	v_lshl_add_u64 v[148:149], v[152:153], 0, s[92:93]
	s_add_i32 m0, s34, 0x2000
	s_add_i32 s34, s63, s41
	global_load_lds_dwordx4 v[148:149], off
	v_lshl_add_u64 v[148:149], v[218:219], 0, s[92:93]
	s_mov_b32 m0, s34
	s_nop 0
	global_load_lds_dwordx4 v[148:149], off
	v_lshl_add_u64 v[148:149], v[242:243], 0, s[92:93]
	s_add_i32 m0, s34, 0x2000
	s_nop 0
	global_load_lds_dwordx4 v[148:149], off
	v_lshl_add_u64 v[148:149], v[244:245], 0, s[92:93]
	s_mov_b32 m0, s50
	s_nop 0
	global_load_lds_dwordx4 v[148:149], off
	v_lshl_add_u64 v[148:149], v[246:247], 0, s[92:93]
	s_mov_b32 m0, s51
	s_nop 0
	global_load_lds_dwordx4 v[148:149], off
	s_waitcnt vmcnt(8)
	s_waitcnt lgkmcnt(0)
	s_barrier
	s_setprio 1
	s_waitcnt lgkmcnt(0)
	v_mfma_f32_16x16x32_bf16 v[62:65], v[130:133], v[186:189], v[62:65]
	v_mfma_f32_16x16x32_bf16 v[58:61], v[162:165], v[186:189], v[58:61]
	v_mfma_f32_16x16x32_bf16 v[46:49], v[130:133], v[194:197], v[46:49]
	v_mfma_f32_16x16x32_bf16 v[42:45], v[162:165], v[194:197], v[42:45]
	v_mfma_f32_16x16x32_bf16 v[30:33], v[130:133], v[202:205], v[30:33]
	v_mfma_f32_16x16x32_bf16 v[26:29], v[162:165], v[202:205], v[26:29]
	v_mfma_f32_16x16x32_bf16 v[14:17], v[130:133], v[210:213], v[14:17]
	v_mfma_f32_16x16x32_bf16 v[10:13], v[162:165], v[210:213], v[10:13]
	v_mfma_f32_16x16x32_bf16 v[62:65], v[156:159], v[190:193], v[62:65]
	v_mfma_f32_16x16x32_bf16 v[58:61], v[166:169], v[190:193], v[58:61]
	v_mfma_f32_16x16x32_bf16 v[46:49], v[156:159], v[198:201], v[46:49]
	v_mfma_f32_16x16x32_bf16 v[42:45], v[166:169], v[198:201], v[42:45]
	v_mfma_f32_16x16x32_bf16 v[30:33], v[156:159], v[206:209], v[30:33]
	v_mfma_f32_16x16x32_bf16 v[26:29], v[166:169], v[206:209], v[26:29]
	v_mfma_f32_16x16x32_bf16 v[14:17], v[156:159], v[214:217], v[14:17]
	v_mfma_f32_16x16x32_bf16 v[10:13], v[166:169], v[214:217], v[10:13]
	v_mfma_f32_16x16x32_bf16 v[54:57], v[170:173], v[186:189], v[54:57]
	v_mfma_f32_16x16x32_bf16 v[50:53], v[178:181], v[186:189], v[50:53]
	v_mfma_f32_16x16x32_bf16 v[38:41], v[170:173], v[194:197], v[38:41]
	v_mfma_f32_16x16x32_bf16 v[34:37], v[178:181], v[194:197], v[34:37]
	v_mfma_f32_16x16x32_bf16 v[22:25], v[170:173], v[202:205], v[22:25]
	v_mfma_f32_16x16x32_bf16 v[18:21], v[178:181], v[202:205], v[18:21]
	v_mfma_f32_16x16x32_bf16 v[6:9], v[170:173], v[210:213], v[6:9]
	v_mfma_f32_16x16x32_bf16 v[2:5], v[178:181], v[210:213], v[2:5]
	v_mfma_f32_16x16x32_bf16 v[54:57], v[174:177], v[190:193], v[54:57]
	v_mfma_f32_16x16x32_bf16 v[50:53], v[182:185], v[190:193], v[50:53]
	v_mfma_f32_16x16x32_bf16 v[38:41], v[174:177], v[198:201], v[38:41]
	v_mfma_f32_16x16x32_bf16 v[34:37], v[182:185], v[198:201], v[34:37]
	v_mfma_f32_16x16x32_bf16 v[22:25], v[174:177], v[206:209], v[22:25]
	v_mfma_f32_16x16x32_bf16 v[18:21], v[182:185], v[206:209], v[18:21]
	v_mfma_f32_16x16x32_bf16 v[6:9], v[174:177], v[214:217], v[6:9]
	v_mfma_f32_16x16x32_bf16 v[2:5], v[182:185], v[214:217], v[2:5]
	s_setprio 0
	s_barrier
	s_add_u32 s59, s59, 0x100
	s_addc_u32 s60, s60, 0
	s_add_u32 s30, s30, 0x100
	s_addc_u32 s31, s31, 0
	s_cmp_ge_i32 s61, s52
	s_mov_b32 s34, s61
	s_cbranch_scc0 .LBB0_3165

; #define PG8_STAGE(bufoff, gbase, voff) do { _Pragma("unroll") for (int _i = 0; _i < 2; ++_i) \
;         __builtin_amdgcn_global_load_lds((const unsigned*)((const char*)(gbase) + (voff)[_i]), (PG8_LAS unsigned*)(lds + (bufoff) + ldsw + _i * 8192), 16, 0, 0); } while (0)
; #define PG8_LDA(dst, b, h) do { _Pragma("unroll") for (int m = 0; m < 4; ++m) _Pragma("unroll") for (int k = 0; k < 2; ++k) dst[m][k] = *(const PG8_LAS bf16x8*)(lds + PG8_SA(b, h) + aoff + m * 2048 + k * 1024); } while (0)
; #define PG8_LDB(dst, b, h) do { _Pragma("unroll") for (int n = 0; n < 2; ++n) _Pragma("unroll") for (int k = 0; k < 2; ++k) dst[n][k] = *(const PG8_LAS bf16x8*)(lds + PG8_SB(b, h) + boff + n * 2048 + k * 1024); } while (0)
; #define PG8_MMA(ai, bj, At, Bt) do { __builtin_amdgcn_s_setprio(1); _Pragma("unroll") for (int m = 0; m < 4; ++m) _Pragma("unroll") for (int n = 0; n < 2; ++n) _Pragma("unroll") for (int k = 0; k < 2; ++k) \
;         acc[ai][bj][m][n] = __builtin_amdgcn_mfma_f32_16x16x32_bf16(Bt[n][k], At[m][k], acc[ai][bj][m][n], 0, 0, 0); __builtin_amdgcn_s_setprio(0); } while (0)
; #define PG8_WAIT_V(n) asm volatile("s_waitcnt vmcnt(" #n ")" ::: "memory")
; #define PG8_BAR __builtin_amdgcn_s_barrier()
; template <class Epi, class Sched, bool ALIGN_EPI = false, bool SP2 = false>
; __device__ __forceinline__ void gemm_phase(PG8_LAS unsigned char* lds, const Gemm g, const Sched& S, const Epi& E) {
;     ...
;         for (int t = 0; t < nt; t += 2) {
;             const bool last = (t == nt - 2);
;             const char* a1 = cA + (size_t)(t + 1) * kstep;
;             const char* a2 = last ? nA : cA + (size_t)(t + 2) * kstep; const char* b2 = last ? nB : cB + (size_t)(t + 2) * kstep;
;             const char* a3 = a2 + kstep; const char* b3 = b2 + kstep;
;             if (last && has_next) S.a_ready(nxt);
;             if constexpr (SP2) {
;             PG8_LDB(B0, 0, 0); PG8_LDB(B1, 0, 1); PG8_SCHED; PG8_LDA(At, 0, 0); PG8_STAGE(PG8_SA(1, 1), a1 + hstep, voffA);
;             PG8_WAIT_V(8); PG8_WAIT_L(0); PG8_BAR; PG8_MMA(0, 0, At, B0); PG8_MMA(0, 1, At, B1); PG8_BAR; PG8_SCHED;
;             PG8_LDA(At, 0, 1); PG8_STAGE(PG8_SB(0, 0), b2, voffB); PG8_STAGE(PG8_SB(0, 1), b2 + hstep, voffB); PG8_STAGE(PG8_SA(0, 0), a2, voffA);
;             PG8_WAIT_V(8); PG8_WAIT_L(0); PG8_BAR; PG8_MMA(1, 0, At, B0); PG8_MMA(1, 1, At, B1); PG8_BAR; PG8_SCHED;
.LBB0_3248:
	s_add_i32 s67, s40, 2
	s_add_u32 s68, s38, 0x80
	s_addc_u32 s41, s39, 0
	s_add_i32 s70, 0, 0x10000
	s_cmp_eq_u32 s52, s40
	s_cselect_b32 s41, s1, s41
	s_cselect_b32 s40, s0, s68
	s_cselect_b32 s69, s37, s66
	s_cselect_b32 s68, s36, s65
	s_add_i32 s71, 0, 0x14000
	v_add_u32_e32 v154, s70, v242
	v_add_u32_e32 v170, s71, v242
	ds_read_b128 v[142:145], v154
	ds_read_b128 v[146:149], v154 offset:1024
	ds_read_b128 v[150:153], v154 offset:2048
	ds_read_b128 v[154:157], v154 offset:3072
	ds_read_b128 v[158:161], v170
	ds_read_b128 v[162:165], v170 offset:1024
	ds_read_b128 v[166:169], v170 offset:2048
	ds_read_b128 v[170:173], v170 offset:3072
	v_lshl_add_u64 v[206:207], s[38:39], 0, v[140:141]
	s_add_i32 m0, s44, 0xc000
	ds_read_b128 v[174:177], v244
	ds_read_b128 v[178:181], v244 offset:1024
	ds_read_b128 v[182:185], v244 offset:2048
	ds_read_b128 v[186:189], v244 offset:3072
	ds_read_b128 v[190:193], v244 offset:4096
	ds_read_b128 v[194:197], v244 offset:5120
	ds_read_b128 v[198:201], v244 offset:6144
	ds_read_b128 v[202:205], v244 offset:7168
	global_load_lds_dwordx4 v[206:207], off
	v_lshl_add_u64 v[206:207], s[38:39], 0, v[138:139]
	s_add_i32 m0, s44, 0xe000
	s_nop 0
	global_load_lds_dwordx4 v[206:207], off
	s_waitcnt vmcnt(8)
	s_waitcnt lgkmcnt(0)
	s_barrier
	s_setprio 1
	s_waitcnt lgkmcnt(0)
	v_mfma_f32_16x16x32_bf16 v[126:129], v[142:145], v[174:177], v[126:129]
	v_mfma_f32_16x16x32_bf16 v[122:125], v[150:153], v[174:177], v[122:125]
	v_mfma_f32_16x16x32_bf16 v[118:121], v[142:145], v[182:185], v[118:121]
	v_mfma_f32_16x16x32_bf16 v[114:117], v[150:153], v[182:185], v[114:117]
	v_mfma_f32_16x16x32_bf16 v[106:109], v[142:145], v[190:193], v[106:109]
	v_mfma_f32_16x16x32_bf16 v[98:101], v[150:153], v[190:193], v[98:101]
	v_mfma_f32_16x16x32_bf16 v[90:93], v[142:145], v[198:201], v[90:93]
	v_mfma_f32_16x16x32_bf16 v[82:85], v[150:153], v[198:201], v[82:85]
	v_mfma_f32_16x16x32_bf16 v[126:129], v[146:149], v[178:181], v[126:129]
	v_mfma_f32_16x16x32_bf16 v[122:125], v[154:157], v[178:181], v[122:125]
	v_mfma_f32_16x16x32_bf16 v[118:121], v[146:149], v[186:189], v[118:121]
	v_mfma_f32_16x16x32_bf16 v[114:117], v[154:157], v[186:189], v[114:117]
	v_mfma_f32_16x16x32_bf16 v[106:109], v[146:149], v[194:197], v[106:109]
	v_mfma_f32_16x16x32_bf16 v[98:101], v[154:157], v[194:197], v[98:101]
	v_mfma_f32_16x16x32_bf16 v[90:93], v[146:149], v[202:205], v[90:93]
	v_mfma_f32_16x16x32_bf16 v[82:85], v[154:157], v[202:205], v[82:85]
	v_mfma_f32_16x16x32_bf16 v[110:113], v[158:161], v[174:177], v[110:113]
	v_mfma_f32_16x16x32_bf16 v[102:105], v[166:169], v[174:177], v[102:105]
	v_mfma_f32_16x16x32_bf16 v[94:97], v[158:161], v[182:185], v[94:97]
	v_mfma_f32_16x16x32_bf16 v[86:89], v[166:169], v[182:185], v[86:89]
	v_mfma_f32_16x16x32_bf16 v[78:81], v[158:161], v[190:193], v[78:81]
	v_mfma_f32_16x16x32_bf16 v[74:77], v[166:169], v[190:193], v[74:77]
	v_mfma_f32_16x16x32_bf16 v[70:73], v[158:161], v[198:201], v[70:73]
	v_mfma_f32_16x16x32_bf16 v[66:69], v[166:169], v[198:201], v[66:69]
	v_mfma_f32_16x16x32_bf16 v[110:113], v[162:165], v[178:181], v[110:113]
	v_mfma_f32_16x16x32_bf16 v[102:105], v[170:173], v[178:181], v[102:105]
	v_mfma_f32_16x16x32_bf16 v[94:97], v[162:165], v[186:189], v[94:97]
	v_mfma_f32_16x16x32_bf16 v[86:89], v[170:173], v[186:189], v[86:89]
	v_mfma_f32_16x16x32_bf16 v[78:81], v[162:165], v[194:197], v[78:81]
	v_mfma_f32_16x16x32_bf16 v[74:77], v[170:173], v[194:197], v[74:77]
	v_mfma_f32_16x16x32_bf16 v[70:73], v[162:165], v[202:205], v[70:73]
	v_mfma_f32_16x16x32_bf16 v[66:69], v[170:173], v[202:205], v[66:69]
	s_setprio 0
	s_barrier
	s_add_i32 s70, s70, s43
	v_lshl_add_u64 v[206:207], s[68:69], 0, v[132:133]
	s_mov_b32 m0, s70
	ds_read_b128 v[174:177], v244 offset:16384
	ds_read_b128 v[178:181], v244 offset:17408
	ds_read_b128 v[182:185], v244 offset:18432
	ds_read_b128 v[186:189], v244 offset:19456
	ds_read_b128 v[190:193], v244 offset:20480
	ds_read_b128 v[194:197], v244 offset:21504
	ds_read_b128 v[198:201], v244 offset:22528
	ds_read_b128 v[202:205], v244 offset:23552
	global_load_lds_dwordx4 v[206:207], off
	s_add_i32 m0, s70, 0x2000
	v_lshl_add_u64 v[208:209], s[68:69], 0, v[136:137]
	s_add_u32 s68, s68, s22
	s_addc_u32 s69, s69, s23
	s_add_i32 s70, s71, s43
	global_load_lds_dwordx4 v[208:209], off
	v_lshl_add_u64 v[210:211], s[68:69], 0, v[132:133]
	s_mov_b32 m0, s70
	v_lshl_add_u64 v[212:213], s[68:69], 0, v[136:137]
	global_load_lds_dwordx4 v[210:211], off
	s_add_i32 m0, s70, 0x2000
	v_lshl_add_u64 v[214:215], s[40:41], 0, v[130:131]
	global_load_lds_dwordx4 v[212:213], off
	s_mov_b32 m0, s44
	v_lshl_add_u64 v[216:217], s[40:41], 0, v[134:135]
	global_load_lds_dwordx4 v[214:215], off
	s_mov_b32 m0, s45
	s_nop 0
	global_load_lds_dwordx4 v[216:217], off
	s_waitcnt vmcnt(8)
	s_waitcnt lgkmcnt(0)
	s_barrier
; #define PG8_STAGE(bufoff, gbase, voff) do { _Pragma("unroll") for (int _i = 0; _i < 2; ++_i) \
;         __builtin_amdgcn_global_load_lds((const unsigned*)((const char*)(gbase) + (voff)[_i]), (PG8_LAS unsigned*)(lds + (bufoff) + ldsw + _i * 8192), 16, 0, 0); } while (0)
; #define PG8_LDA(dst, b, h) do { _Pragma("unroll") for (int m = 0; m < 4; ++m) _Pragma("unroll") for (int k = 0; k < 2; ++k) dst[m][k] = *(const PG8_LAS bf16x8*)(lds + PG8_SA(b, h) + aoff + m * 2048 + k * 1024); } while (0)
; #define PG8_LDB(dst, b, h) do { _Pragma("unroll") for (int n = 0; n < 2; ++n) _Pragma("unroll") for (int k = 0; k < 2; ++k) dst[n][k] = *(const PG8_LAS bf16x8*)(lds + PG8_SB(b, h) + boff + n * 2048 + k * 1024); } while (0)
; #define PG8_MMA(ai, bj, At, Bt) do { __builtin_amdgcn_s_setprio(1); _Pragma("unroll") for (int m = 0; m < 4; ++m) _Pragma("unroll") for (int n = 0; n < 2; ++n) _Pragma("unroll") for (int k = 0; k < 2; ++k) \
;         acc[ai][bj][m][n] = __builtin_amdgcn_mfma_f32_16x16x32_bf16(Bt[n][k], At[m][k], acc[ai][bj][m][n], 0, 0, 0); __builtin_amdgcn_s_setprio(0); } while (0)
; #define PG8_WAIT_V(n) asm volatile("s_waitcnt vmcnt(" #n ")" ::: "memory")
; #define PG8_WAIT_L(n) asm volatile("s_waitcnt lgkmcnt(" #n ")" ::: "memory")
; #define PG8_BAR __builtin_amdgcn_s_barrier()
; #define PG8_SCHED __builtin_amdgcn_sched_barrier(0)
; template <class Epi, class Sched, bool ALIGN_EPI = false, bool SP2 = false>
; __device__ __forceinline__ void gemm_phase(PG8_LAS unsigned char* lds, const Gemm g, const Sched& S, const Epi& E) {
;     ...
;             PG8_WAIT_V(8); PG8_WAIT_L(0); PG8_BAR; PG8_MMA(1, 0, At, B0); PG8_MMA(1, 1, At, B1); PG8_BAR; PG8_SCHED;
;             PG8_LDB(B0, 1, 0); PG8_LDB(B1, 1, 1); PG8_SCHED; PG8_LDA(At, 1, 0); PG8_STAGE(PG8_SA(0, 1), a2 + hstep, voffA);
;             PG8_WAIT_V(8); PG8_WAIT_L(0); PG8_BAR; PG8_MMA(0, 0, At, B0); PG8_MMA(0, 1, At, B1); PG8_BAR; PG8_SCHED;
	s_setprio 1
	s_waitcnt lgkmcnt(0)
	v_mfma_f32_16x16x32_bf16 v[62:65], v[142:145], v[174:177], v[62:65]
	v_mfma_f32_16x16x32_bf16 v[58:61], v[150:153], v[174:177], v[58:61]
	v_mfma_f32_16x16x32_bf16 v[54:57], v[142:145], v[182:185], v[54:57]
	v_mfma_f32_16x16x32_bf16 v[50:53], v[150:153], v[182:185], v[50:53]
	v_mfma_f32_16x16x32_bf16 v[42:45], v[142:145], v[190:193], v[42:45]
	v_mfma_f32_16x16x32_bf16 v[34:37], v[150:153], v[190:193], v[34:37]
	v_mfma_f32_16x16x32_bf16 v[26:29], v[142:145], v[198:201], v[26:29]
	v_mfma_f32_16x16x32_bf16 v[18:21], v[150:153], v[198:201], v[18:21]
	v_mfma_f32_16x16x32_bf16 v[62:65], v[146:149], v[178:181], v[62:65]
	v_mfma_f32_16x16x32_bf16 v[58:61], v[154:157], v[178:181], v[58:61]
	v_mfma_f32_16x16x32_bf16 v[54:57], v[146:149], v[186:189], v[54:57]
	v_mfma_f32_16x16x32_bf16 v[50:53], v[154:157], v[186:189], v[50:53]
	v_mfma_f32_16x16x32_bf16 v[42:45], v[146:149], v[194:197], v[42:45]
	v_mfma_f32_16x16x32_bf16 v[34:37], v[154:157], v[194:197], v[34:37]
	v_mfma_f32_16x16x32_bf16 v[26:29], v[146:149], v[202:205], v[26:29]
	v_mfma_f32_16x16x32_bf16 v[18:21], v[154:157], v[202:205], v[18:21]
	v_mfma_f32_16x16x32_bf16 v[46:49], v[158:161], v[174:177], v[46:49]
	v_mfma_f32_16x16x32_bf16 v[38:41], v[166:169], v[174:177], v[38:41]
	v_mfma_f32_16x16x32_bf16 v[30:33], v[158:161], v[182:185], v[30:33]
	v_mfma_f32_16x16x32_bf16 v[22:25], v[166:169], v[182:185], v[22:25]
	v_mfma_f32_16x16x32_bf16 v[14:17], v[158:161], v[190:193], v[14:17]
	v_mfma_f32_16x16x32_bf16 v[10:13], v[166:169], v[190:193], v[10:13]
	v_mfma_f32_16x16x32_bf16 v[6:9], v[158:161], v[198:201], v[6:9]
	v_mfma_f32_16x16x32_bf16 v[2:5], v[166:169], v[198:201], v[2:5]
	v_mfma_f32_16x16x32_bf16 v[46:49], v[162:165], v[178:181], v[46:49]
	v_mfma_f32_16x16x32_bf16 v[38:41], v[170:173], v[178:181], v[38:41]
	v_mfma_f32_16x16x32_bf16 v[30:33], v[162:165], v[186:189], v[30:33]
	v_mfma_f32_16x16x32_bf16 v[22:25], v[170:173], v[186:189], v[22:25]
	v_mfma_f32_16x16x32_bf16 v[14:17], v[162:165], v[194:197], v[14:17]
	v_mfma_f32_16x16x32_bf16 v[10:13], v[170:173], v[194:197], v[10:13]
	v_mfma_f32_16x16x32_bf16 v[6:9], v[162:165], v[202:205], v[6:9]
	v_mfma_f32_16x16x32_bf16 v[2:5], v[170:173], v[202:205], v[2:5]
	s_setprio 0
	s_barrier
	s_add_i32 s68, 0, 0x18000
	s_add_i32 s69, 0, 0x1c000
	v_add_u32_e32 v154, s68, v242
	v_add_u32_e32 v170, s69, v242
	ds_read_b128 v[142:145], v154
	ds_read_b128 v[146:149], v154 offset:1024
	ds_read_b128 v[150:153], v154 offset:2048
	ds_read_b128 v[154:157], v154 offset:3072
	ds_read_b128 v[158:161], v170
	ds_read_b128 v[162:165], v170 offset:1024
	ds_read_b128 v[166:169], v170 offset:2048
	ds_read_b128 v[170:173], v170 offset:3072
	s_add_u32 s40, s40, s22
	s_addc_u32 s41, s41, s23
	s_mov_b32 m0, s46
	v_lshl_add_u64 v[218:219], s[40:41], 0, v[130:131]
	ds_read_b128 v[174:177], v244 offset:32768
	ds_read_b128 v[178:181], v244 offset:33792
	ds_read_b128 v[182:185], v244 offset:34816
	ds_read_b128 v[186:189], v244 offset:35840
	ds_read_b128 v[190:193], v244 offset:36864
	ds_read_b128 v[194:197], v244 offset:37888
	ds_read_b128 v[198:201], v244 offset:38912
	ds_read_b128 v[202:205], v244 offset:39936
	global_load_lds_dwordx4 v[218:219], off
	v_lshl_add_u64 v[218:219], s[40:41], 0, v[134:135]
	s_mov_b32 m0, s47
	s_nop 0
	global_load_lds_dwordx4 v[218:219], off
	s_waitcnt vmcnt(8)
	s_waitcnt lgkmcnt(0)
	s_barrier
	s_setprio 1
	s_waitcnt lgkmcnt(0)
	v_mfma_f32_16x16x32_bf16 v[126:129], v[142:145], v[174:177], v[126:129]
	v_mfma_f32_16x16x32_bf16 v[122:125], v[150:153], v[174:177], v[122:125]
	v_mfma_f32_16x16x32_bf16 v[118:121], v[142:145], v[182:185], v[118:121]
	v_mfma_f32_16x16x32_bf16 v[114:117], v[150:153], v[182:185], v[114:117]
	v_mfma_f32_16x16x32_bf16 v[106:109], v[142:145], v[190:193], v[106:109]
	v_mfma_f32_16x16x32_bf16 v[98:101], v[150:153], v[190:193], v[98:101]
	v_mfma_f32_16x16x32_bf16 v[90:93], v[142:145], v[198:201], v[90:93]
	v_mfma_f32_16x16x32_bf16 v[82:85], v[150:153], v[198:201], v[82:85]
	v_mfma_f32_16x16x32_bf16 v[126:129], v[146:149], v[178:181], v[126:129]
	v_mfma_f32_16x16x32_bf16 v[122:125], v[154:157], v[178:181], v[122:125]
	v_mfma_f32_16x16x32_bf16 v[118:121], v[146:149], v[186:189], v[118:121]
	v_mfma_f32_16x16x32_bf16 v[114:117], v[154:157], v[186:189], v[114:117]
	v_mfma_f32_16x16x32_bf16 v[106:109], v[146:149], v[194:197], v[106:109]
	v_mfma_f32_16x16x32_bf16 v[98:101], v[154:157], v[194:197], v[98:101]
	v_mfma_f32_16x16x32_bf16 v[90:93], v[146:149], v[202:205], v[90:93]
	v_mfma_f32_16x16x32_bf16 v[82:85], v[154:157], v[202:205], v[82:85]
	v_mfma_f32_16x16x32_bf16 v[110:113], v[158:161], v[174:177], v[110:113]
	v_mfma_f32_16x16x32_bf16 v[102:105], v[166:169], v[174:177], v[102:105]
	v_mfma_f32_16x16x32_bf16 v[94:97], v[158:161], v[182:185], v[94:97]
	v_mfma_f32_16x16x32_bf16 v[86:89], v[166:169], v[182:185], v[86:89]
	v_mfma_f32_16x16x32_bf16 v[78:81], v[158:161], v[190:193], v[78:81]
	v_mfma_f32_16x16x32_bf16 v[74:77], v[166:169], v[190:193], v[74:77]
	v_mfma_f32_16x16x32_bf16 v[70:73], v[158:161], v[198:201], v[70:73]
	v_mfma_f32_16x16x32_bf16 v[66:69], v[166:169], v[198:201], v[66:69]
	v_mfma_f32_16x16x32_bf16 v[110:113], v[162:165], v[178:181], v[110:113]
	v_mfma_f32_16x16x32_bf16 v[102:105], v[170:173], v[178:181], v[102:105]
	v_mfma_f32_16x16x32_bf16 v[94:97], v[162:165], v[186:189], v[94:97]
	v_mfma_f32_16x16x32_bf16 v[86:89], v[170:173], v[186:189], v[86:89]
	v_mfma_f32_16x16x32_bf16 v[78:81], v[162:165], v[194:197], v[78:81]
	v_mfma_f32_16x16x32_bf16 v[74:77], v[170:173], v[194:197], v[74:77]
	v_mfma_f32_16x16x32_bf16 v[70:73], v[162:165], v[202:205], v[70:73]
	v_mfma_f32_16x16x32_bf16 v[66:69], v[170:173], v[202:205], v[66:69]
	s_setprio 0
	s_barrier
; #define PG8_STAGE(bufoff, gbase, voff) do { _Pragma("unroll") for (int _i = 0; _i < 2; ++_i) \
;         __builtin_amdgcn_global_load_lds((const unsigned*)((const char*)(gbase) + (voff)[_i]), (PG8_LAS unsigned*)(lds + (bufoff) + ldsw + _i * 8192), 16, 0, 0); } while (0)
; #define PG8_LDA(dst, b, h) do { _Pragma("unroll") for (int m = 0; m < 4; ++m) _Pragma("unroll") for (int k = 0; k < 2; ++k) dst[m][k] = *(const PG8_LAS bf16x8*)(lds + PG8_SA(b, h) + aoff + m * 2048 + k * 1024); } while (0)
; #define PG8_MMA(ai, bj, At, Bt) do { __builtin_amdgcn_s_setprio(1); _Pragma("unroll") for (int m = 0; m < 4; ++m) _Pragma("unroll") for (int n = 0; n < 2; ++n) _Pragma("unroll") for (int k = 0; k < 2; ++k) \
;         acc[ai][bj][m][n] = __builtin_amdgcn_mfma_f32_16x16x32_bf16(Bt[n][k], At[m][k], acc[ai][bj][m][n], 0, 0, 0); __builtin_amdgcn_s_setprio(0); } while (0)
; #define PG8_WAIT_V(n) asm volatile("s_waitcnt vmcnt(" #n ")" ::: "memory")
; #define PG8_WAIT_L(n) asm volatile("s_waitcnt lgkmcnt(" #n ")" ::: "memory")
; #define PG8_BAR __builtin_amdgcn_s_barrier()
; #define PG8_SCHED __builtin_amdgcn_sched_barrier(0)
; template <class Epi, class Sched, bool ALIGN_EPI = false, bool SP2 = false>
; __device__ __forceinline__ void gemm_phase(PG8_LAS unsigned char* lds, const Gemm g, const Sched& S, const Epi& E) {
;     ...
;         for (int t = 0; t < nt; t += 2) {
;             const bool last = (t == nt - 2);
;             const char* a1 = cA + (size_t)(t + 1) * kstep;
;             const char* a2 = last ? nA : cA + (size_t)(t + 2) * kstep; const char* b2 = last ? nB : cB + (size_t)(t + 2) * kstep;
;     ...
;             PG8_LDA(At, 1, 1); PG8_STAGE(PG8_SB(1, 0), b3, voffB); PG8_STAGE(PG8_SB(1, 1), b3 + hstep, voffB); PG8_STAGE(PG8_SA(1, 0), a3, voffA);
;             PG8_WAIT_V(8); PG8_WAIT_L(0); PG8_BAR; PG8_MMA(1, 0, At, B0); PG8_MMA(1, 1, At, B1); PG8_BAR; PG8_SCHED;
	s_add_i32 s40, s68, s43
	v_lshl_add_u64 v[206:207], v[206:207], 0, s[92:93]
	s_mov_b32 m0, s40
	ds_read_b128 v[174:177], v244 offset:49152
	ds_read_b128 v[178:181], v244 offset:50176
	ds_read_b128 v[182:185], v244 offset:51200
	ds_read_b128 v[186:189], v244 offset:52224
	ds_read_b128 v[190:193], v244 offset:53248
	ds_read_b128 v[194:197], v244 offset:54272
	ds_read_b128 v[198:201], v244 offset:55296
	ds_read_b128 v[202:205], v244 offset:56320
	global_load_lds_dwordx4 v[206:207], off
	v_lshl_add_u64 v[206:207], v[208:209], 0, s[92:93]
	s_add_i32 m0, s40, 0x2000
	s_add_i32 s40, s69, s43
	global_load_lds_dwordx4 v[206:207], off
	v_lshl_add_u64 v[206:207], v[210:211], 0, s[92:93]
	s_mov_b32 m0, s40
	s_nop 0
	global_load_lds_dwordx4 v[206:207], off
	v_lshl_add_u64 v[206:207], v[212:213], 0, s[92:93]
	s_add_i32 m0, s40, 0x2000
	s_nop 0
	global_load_lds_dwordx4 v[206:207], off
	v_lshl_add_u64 v[206:207], v[214:215], 0, s[92:93]
	s_mov_b32 m0, s48
	s_nop 0
	global_load_lds_dwordx4 v[206:207], off
	v_lshl_add_u64 v[206:207], v[216:217], 0, s[92:93]
	s_mov_b32 m0, s49
	s_nop 0
	global_load_lds_dwordx4 v[206:207], off
	s_waitcnt vmcnt(8)
	s_waitcnt lgkmcnt(0)
	s_barrier
	s_setprio 1
	s_waitcnt lgkmcnt(0)
	v_mfma_f32_16x16x32_bf16 v[62:65], v[142:145], v[174:177], v[62:65]
	v_mfma_f32_16x16x32_bf16 v[58:61], v[150:153], v[174:177], v[58:61]
	v_mfma_f32_16x16x32_bf16 v[54:57], v[142:145], v[182:185], v[54:57]
	v_mfma_f32_16x16x32_bf16 v[50:53], v[150:153], v[182:185], v[50:53]
	v_mfma_f32_16x16x32_bf16 v[42:45], v[142:145], v[190:193], v[42:45]
	v_mfma_f32_16x16x32_bf16 v[34:37], v[150:153], v[190:193], v[34:37]
	v_mfma_f32_16x16x32_bf16 v[26:29], v[142:145], v[198:201], v[26:29]
	v_mfma_f32_16x16x32_bf16 v[18:21], v[150:153], v[198:201], v[18:21]
	v_mfma_f32_16x16x32_bf16 v[62:65], v[146:149], v[178:181], v[62:65]
	v_mfma_f32_16x16x32_bf16 v[58:61], v[154:157], v[178:181], v[58:61]
	v_mfma_f32_16x16x32_bf16 v[54:57], v[146:149], v[186:189], v[54:57]
	v_mfma_f32_16x16x32_bf16 v[50:53], v[154:157], v[186:189], v[50:53]
	v_mfma_f32_16x16x32_bf16 v[42:45], v[146:149], v[194:197], v[42:45]
	v_mfma_f32_16x16x32_bf16 v[34:37], v[154:157], v[194:197], v[34:37]
	v_mfma_f32_16x16x32_bf16 v[26:29], v[146:149], v[202:205], v[26:29]
	v_mfma_f32_16x16x32_bf16 v[18:21], v[154:157], v[202:205], v[18:21]
	v_mfma_f32_16x16x32_bf16 v[46:49], v[158:161], v[174:177], v[46:49]
	v_mfma_f32_16x16x32_bf16 v[38:41], v[166:169], v[174:177], v[38:41]
	v_mfma_f32_16x16x32_bf16 v[30:33], v[158:161], v[182:185], v[30:33]
	v_mfma_f32_16x16x32_bf16 v[22:25], v[166:169], v[182:185], v[22:25]
	v_mfma_f32_16x16x32_bf16 v[14:17], v[158:161], v[190:193], v[14:17]
	v_mfma_f32_16x16x32_bf16 v[10:13], v[166:169], v[190:193], v[10:13]
	v_mfma_f32_16x16x32_bf16 v[6:9], v[158:161], v[198:201], v[6:9]
	v_mfma_f32_16x16x32_bf16 v[2:5], v[166:169], v[198:201], v[2:5]
	v_mfma_f32_16x16x32_bf16 v[46:49], v[162:165], v[178:181], v[46:49]
	v_mfma_f32_16x16x32_bf16 v[38:41], v[170:173], v[178:181], v[38:41]
	v_mfma_f32_16x16x32_bf16 v[30:33], v[162:165], v[186:189], v[30:33]
	v_mfma_f32_16x16x32_bf16 v[22:25], v[170:173], v[186:189], v[22:25]
	v_mfma_f32_16x16x32_bf16 v[14:17], v[162:165], v[194:197], v[14:17]
	v_mfma_f32_16x16x32_bf16 v[10:13], v[170:173], v[194:197], v[10:13]
	v_mfma_f32_16x16x32_bf16 v[6:9], v[162:165], v[202:205], v[6:9]
	v_mfma_f32_16x16x32_bf16 v[2:5], v[170:173], v[202:205], v[2:5]
	s_setprio 0
	s_barrier
	s_add_u32 s65, s65, 0x100
	s_addc_u32 s66, s66, 0
	s_add_u32 s38, s38, 0x100
	s_addc_u32 s39, s39, 0
	s_cmp_ge_i32 s67, s51
	s_mov_b32 s40, s67
	s_cbranch_scc0 .LBB0_3248
;     __device__ __forceinline__ void operator()(const f32x4 (&acc)[2][2][4][2], const Unit& u, int wr, int wc, int fr, int fq) const {
;     ...
;                     const f32x4 o0 = xv[g & 1][rr][bj][0] + acc[ai][bj][m][0] * scale, o1 = xv[g & 1][rr][bj][1] + acc[ai][bj][m][1] * scale;
	v_pk_mul_f32 v[206:207], v[128:129], 0.5 op_sel_hi:[1,0]
	v_pk_mul_f32 v[212:213], v[126:127], 0.5 op_sel_hi:[1,0]
	v_pk_mul_f32 v[210:211], v[124:125], 0.5 op_sel_hi:[1,0]
	v_pk_mul_f32 v[208:209], v[122:123], 0.5 op_sel_hi:[1,0]
	v_pk_mul_f32 v[202:203], v[112:113], 0.5 op_sel_hi:[1,0]
	v_pk_mul_f32 v[200:201], v[110:111], 0.5 op_sel_hi:[1,0]
	v_pk_mul_f32 v[198:199], v[104:105], 0.5 op_sel_hi:[1,0]
	v_pk_mul_f32 v[196:197], v[102:103], 0.5 op_sel_hi:[1,0]
	v_pk_mul_f32 v[190:191], v[120:121], 0.5 op_sel_hi:[1,0]
	v_pk_mul_f32 v[188:189], v[118:119], 0.5 op_sel_hi:[1,0]
	v_pk_mul_f32 v[186:187], v[116:117], 0.5 op_sel_hi:[1,0]
	v_pk_mul_f32 v[184:185], v[114:115], 0.5 op_sel_hi:[1,0]
	v_pk_mul_f32 v[182:183], v[96:97], 0.5 op_sel_hi:[1,0]
	v_pk_mul_f32 v[180:181], v[94:95], 0.5 op_sel_hi:[1,0]
	v_pk_mul_f32 v[178:179], v[88:89], 0.5 op_sel_hi:[1,0]
	v_pk_mul_f32 v[176:177], v[86:87], 0.5 op_sel_hi:[1,0]
	v_pk_mul_f32 v[174:175], v[108:109], 0.5 op_sel_hi:[1,0]
	v_pk_mul_f32 v[172:173], v[106:107], 0.5 op_sel_hi:[1,0]
	v_pk_mul_f32 v[170:171], v[100:101], 0.5 op_sel_hi:[1,0]
	v_pk_mul_f32 v[168:169], v[98:99], 0.5 op_sel_hi:[1,0]
	v_pk_mul_f32 v[166:167], v[80:81], 0.5 op_sel_hi:[1,0]
	v_pk_mul_f32 v[164:165], v[78:79], 0.5 op_sel_hi:[1,0]
	v_pk_mul_f32 v[162:163], v[76:77], 0.5 op_sel_hi:[1,0]
	v_pk_mul_f32 v[160:161], v[74:75], 0.5 op_sel_hi:[1,0]
	v_pk_mul_f32 v[158:159], v[92:93], 0.5 op_sel_hi:[1,0]
	v_pk_mul_f32 v[156:157], v[90:91], 0.5 op_sel_hi:[1,0]
	v_pk_mul_f32 v[154:155], v[84:85], 0.5 op_sel_hi:[1,0]
	v_pk_mul_f32 v[152:153], v[82:83], 0.5 op_sel_hi:[1,0]
	v_pk_mul_f32 v[150:151], v[72:73], 0.5 op_sel_hi:[1,0]
	v_pk_mul_f32 v[148:149], v[70:71], 0.5 op_sel_hi:[1,0]
	v_pk_mul_f32 v[146:147], v[68:69], 0.5 op_sel_hi:[1,0]
	v_pk_mul_f32 v[144:145], v[66:67], 0.5 op_sel_hi:[1,0]
	v_pk_mul_f32 v[128:129], v[64:65], 0.5 op_sel_hi:[1,0]
	v_pk_mul_f32 v[126:127], v[62:63], 0.5 op_sel_hi:[1,0]
	v_pk_mul_f32 v[124:125], v[60:61], 0.5 op_sel_hi:[1,0]
	v_pk_mul_f32 v[122:123], v[58:59], 0.5 op_sel_hi:[1,0]
	v_pk_mul_f32 v[120:121], v[48:49], 0.5 op_sel_hi:[1,0]
	v_pk_mul_f32 v[118:119], v[46:47], 0.5 op_sel_hi:[1,0]
	v_pk_mul_f32 v[116:117], v[40:41], 0.5 op_sel_hi:[1,0]
	v_pk_mul_f32 v[114:115], v[38:39], 0.5 op_sel_hi:[1,0]
	v_pk_mul_f32 v[112:113], v[56:57], 0.5 op_sel_hi:[1,0]
	v_pk_mul_f32 v[110:111], v[54:55], 0.5 op_sel_hi:[1,0]
	v_pk_mul_f32 v[108:109], v[52:53], 0.5 op_sel_hi:[1,0]
	v_pk_mul_f32 v[106:107], v[50:51], 0.5 op_sel_hi:[1,0]
	v_pk_mul_f32 v[104:105], v[32:33], 0.5 op_sel_hi:[1,0]
	v_pk_mul_f32 v[102:103], v[30:31], 0.5 op_sel_hi:[1,0]
	v_pk_mul_f32 v[100:101], v[24:25], 0.5 op_sel_hi:[1,0]
	v_pk_mul_f32 v[98:99], v[22:23], 0.5 op_sel_hi:[1,0]
	v_pk_mul_f32 v[96:97], v[44:45], 0.5 op_sel_hi:[1,0]
	v_pk_mul_f32 v[94:95], v[42:43], 0.5 op_sel_hi:[1,0]
	v_pk_mul_f32 v[92:93], v[36:37], 0.5 op_sel_hi:[1,0]
	v_pk_mul_f32 v[90:91], v[34:35], 0.5 op_sel_hi:[1,0]
	v_pk_mul_f32 v[88:89], v[16:17], 0.5 op_sel_hi:[1,0]
	v_pk_mul_f32 v[86:87], v[14:15], 0.5 op_sel_hi:[1,0]
	v_pk_mul_f32 v[84:85], v[12:13], 0.5 op_sel_hi:[1,0]
	v_pk_mul_f32 v[82:83], v[10:11], 0.5 op_sel_hi:[1,0]
	v_pk_mul_f32 v[80:81], v[28:29], 0.5 op_sel_hi:[1,0]
	v_pk_mul_f32 v[78:79], v[26:27], 0.5 op_sel_hi:[1,0]
	v_pk_mul_f32 v[76:77], v[20:21], 0.5 op_sel_hi:[1,0]
	v_pk_mul_f32 v[74:75], v[18:19], 0.5 op_sel_hi:[1,0]
	v_pk_mul_f32 v[72:73], v[8:9], 0.5 op_sel_hi:[1,0]
	v_pk_mul_f32 v[70:71], v[6:7], 0.5 op_sel_hi:[1,0]
	v_pk_mul_f32 v[68:69], v[4:5], 0.5 op_sel_hi:[1,0]
	v_pk_mul_f32 v[66:67], v[2:3], 0.5 op_sel_hi:[1,0]
	v_readlane_b32 s68, v252, 27
	v_readlane_b32 s69, v252, 28
	v_readlane_b32 s70, v252, 29
	v_readlane_b32 s71, v252, 30

; #define PG8_STAGE(bufoff, gbase, voff) do { _Pragma("unroll") for (int _i = 0; _i < 2; ++_i) \
;         __builtin_amdgcn_global_load_lds((const unsigned*)((const char*)(gbase) + (voff)[_i]), (PG8_LAS unsigned*)(lds + (bufoff) + ldsw + _i * 8192), 16, 0, 0); } while (0)
; #define PG8_LDA(dst, b, h) do { _Pragma("unroll") for (int m = 0; m < 4; ++m) _Pragma("unroll") for (int k = 0; k < 2; ++k) dst[m][k] = *(const PG8_LAS bf16x8*)(lds + PG8_SA(b, h) + aoff + m * 2048 + k * 1024); } while (0)
; #define PG8_LDB(dst, b, h) do { _Pragma("unroll") for (int n = 0; n < 2; ++n) _Pragma("unroll") for (int k = 0; k < 2; ++k) dst[n][k] = *(const PG8_LAS bf16x8*)(lds + PG8_SB(b, h) + boff + n * 2048 + k * 1024); } while (0)
; #define PG8_MMA(ai, bj, At, Bt) do { __builtin_amdgcn_s_setprio(1); _Pragma("unroll") for (int m = 0; m < 4; ++m) _Pragma("unroll") for (int n = 0; n < 2; ++n) _Pragma("unroll") for (int k = 0; k < 2; ++k) \
;         acc[ai][bj][m][n] = __builtin_amdgcn_mfma_f32_16x16x32_bf16(Bt[n][k], At[m][k], acc[ai][bj][m][n], 0, 0, 0); __builtin_amdgcn_s_setprio(0); } while (0)
; #define PG8_WAIT_V(n) asm volatile("s_waitcnt vmcnt(" #n ")" ::: "memory")
; #define PG8_BAR __builtin_amdgcn_s_barrier()
; template <class Epi, class Sched, bool ALIGN_EPI = false, bool SP2 = false>
; __device__ __forceinline__ void gemm_phase(PG8_LAS unsigned char* lds, const Gemm g, const Sched& S, const Epi& E) {
;     ...
;         for (int t = 0; t < nt; t += 2) {
;             const bool last = (t == nt - 2);
;             const char* a1 = cA + (size_t)(t + 1) * kstep;
;             const char* a2 = last ? nA : cA + (size_t)(t + 2) * kstep; const char* b2 = last ? nB : cB + (size_t)(t + 2) * kstep;
;             const char* a3 = a2 + kstep; const char* b3 = b2 + kstep;
;             if (last && has_next) S.a_ready(nxt);
;             if constexpr (SP2) {
;             PG8_LDB(B0, 0, 0); PG8_LDB(B1, 0, 1); PG8_SCHED; PG8_LDA(At, 0, 0); PG8_STAGE(PG8_SA(1, 1), a1 + hstep, voffA);
;             PG8_WAIT_V(8); PG8_WAIT_L(0); PG8_BAR; PG8_MMA(0, 0, At, B0); PG8_MMA(0, 1, At, B1); PG8_BAR; PG8_SCHED;
;             PG8_LDA(At, 0, 1); PG8_STAGE(PG8_SB(0, 0), b2, voffB); PG8_STAGE(PG8_SB(0, 1), b2 + hstep, voffB); PG8_STAGE(PG8_SA(0, 0), a2, voffA);
;             PG8_WAIT_V(8); PG8_WAIT_L(0); PG8_BAR; PG8_MMA(1, 0, At, B0); PG8_MMA(1, 1, At, B1); PG8_BAR; PG8_SCHED;
.LBB0_3346:
	s_add_i32 s58, s28, 2
	s_add_u32 s59, s26, 0x80
	s_addc_u32 s29, s27, 0
	s_add_i32 s62, 0, 0x10000
	s_cmp_eq_u32 s50, s28
	s_cselect_b32 s29, s1, s29
	s_cselect_b32 s28, s0, s59
	v_add_u32_e32 v148, s62, v149
	s_cselect_b32 s61, s25, s57
	s_cselect_b32 s60, s24, s56
	s_add_i32 s59, 0, 0x14000
	ds_read_b128 v[130:133], v148
	ds_read_b128 v[154:157], v148 offset:1024
	ds_read_b128 v[158:161], v148 offset:2048
	ds_read_b128 v[162:165], v148 offset:3072
	v_add_u32_e32 v148, s59, v149
	ds_read_b128 v[166:169], v148
	ds_read_b128 v[170:173], v148 offset:1024
	ds_read_b128 v[174:177], v148 offset:2048
	ds_read_b128 v[178:181], v148 offset:3072
	v_lshl_add_u64 v[214:215], s[26:27], 0, v[146:147]
	s_add_i32 m0, s43, 0xc000
	ds_read_b128 v[182:185], v153
	ds_read_b128 v[186:189], v153 offset:1024
	ds_read_b128 v[190:193], v153 offset:2048
	ds_read_b128 v[194:197], v153 offset:3072
	ds_read_b128 v[198:201], v153 offset:4096
	ds_read_b128 v[202:205], v153 offset:5120
	ds_read_b128 v[206:209], v153 offset:6144
	ds_read_b128 v[210:213], v153 offset:7168
	global_load_lds_dwordx4 v[214:215], off
	v_lshl_add_u64 v[214:215], s[26:27], 0, v[144:145]
	s_add_i32 m0, s43, 0xe000
	s_nop 0
	global_load_lds_dwordx4 v[214:215], off
	s_waitcnt vmcnt(8)
	s_waitcnt lgkmcnt(0)
	s_barrier
	s_setprio 1
	s_waitcnt lgkmcnt(0)
	v_mfma_f32_16x16x32_bf16 v[126:129], v[130:133], v[182:185], v[126:129]
	v_mfma_f32_16x16x32_bf16 v[122:125], v[158:161], v[182:185], v[122:125]
	v_mfma_f32_16x16x32_bf16 v[110:113], v[130:133], v[190:193], v[110:113]
	v_mfma_f32_16x16x32_bf16 v[106:109], v[158:161], v[190:193], v[106:109]
	v_mfma_f32_16x16x32_bf16 v[94:97], v[130:133], v[198:201], v[94:97]
	v_mfma_f32_16x16x32_bf16 v[90:93], v[158:161], v[198:201], v[90:93]
	v_mfma_f32_16x16x32_bf16 v[78:81], v[130:133], v[206:209], v[78:81]
	v_mfma_f32_16x16x32_bf16 v[74:77], v[158:161], v[206:209], v[74:77]
	v_mfma_f32_16x16x32_bf16 v[126:129], v[154:157], v[186:189], v[126:129]
	v_mfma_f32_16x16x32_bf16 v[122:125], v[162:165], v[186:189], v[122:125]
	v_mfma_f32_16x16x32_bf16 v[110:113], v[154:157], v[194:197], v[110:113]
	v_mfma_f32_16x16x32_bf16 v[106:109], v[162:165], v[194:197], v[106:109]
	v_mfma_f32_16x16x32_bf16 v[94:97], v[154:157], v[202:205], v[94:97]
	v_mfma_f32_16x16x32_bf16 v[90:93], v[162:165], v[202:205], v[90:93]
	v_mfma_f32_16x16x32_bf16 v[78:81], v[154:157], v[210:213], v[78:81]
	v_mfma_f32_16x16x32_bf16 v[74:77], v[162:165], v[210:213], v[74:77]
	v_mfma_f32_16x16x32_bf16 v[118:121], v[166:169], v[182:185], v[118:121]
	v_mfma_f32_16x16x32_bf16 v[114:117], v[174:177], v[182:185], v[114:117]
	v_mfma_f32_16x16x32_bf16 v[102:105], v[166:169], v[190:193], v[102:105]
	v_mfma_f32_16x16x32_bf16 v[98:101], v[174:177], v[190:193], v[98:101]
	v_mfma_f32_16x16x32_bf16 v[86:89], v[166:169], v[198:201], v[86:89]
	v_mfma_f32_16x16x32_bf16 v[82:85], v[174:177], v[198:201], v[82:85]
	v_mfma_f32_16x16x32_bf16 v[70:73], v[166:169], v[206:209], v[70:73]
	v_mfma_f32_16x16x32_bf16 v[66:69], v[174:177], v[206:209], v[66:69]
	v_mfma_f32_16x16x32_bf16 v[118:121], v[170:173], v[186:189], v[118:121]
	v_mfma_f32_16x16x32_bf16 v[114:117], v[178:181], v[186:189], v[114:117]
	v_mfma_f32_16x16x32_bf16 v[102:105], v[170:173], v[194:197], v[102:105]
	v_mfma_f32_16x16x32_bf16 v[98:101], v[178:181], v[194:197], v[98:101]
	v_mfma_f32_16x16x32_bf16 v[86:89], v[170:173], v[202:205], v[86:89]
	v_mfma_f32_16x16x32_bf16 v[82:85], v[178:181], v[202:205], v[82:85]
	v_mfma_f32_16x16x32_bf16 v[70:73], v[170:173], v[210:213], v[70:73]
	v_mfma_f32_16x16x32_bf16 v[66:69], v[178:181], v[210:213], v[66:69]
	s_setprio 0
	s_barrier
	s_add_i32 s62, s62, s38
	v_lshl_add_u64 v[214:215], s[60:61], 0, v[136:137]
	s_mov_b32 m0, s62
	ds_read_b128 v[182:185], v153 offset:16384
	ds_read_b128 v[186:189], v153 offset:17408
	ds_read_b128 v[190:193], v153 offset:18432
	ds_read_b128 v[194:197], v153 offset:19456
	ds_read_b128 v[198:201], v153 offset:20480
	ds_read_b128 v[202:205], v153 offset:21504
	ds_read_b128 v[206:209], v153 offset:22528
	ds_read_b128 v[210:213], v153 offset:23552
	global_load_lds_dwordx4 v[214:215], off
	s_add_i32 m0, s62, 0x2000
	v_lshl_add_u64 v[216:217], s[60:61], 0, v[140:141]
	s_add_u32 s60, s60, s12
	s_addc_u32 s61, s61, s13
	s_add_i32 s59, s59, s38
	global_load_lds_dwordx4 v[216:217], off
	v_lshl_add_u64 v[218:219], s[60:61], 0, v[136:137]
	s_mov_b32 m0, s59
	v_lshl_add_u64 v[228:229], s[60:61], 0, v[140:141]
	global_load_lds_dwordx4 v[218:219], off
	s_add_i32 m0, s59, 0x2000
	v_lshl_add_u64 v[242:243], s[28:29], 0, v[134:135]
	global_load_lds_dwordx4 v[228:229], off
	s_mov_b32 m0, s43
	v_lshl_add_u64 v[244:245], s[28:29], 0, v[138:139]
	global_load_lds_dwordx4 v[242:243], off
	s_mov_b32 m0, s44
	s_nop 0
	global_load_lds_dwordx4 v[244:245], off
	s_waitcnt vmcnt(8)
	s_waitcnt lgkmcnt(0)
	s_barrier
; #define PG8_STAGE(bufoff, gbase, voff) do { _Pragma("unroll") for (int _i = 0; _i < 2; ++_i) \
;         __builtin_amdgcn_global_load_lds((const unsigned*)((const char*)(gbase) + (voff)[_i]), (PG8_LAS unsigned*)(lds + (bufoff) + ldsw + _i * 8192), 16, 0, 0); } while (0)
; #define PG8_LDA(dst, b, h) do { _Pragma("unroll") for (int m = 0; m < 4; ++m) _Pragma("unroll") for (int k = 0; k < 2; ++k) dst[m][k] = *(const PG8_LAS bf16x8*)(lds + PG8_SA(b, h) + aoff + m * 2048 + k * 1024); } while (0)
; #define PG8_LDB(dst, b, h) do { _Pragma("unroll") for (int n = 0; n < 2; ++n) _Pragma("unroll") for (int k = 0; k < 2; ++k) dst[n][k] = *(const PG8_LAS bf16x8*)(lds + PG8_SB(b, h) + boff + n * 2048 + k * 1024); } while (0)
; #define PG8_MMA(ai, bj, At, Bt) do { __builtin_amdgcn_s_setprio(1); _Pragma("unroll") for (int m = 0; m < 4; ++m) _Pragma("unroll") for (int n = 0; n < 2; ++n) _Pragma("unroll") for (int k = 0; k < 2; ++k) \
;         acc[ai][bj][m][n] = __builtin_amdgcn_mfma_f32_16x16x32_bf16(Bt[n][k], At[m][k], acc[ai][bj][m][n], 0, 0, 0); __builtin_amdgcn_s_setprio(0); } while (0)
; #define PG8_WAIT_V(n) asm volatile("s_waitcnt vmcnt(" #n ")" ::: "memory")
; #define PG8_WAIT_L(n) asm volatile("s_waitcnt lgkmcnt(" #n ")" ::: "memory")
; #define PG8_BAR __builtin_amdgcn_s_barrier()
; #define PG8_SCHED __builtin_amdgcn_sched_barrier(0)
; template <class Epi, class Sched, bool ALIGN_EPI = false, bool SP2 = false>
; __device__ __forceinline__ void gemm_phase(PG8_LAS unsigned char* lds, const Gemm g, const Sched& S, const Epi& E) {
;     ...
;             PG8_WAIT_V(8); PG8_WAIT_L(0); PG8_BAR; PG8_MMA(1, 0, At, B0); PG8_MMA(1, 1, At, B1); PG8_BAR; PG8_SCHED;
;             PG8_LDB(B0, 1, 0); PG8_LDB(B1, 1, 1); PG8_SCHED; PG8_LDA(At, 1, 0); PG8_STAGE(PG8_SA(0, 1), a2 + hstep, voffA);
;             PG8_WAIT_V(8); PG8_WAIT_L(0); PG8_BAR; PG8_MMA(0, 0, At, B0); PG8_MMA(0, 1, At, B1); PG8_BAR; PG8_SCHED;
	s_setprio 1
	s_waitcnt lgkmcnt(0)
	v_mfma_f32_16x16x32_bf16 v[62:65], v[130:133], v[182:185], v[62:65]
	v_mfma_f32_16x16x32_bf16 v[58:61], v[158:161], v[182:185], v[58:61]
	v_mfma_f32_16x16x32_bf16 v[46:49], v[130:133], v[190:193], v[46:49]
	v_mfma_f32_16x16x32_bf16 v[42:45], v[158:161], v[190:193], v[42:45]
	v_mfma_f32_16x16x32_bf16 v[30:33], v[130:133], v[198:201], v[30:33]
	v_mfma_f32_16x16x32_bf16 v[26:29], v[158:161], v[198:201], v[26:29]
	v_mfma_f32_16x16x32_bf16 v[14:17], v[130:133], v[206:209], v[14:17]
	v_mfma_f32_16x16x32_bf16 v[10:13], v[158:161], v[206:209], v[10:13]
	v_mfma_f32_16x16x32_bf16 v[62:65], v[154:157], v[186:189], v[62:65]
	v_mfma_f32_16x16x32_bf16 v[58:61], v[162:165], v[186:189], v[58:61]
	v_mfma_f32_16x16x32_bf16 v[46:49], v[154:157], v[194:197], v[46:49]
	v_mfma_f32_16x16x32_bf16 v[42:45], v[162:165], v[194:197], v[42:45]
	v_mfma_f32_16x16x32_bf16 v[30:33], v[154:157], v[202:205], v[30:33]
	v_mfma_f32_16x16x32_bf16 v[26:29], v[162:165], v[202:205], v[26:29]
	v_mfma_f32_16x16x32_bf16 v[14:17], v[154:157], v[210:213], v[14:17]
	v_mfma_f32_16x16x32_bf16 v[10:13], v[162:165], v[210:213], v[10:13]
	v_mfma_f32_16x16x32_bf16 v[54:57], v[166:169], v[182:185], v[54:57]
	v_mfma_f32_16x16x32_bf16 v[50:53], v[174:177], v[182:185], v[50:53]
	v_mfma_f32_16x16x32_bf16 v[38:41], v[166:169], v[190:193], v[38:41]
	v_mfma_f32_16x16x32_bf16 v[34:37], v[174:177], v[190:193], v[34:37]
	v_mfma_f32_16x16x32_bf16 v[22:25], v[166:169], v[198:201], v[22:25]
	v_mfma_f32_16x16x32_bf16 v[18:21], v[174:177], v[198:201], v[18:21]
	v_mfma_f32_16x16x32_bf16 v[6:9], v[166:169], v[206:209], v[6:9]
	v_mfma_f32_16x16x32_bf16 v[2:5], v[174:177], v[206:209], v[2:5]
	v_mfma_f32_16x16x32_bf16 v[54:57], v[170:173], v[186:189], v[54:57]
	v_mfma_f32_16x16x32_bf16 v[50:53], v[178:181], v[186:189], v[50:53]
	v_mfma_f32_16x16x32_bf16 v[38:41], v[170:173], v[194:197], v[38:41]
	v_mfma_f32_16x16x32_bf16 v[34:37], v[178:181], v[194:197], v[34:37]
	v_mfma_f32_16x16x32_bf16 v[22:25], v[170:173], v[202:205], v[22:25]
	v_mfma_f32_16x16x32_bf16 v[18:21], v[178:181], v[202:205], v[18:21]
	v_mfma_f32_16x16x32_bf16 v[6:9], v[170:173], v[210:213], v[6:9]
	v_mfma_f32_16x16x32_bf16 v[2:5], v[178:181], v[210:213], v[2:5]
	s_setprio 0
	s_barrier
	s_add_i32 s59, 0, 0x18000
	v_add_u32_e32 v148, s59, v149
	s_add_i32 s60, 0, 0x1c000
	ds_read_b128 v[130:133], v148
	ds_read_b128 v[154:157], v148 offset:1024
	ds_read_b128 v[158:161], v148 offset:2048
	ds_read_b128 v[162:165], v148 offset:3072
	v_add_u32_e32 v148, s60, v149
	ds_read_b128 v[166:169], v148
	ds_read_b128 v[170:173], v148 offset:1024
	ds_read_b128 v[174:177], v148 offset:2048
	ds_read_b128 v[178:181], v148 offset:3072
	s_add_u32 s28, s28, s12
	s_addc_u32 s29, s29, s13
	s_mov_b32 m0, s45
	v_lshl_add_u64 v[246:247], s[28:29], 0, v[134:135]
	ds_read_b128 v[182:185], v153 offset:32768
	ds_read_b128 v[186:189], v153 offset:33792
	ds_read_b128 v[190:193], v153 offset:34816
	ds_read_b128 v[194:197], v153 offset:35840
	ds_read_b128 v[198:201], v153 offset:36864
	ds_read_b128 v[202:205], v153 offset:37888
	ds_read_b128 v[206:209], v153 offset:38912
	ds_read_b128 v[210:213], v153 offset:39936
	global_load_lds_dwordx4 v[246:247], off
	v_lshl_add_u64 v[246:247], s[28:29], 0, v[138:139]
	s_mov_b32 m0, s46
	s_nop 0
	global_load_lds_dwordx4 v[246:247], off
	s_waitcnt vmcnt(8)
	s_waitcnt lgkmcnt(0)
	s_barrier
	s_setprio 1
	s_waitcnt lgkmcnt(0)
	v_mfma_f32_16x16x32_bf16 v[126:129], v[130:133], v[182:185], v[126:129]
	v_mfma_f32_16x16x32_bf16 v[122:125], v[158:161], v[182:185], v[122:125]
	v_mfma_f32_16x16x32_bf16 v[110:113], v[130:133], v[190:193], v[110:113]
	v_mfma_f32_16x16x32_bf16 v[106:109], v[158:161], v[190:193], v[106:109]
	v_mfma_f32_16x16x32_bf16 v[94:97], v[130:133], v[198:201], v[94:97]
	v_mfma_f32_16x16x32_bf16 v[90:93], v[158:161], v[198:201], v[90:93]
	v_mfma_f32_16x16x32_bf16 v[78:81], v[130:133], v[206:209], v[78:81]
	v_mfma_f32_16x16x32_bf16 v[74:77], v[158:161], v[206:209], v[74:77]
	v_mfma_f32_16x16x32_bf16 v[126:129], v[154:157], v[186:189], v[126:129]
	v_mfma_f32_16x16x32_bf16 v[122:125], v[162:165], v[186:189], v[122:125]
	v_mfma_f32_16x16x32_bf16 v[110:113], v[154:157], v[194:197], v[110:113]
	v_mfma_f32_16x16x32_bf16 v[106:109], v[162:165], v[194:197], v[106:109]
	v_mfma_f32_16x16x32_bf16 v[94:97], v[154:157], v[202:205], v[94:97]
	v_mfma_f32_16x16x32_bf16 v[90:93], v[162:165], v[202:205], v[90:93]
	v_mfma_f32_16x16x32_bf16 v[78:81], v[154:157], v[210:213], v[78:81]
	v_mfma_f32_16x16x32_bf16 v[74:77], v[162:165], v[210:213], v[74:77]
	v_mfma_f32_16x16x32_bf16 v[118:121], v[166:169], v[182:185], v[118:121]
	v_mfma_f32_16x16x32_bf16 v[114:117], v[174:177], v[182:185], v[114:117]
	v_mfma_f32_16x16x32_bf16 v[102:105], v[166:169], v[190:193], v[102:105]
	v_mfma_f32_16x16x32_bf16 v[98:101], v[174:177], v[190:193], v[98:101]
	v_mfma_f32_16x16x32_bf16 v[86:89], v[166:169], v[198:201], v[86:89]
	v_mfma_f32_16x16x32_bf16 v[82:85], v[174:177], v[198:201], v[82:85]
	v_mfma_f32_16x16x32_bf16 v[70:73], v[166:169], v[206:209], v[70:73]
	v_mfma_f32_16x16x32_bf16 v[66:69], v[174:177], v[206:209], v[66:69]
	v_mfma_f32_16x16x32_bf16 v[118:121], v[170:173], v[186:189], v[118:121]
	v_mfma_f32_16x16x32_bf16 v[114:117], v[178:181], v[186:189], v[114:117]
	v_mfma_f32_16x16x32_bf16 v[102:105], v[170:173], v[194:197], v[102:105]
	v_mfma_f32_16x16x32_bf16 v[98:101], v[178:181], v[194:197], v[98:101]
	v_mfma_f32_16x16x32_bf16 v[86:89], v[170:173], v[202:205], v[86:89]
	v_mfma_f32_16x16x32_bf16 v[82:85], v[178:181], v[202:205], v[82:85]
	v_mfma_f32_16x16x32_bf16 v[70:73], v[170:173], v[210:213], v[70:73]
	v_mfma_f32_16x16x32_bf16 v[66:69], v[178:181], v[210:213], v[66:69]
	s_setprio 0
	s_barrier
; #define PG8_STAGE(bufoff, gbase, voff) do { _Pragma("unroll") for (int _i = 0; _i < 2; ++_i) \
;         __builtin_amdgcn_global_load_lds((const unsigned*)((const char*)(gbase) + (voff)[_i]), (PG8_LAS unsigned*)(lds + (bufoff) + ldsw + _i * 8192), 16, 0, 0); } while (0)
; #define PG8_LDA(dst, b, h) do { _Pragma("unroll") for (int m = 0; m < 4; ++m) _Pragma("unroll") for (int k = 0; k < 2; ++k) dst[m][k] = *(const PG8_LAS bf16x8*)(lds + PG8_SA(b, h) + aoff + m * 2048 + k * 1024); } while (0)
; #define PG8_MMA(ai, bj, At, Bt) do { __builtin_amdgcn_s_setprio(1); _Pragma("unroll") for (int m = 0; m < 4; ++m) _Pragma("unroll") for (int n = 0; n < 2; ++n) _Pragma("unroll") for (int k = 0; k < 2; ++k) \
;         acc[ai][bj][m][n] = __builtin_amdgcn_mfma_f32_16x16x32_bf16(Bt[n][k], At[m][k], acc[ai][bj][m][n], 0, 0, 0); __builtin_amdgcn_s_setprio(0); } while (0)
; #define PG8_WAIT_V(n) asm volatile("s_waitcnt vmcnt(" #n ")" ::: "memory")
; #define PG8_WAIT_L(n) asm volatile("s_waitcnt lgkmcnt(" #n ")" ::: "memory")
; #define PG8_BAR __builtin_amdgcn_s_barrier()
; #define PG8_SCHED __builtin_amdgcn_sched_barrier(0)
; template <class Epi, class Sched, bool ALIGN_EPI = false, bool SP2 = false>
; __device__ __forceinline__ void gemm_phase(PG8_LAS unsigned char* lds, const Gemm g, const Sched& S, const Epi& E) {
;     ...
;         for (int t = 0; t < nt; t += 2) {
;             const bool last = (t == nt - 2);
;             const char* a1 = cA + (size_t)(t + 1) * kstep;
;             const char* a2 = last ? nA : cA + (size_t)(t + 2) * kstep; const char* b2 = last ? nB : cB + (size_t)(t + 2) * kstep;
;     ...
;             PG8_LDA(At, 1, 1); PG8_STAGE(PG8_SB(1, 0), b3, voffB); PG8_STAGE(PG8_SB(1, 1), b3 + hstep, voffB); PG8_STAGE(PG8_SA(1, 0), a3, voffA);
;             PG8_WAIT_V(8); PG8_WAIT_L(0); PG8_BAR; PG8_MMA(1, 0, At, B0); PG8_MMA(1, 1, At, B1); PG8_BAR; PG8_SCHED;
	s_add_i32 s28, s59, s38
	v_lshl_add_u64 v[214:215], v[214:215], 0, s[92:93]
	s_mov_b32 m0, s28
	ds_read_b128 v[182:185], v153 offset:49152
	ds_read_b128 v[186:189], v153 offset:50176
	ds_read_b128 v[190:193], v153 offset:51200
	ds_read_b128 v[194:197], v153 offset:52224
	ds_read_b128 v[198:201], v153 offset:53248
	ds_read_b128 v[202:205], v153 offset:54272
	ds_read_b128 v[206:209], v153 offset:55296
	ds_read_b128 v[210:213], v153 offset:56320
	global_load_lds_dwordx4 v[214:215], off
	v_lshl_add_u64 v[214:215], v[216:217], 0, s[92:93]
	s_add_i32 m0, s28, 0x2000
	s_add_i32 s28, s60, s38
	global_load_lds_dwordx4 v[214:215], off
	v_lshl_add_u64 v[214:215], v[218:219], 0, s[92:93]
	s_mov_b32 m0, s28
	s_nop 0
	global_load_lds_dwordx4 v[214:215], off
	v_lshl_add_u64 v[214:215], v[228:229], 0, s[92:93]
	s_add_i32 m0, s28, 0x2000
	s_nop 0
	global_load_lds_dwordx4 v[214:215], off
	v_lshl_add_u64 v[214:215], v[242:243], 0, s[92:93]
	s_mov_b32 m0, s47
	s_nop 0
	global_load_lds_dwordx4 v[214:215], off
	v_lshl_add_u64 v[214:215], v[244:245], 0, s[92:93]
	s_mov_b32 m0, s48
	s_nop 0
	global_load_lds_dwordx4 v[214:215], off
	s_waitcnt vmcnt(8)
	s_waitcnt lgkmcnt(0)
	s_barrier
	s_setprio 1
	s_waitcnt lgkmcnt(0)
	v_mfma_f32_16x16x32_bf16 v[62:65], v[130:133], v[182:185], v[62:65]
	v_mfma_f32_16x16x32_bf16 v[58:61], v[158:161], v[182:185], v[58:61]
	v_mfma_f32_16x16x32_bf16 v[46:49], v[130:133], v[190:193], v[46:49]
	v_mfma_f32_16x16x32_bf16 v[42:45], v[158:161], v[190:193], v[42:45]
	v_mfma_f32_16x16x32_bf16 v[30:33], v[130:133], v[198:201], v[30:33]
	v_mfma_f32_16x16x32_bf16 v[26:29], v[158:161], v[198:201], v[26:29]
	v_mfma_f32_16x16x32_bf16 v[14:17], v[130:133], v[206:209], v[14:17]
	v_mfma_f32_16x16x32_bf16 v[10:13], v[158:161], v[206:209], v[10:13]
	v_mfma_f32_16x16x32_bf16 v[62:65], v[154:157], v[186:189], v[62:65]
	v_mfma_f32_16x16x32_bf16 v[58:61], v[162:165], v[186:189], v[58:61]
	v_mfma_f32_16x16x32_bf16 v[46:49], v[154:157], v[194:197], v[46:49]
	v_mfma_f32_16x16x32_bf16 v[42:45], v[162:165], v[194:197], v[42:45]
	v_mfma_f32_16x16x32_bf16 v[30:33], v[154:157], v[202:205], v[30:33]
	v_mfma_f32_16x16x32_bf16 v[26:29], v[162:165], v[202:205], v[26:29]
	v_mfma_f32_16x16x32_bf16 v[14:17], v[154:157], v[210:213], v[14:17]
	v_mfma_f32_16x16x32_bf16 v[10:13], v[162:165], v[210:213], v[10:13]
	v_mfma_f32_16x16x32_bf16 v[54:57], v[166:169], v[182:185], v[54:57]
	v_mfma_f32_16x16x32_bf16 v[50:53], v[174:177], v[182:185], v[50:53]
	v_mfma_f32_16x16x32_bf16 v[38:41], v[166:169], v[190:193], v[38:41]
	v_mfma_f32_16x16x32_bf16 v[34:37], v[174:177], v[190:193], v[34:37]
	v_mfma_f32_16x16x32_bf16 v[22:25], v[166:169], v[198:201], v[22:25]
	v_mfma_f32_16x16x32_bf16 v[18:21], v[174:177], v[198:201], v[18:21]
	v_mfma_f32_16x16x32_bf16 v[6:9], v[166:169], v[206:209], v[6:9]
	v_mfma_f32_16x16x32_bf16 v[2:5], v[174:177], v[206:209], v[2:5]
	v_mfma_f32_16x16x32_bf16 v[54:57], v[170:173], v[186:189], v[54:57]
	v_mfma_f32_16x16x32_bf16 v[50:53], v[178:181], v[186:189], v[50:53]
	v_mfma_f32_16x16x32_bf16 v[38:41], v[170:173], v[194:197], v[38:41]
	v_mfma_f32_16x16x32_bf16 v[34:37], v[178:181], v[194:197], v[34:37]
	v_mfma_f32_16x16x32_bf16 v[22:25], v[170:173], v[202:205], v[22:25]
	v_mfma_f32_16x16x32_bf16 v[18:21], v[178:181], v[202:205], v[18:21]
	v_mfma_f32_16x16x32_bf16 v[6:9], v[170:173], v[210:213], v[6:9]
	v_mfma_f32_16x16x32_bf16 v[2:5], v[178:181], v[210:213], v[2:5]
	s_setprio 0
	s_barrier
	s_add_u32 s56, s56, 0x100
	s_addc_u32 s57, s57, 0
	s_add_u32 s26, s26, 0x100
	s_addc_u32 s27, s27, 0
	s_cmp_ge_i32 s58, s49
	s_mov_b32 s28, s58
	s_cbranch_scc0 .LBB0_3346

; #define PG8_STAGE(bufoff, gbase, voff) do { _Pragma("unroll") for (int _i = 0; _i < 2; ++_i) \
;         __builtin_amdgcn_global_load_lds((const unsigned*)((const char*)(gbase) + (voff)[_i]), (PG8_LAS unsigned*)(lds + (bufoff) + ldsw + _i * 8192), 16, 0, 0); } while (0)
; #define PG8_LDA(dst, b, h) do { _Pragma("unroll") for (int m = 0; m < 4; ++m) _Pragma("unroll") for (int k = 0; k < 2; ++k) dst[m][k] = *(const PG8_LAS bf16x8*)(lds + PG8_SA(b, h) + aoff + m * 2048 + k * 1024); } while (0)
; #define PG8_LDB(dst, b, h) do { _Pragma("unroll") for (int n = 0; n < 2; ++n) _Pragma("unroll") for (int k = 0; k < 2; ++k) dst[n][k] = *(const PG8_LAS bf16x8*)(lds + PG8_SB(b, h) + boff + n * 2048 + k * 1024); } while (0)
; #define PG8_MMA(ai, bj, At, Bt) do { __builtin_amdgcn_s_setprio(1); _Pragma("unroll") for (int m = 0; m < 4; ++m) _Pragma("unroll") for (int n = 0; n < 2; ++n) _Pragma("unroll") for (int k = 0; k < 2; ++k) \
;         acc[ai][bj][m][n] = __builtin_amdgcn_mfma_f32_16x16x32_bf16(Bt[n][k], At[m][k], acc[ai][bj][m][n], 0, 0, 0); __builtin_amdgcn_s_setprio(0); } while (0)
; #define PG8_WAIT_V(n) asm volatile("s_waitcnt vmcnt(" #n ")" ::: "memory")
; #define PG8_BAR __builtin_amdgcn_s_barrier()
; template <class Epi, class Sched, bool ALIGN_EPI = false, bool SP2 = false>
; __device__ __forceinline__ void gemm_phase(PG8_LAS unsigned char* lds, const Gemm g, const Sched& S, const Epi& E) {
;     ...
;         for (int t = 0; t < nt; t += 2) {
;             const bool last = (t == nt - 2);
;             const char* a1 = cA + (size_t)(t + 1) * kstep;
;             const char* a2 = last ? nA : cA + (size_t)(t + 2) * kstep; const char* b2 = last ? nB : cB + (size_t)(t + 2) * kstep;
;             const char* a3 = a2 + kstep; const char* b3 = b2 + kstep;
;             if (last && has_next) S.a_ready(nxt);
;             if constexpr (SP2) {
;             PG8_LDB(B0, 0, 0); PG8_LDB(B1, 0, 1); PG8_SCHED; PG8_LDA(At, 0, 0); PG8_STAGE(PG8_SA(1, 1), a1 + hstep, voffA);
;             PG8_WAIT_V(8); PG8_WAIT_L(0); PG8_BAR; PG8_MMA(0, 0, At, B0); PG8_MMA(0, 1, At, B1); PG8_BAR; PG8_SCHED;
;             PG8_LDA(At, 0, 1); PG8_STAGE(PG8_SB(0, 0), b2, voffB); PG8_STAGE(PG8_SB(0, 1), b2 + hstep, voffB); PG8_STAGE(PG8_SA(0, 0), a2, voffA);
;             PG8_WAIT_V(8); PG8_WAIT_L(0); PG8_BAR; PG8_MMA(1, 0, At, B0); PG8_MMA(1, 1, At, B1); PG8_BAR; PG8_SCHED;
.LBB0_3989:
	s_add_i32 s61, s34, 2
	s_add_u32 s62, s30, 0x80
	s_addc_u32 s35, s31, 0
	s_add_i32 s64, 0, 0x10000
	s_cmp_eq_u32 s46, s34
	s_cselect_b32 s35, s1, s35
	s_cselect_b32 s34, s0, s62
	s_cselect_b32 s63, s29, s60
	s_cselect_b32 s62, s28, s59
	s_add_i32 s65, 0, 0x14000
	v_add_u32_e32 v142, s64, v216
	v_add_u32_e32 v158, s65, v216
	ds_read_b128 v[130:133], v142
	ds_read_b128 v[134:137], v142 offset:1024
	ds_read_b128 v[138:141], v142 offset:2048
	ds_read_b128 v[142:145], v142 offset:3072
	ds_read_b128 v[146:149], v158
	ds_read_b128 v[150:153], v158 offset:1024
	ds_read_b128 v[154:157], v158 offset:2048
	ds_read_b128 v[158:161], v158 offset:3072
	v_lshl_add_u64 v[206:207], s[30:31], 0, v[196:197]
	s_add_i32 m0, s38, 0xc000
	ds_read_b128 v[162:165], v218
	ds_read_b128 v[166:169], v218 offset:1024
	ds_read_b128 v[170:173], v218 offset:2048
	ds_read_b128 v[174:177], v218 offset:3072
	ds_read_b128 v[178:181], v218 offset:4096
	ds_read_b128 v[182:185], v218 offset:5120
	ds_read_b128 v[198:201], v218 offset:6144
	ds_read_b128 v[202:205], v218 offset:7168
	global_load_lds_dwordx4 v[206:207], off
	v_lshl_add_u64 v[206:207], s[30:31], 0, v[194:195]
	s_add_i32 m0, s38, 0xe000
	s_nop 0
	global_load_lds_dwordx4 v[206:207], off
	s_waitcnt vmcnt(8)
	s_waitcnt lgkmcnt(0)
	s_barrier
	s_setprio 1
	s_waitcnt lgkmcnt(0)
	v_mfma_f32_16x16x32_bf16 v[126:129], v[130:133], v[162:165], v[126:129]
	v_mfma_f32_16x16x32_bf16 v[122:125], v[138:141], v[162:165], v[122:125]
	v_mfma_f32_16x16x32_bf16 v[110:113], v[130:133], v[170:173], v[110:113]
	v_mfma_f32_16x16x32_bf16 v[106:109], v[138:141], v[170:173], v[106:109]
	v_mfma_f32_16x16x32_bf16 v[94:97], v[130:133], v[178:181], v[94:97]
	v_mfma_f32_16x16x32_bf16 v[90:93], v[138:141], v[178:181], v[90:93]
	v_mfma_f32_16x16x32_bf16 v[78:81], v[130:133], v[198:201], v[78:81]
	v_mfma_f32_16x16x32_bf16 v[74:77], v[138:141], v[198:201], v[74:77]
	v_mfma_f32_16x16x32_bf16 v[126:129], v[134:137], v[166:169], v[126:129]
	v_mfma_f32_16x16x32_bf16 v[122:125], v[142:145], v[166:169], v[122:125]
	v_mfma_f32_16x16x32_bf16 v[110:113], v[134:137], v[174:177], v[110:113]
	v_mfma_f32_16x16x32_bf16 v[106:109], v[142:145], v[174:177], v[106:109]
	v_mfma_f32_16x16x32_bf16 v[94:97], v[134:137], v[182:185], v[94:97]
	v_mfma_f32_16x16x32_bf16 v[90:93], v[142:145], v[182:185], v[90:93]
	v_mfma_f32_16x16x32_bf16 v[78:81], v[134:137], v[202:205], v[78:81]
	v_mfma_f32_16x16x32_bf16 v[74:77], v[142:145], v[202:205], v[74:77]
	v_mfma_f32_16x16x32_bf16 v[118:121], v[146:149], v[162:165], v[118:121]
	v_mfma_f32_16x16x32_bf16 v[114:117], v[154:157], v[162:165], v[114:117]
	v_mfma_f32_16x16x32_bf16 v[102:105], v[146:149], v[170:173], v[102:105]
	v_mfma_f32_16x16x32_bf16 v[98:101], v[154:157], v[170:173], v[98:101]
	v_mfma_f32_16x16x32_bf16 v[86:89], v[146:149], v[178:181], v[86:89]
	v_mfma_f32_16x16x32_bf16 v[82:85], v[154:157], v[178:181], v[82:85]
	v_mfma_f32_16x16x32_bf16 v[70:73], v[146:149], v[198:201], v[70:73]
	v_mfma_f32_16x16x32_bf16 v[66:69], v[154:157], v[198:201], v[66:69]
	v_mfma_f32_16x16x32_bf16 v[118:121], v[150:153], v[166:169], v[118:121]
	v_mfma_f32_16x16x32_bf16 v[114:117], v[158:161], v[166:169], v[114:117]
	v_mfma_f32_16x16x32_bf16 v[102:105], v[150:153], v[174:177], v[102:105]
	v_mfma_f32_16x16x32_bf16 v[98:101], v[158:161], v[174:177], v[98:101]
	v_mfma_f32_16x16x32_bf16 v[86:89], v[150:153], v[182:185], v[86:89]
	v_mfma_f32_16x16x32_bf16 v[82:85], v[158:161], v[182:185], v[82:85]
	v_mfma_f32_16x16x32_bf16 v[70:73], v[150:153], v[202:205], v[70:73]
	v_mfma_f32_16x16x32_bf16 v[66:69], v[158:161], v[202:205], v[66:69]
	s_setprio 0
	s_barrier
	s_add_i32 s64, s64, s37
	v_lshl_add_u64 v[206:207], s[62:63], 0, v[188:189]
	s_mov_b32 m0, s64
	ds_read_b128 v[162:165], v218 offset:16384
	ds_read_b128 v[166:169], v218 offset:17408
	ds_read_b128 v[170:173], v218 offset:18432
	ds_read_b128 v[174:177], v218 offset:19456
	ds_read_b128 v[178:181], v218 offset:20480
	ds_read_b128 v[182:185], v218 offset:21504
	ds_read_b128 v[198:201], v218 offset:22528
	ds_read_b128 v[202:205], v218 offset:23552
	global_load_lds_dwordx4 v[206:207], off
	s_add_i32 m0, s64, 0x2000
	v_lshl_add_u64 v[208:209], s[62:63], 0, v[192:193]
	s_add_u32 s62, s62, s16
	s_addc_u32 s63, s63, s17
	s_add_i32 s64, s65, s37
	global_load_lds_dwordx4 v[208:209], off
	v_lshl_add_u64 v[210:211], s[62:63], 0, v[188:189]
	s_mov_b32 m0, s64
	v_lshl_add_u64 v[212:213], s[62:63], 0, v[192:193]
	global_load_lds_dwordx4 v[210:211], off
	s_add_i32 m0, s64, 0x2000
	v_lshl_add_u64 v[214:215], s[34:35], 0, v[186:187]
	global_load_lds_dwordx4 v[212:213], off
	s_mov_b32 m0, s38
	v_lshl_add_u64 v[228:229], s[34:35], 0, v[190:191]
	global_load_lds_dwordx4 v[214:215], off
	s_mov_b32 m0, s39
	s_nop 0
	global_load_lds_dwordx4 v[228:229], off
	s_waitcnt vmcnt(8)
	s_waitcnt lgkmcnt(0)
	s_barrier
; #define PG8_STAGE(bufoff, gbase, voff) do { _Pragma("unroll") for (int _i = 0; _i < 2; ++_i) \
;         __builtin_amdgcn_global_load_lds((const unsigned*)((const char*)(gbase) + (voff)[_i]), (PG8_LAS unsigned*)(lds + (bufoff) + ldsw + _i * 8192), 16, 0, 0); } while (0)
; #define PG8_LDA(dst, b, h) do { _Pragma("unroll") for (int m = 0; m < 4; ++m) _Pragma("unroll") for (int k = 0; k < 2; ++k) dst[m][k] = *(const PG8_LAS bf16x8*)(lds + PG8_SA(b, h) + aoff + m * 2048 + k * 1024); } while (0)
; #define PG8_LDB(dst, b, h) do { _Pragma("unroll") for (int n = 0; n < 2; ++n) _Pragma("unroll") for (int k = 0; k < 2; ++k) dst[n][k] = *(const PG8_LAS bf16x8*)(lds + PG8_SB(b, h) + boff + n * 2048 + k * 1024); } while (0)
; #define PG8_MMA(ai, bj, At, Bt) do { __builtin_amdgcn_s_setprio(1); _Pragma("unroll") for (int m = 0; m < 4; ++m) _Pragma("unroll") for (int n = 0; n < 2; ++n) _Pragma("unroll") for (int k = 0; k < 2; ++k) \
;         acc[ai][bj][m][n] = __builtin_amdgcn_mfma_f32_16x16x32_bf16(Bt[n][k], At[m][k], acc[ai][bj][m][n], 0, 0, 0); __builtin_amdgcn_s_setprio(0); } while (0)
; #define PG8_WAIT_V(n) asm volatile("s_waitcnt vmcnt(" #n ")" ::: "memory")
; #define PG8_WAIT_L(n) asm volatile("s_waitcnt lgkmcnt(" #n ")" ::: "memory")
; #define PG8_BAR __builtin_amdgcn_s_barrier()
; #define PG8_SCHED __builtin_amdgcn_sched_barrier(0)
; template <class Epi, class Sched, bool ALIGN_EPI = false, bool SP2 = false>
; __device__ __forceinline__ void gemm_phase(PG8_LAS unsigned char* lds, const Gemm g, const Sched& S, const Epi& E) {
;     ...
;             PG8_WAIT_V(8); PG8_WAIT_L(0); PG8_BAR; PG8_MMA(1, 0, At, B0); PG8_MMA(1, 1, At, B1); PG8_BAR; PG8_SCHED;
;             PG8_LDB(B0, 1, 0); PG8_LDB(B1, 1, 1); PG8_SCHED; PG8_LDA(At, 1, 0); PG8_STAGE(PG8_SA(0, 1), a2 + hstep, voffA);
;             PG8_WAIT_V(8); PG8_WAIT_L(0); PG8_BAR; PG8_MMA(0, 0, At, B0); PG8_MMA(0, 1, At, B1); PG8_BAR; PG8_SCHED;
	s_setprio 1
	s_waitcnt lgkmcnt(0)
	v_mfma_f32_16x16x32_bf16 v[62:65], v[130:133], v[162:165], v[62:65]
	v_mfma_f32_16x16x32_bf16 v[58:61], v[138:141], v[162:165], v[58:61]
	v_mfma_f32_16x16x32_bf16 v[46:49], v[130:133], v[170:173], v[46:49]
	v_mfma_f32_16x16x32_bf16 v[42:45], v[138:141], v[170:173], v[42:45]
	v_mfma_f32_16x16x32_bf16 v[30:33], v[130:133], v[178:181], v[30:33]
	v_mfma_f32_16x16x32_bf16 v[26:29], v[138:141], v[178:181], v[26:29]
	v_mfma_f32_16x16x32_bf16 v[14:17], v[130:133], v[198:201], v[14:17]
	v_mfma_f32_16x16x32_bf16 v[10:13], v[138:141], v[198:201], v[10:13]
	v_mfma_f32_16x16x32_bf16 v[62:65], v[134:137], v[166:169], v[62:65]
	v_mfma_f32_16x16x32_bf16 v[58:61], v[142:145], v[166:169], v[58:61]
	v_mfma_f32_16x16x32_bf16 v[46:49], v[134:137], v[174:177], v[46:49]
	v_mfma_f32_16x16x32_bf16 v[42:45], v[142:145], v[174:177], v[42:45]
	v_mfma_f32_16x16x32_bf16 v[30:33], v[134:137], v[182:185], v[30:33]
	v_mfma_f32_16x16x32_bf16 v[26:29], v[142:145], v[182:185], v[26:29]
	v_mfma_f32_16x16x32_bf16 v[14:17], v[134:137], v[202:205], v[14:17]
	v_mfma_f32_16x16x32_bf16 v[10:13], v[142:145], v[202:205], v[10:13]
	v_mfma_f32_16x16x32_bf16 v[54:57], v[146:149], v[162:165], v[54:57]
	v_mfma_f32_16x16x32_bf16 v[50:53], v[154:157], v[162:165], v[50:53]
	v_mfma_f32_16x16x32_bf16 v[38:41], v[146:149], v[170:173], v[38:41]
	v_mfma_f32_16x16x32_bf16 v[34:37], v[154:157], v[170:173], v[34:37]
	v_mfma_f32_16x16x32_bf16 v[22:25], v[146:149], v[178:181], v[22:25]
	v_mfma_f32_16x16x32_bf16 v[18:21], v[154:157], v[178:181], v[18:21]
	v_mfma_f32_16x16x32_bf16 v[6:9], v[146:149], v[198:201], v[6:9]
	v_mfma_f32_16x16x32_bf16 v[2:5], v[154:157], v[198:201], v[2:5]
	v_mfma_f32_16x16x32_bf16 v[54:57], v[150:153], v[166:169], v[54:57]
	v_mfma_f32_16x16x32_bf16 v[50:53], v[158:161], v[166:169], v[50:53]
	v_mfma_f32_16x16x32_bf16 v[38:41], v[150:153], v[174:177], v[38:41]
	v_mfma_f32_16x16x32_bf16 v[34:37], v[158:161], v[174:177], v[34:37]
	v_mfma_f32_16x16x32_bf16 v[22:25], v[150:153], v[182:185], v[22:25]
	v_mfma_f32_16x16x32_bf16 v[18:21], v[158:161], v[182:185], v[18:21]
	v_mfma_f32_16x16x32_bf16 v[6:9], v[150:153], v[202:205], v[6:9]
	v_mfma_f32_16x16x32_bf16 v[2:5], v[158:161], v[202:205], v[2:5]
	s_setprio 0
	s_barrier
	s_add_i32 s62, 0, 0x18000
	s_add_i32 s63, 0, 0x1c000
	v_add_u32_e32 v142, s62, v216
	v_add_u32_e32 v158, s63, v216
	ds_read_b128 v[130:133], v142
	ds_read_b128 v[134:137], v142 offset:1024
	ds_read_b128 v[138:141], v142 offset:2048
	ds_read_b128 v[142:145], v142 offset:3072
	ds_read_b128 v[146:149], v158
	ds_read_b128 v[150:153], v158 offset:1024
	ds_read_b128 v[154:157], v158 offset:2048
	ds_read_b128 v[158:161], v158 offset:3072
	s_add_u32 s34, s34, s16
	s_addc_u32 s35, s35, s17
	s_mov_b32 m0, s40
	v_lshl_add_u64 v[242:243], s[34:35], 0, v[186:187]
	ds_read_b128 v[162:165], v218 offset:32768
	ds_read_b128 v[166:169], v218 offset:33792
	ds_read_b128 v[170:173], v218 offset:34816
	ds_read_b128 v[174:177], v218 offset:35840
	ds_read_b128 v[178:181], v218 offset:36864
	ds_read_b128 v[182:185], v218 offset:37888
	ds_read_b128 v[198:201], v218 offset:38912
	ds_read_b128 v[202:205], v218 offset:39936
	global_load_lds_dwordx4 v[242:243], off
	v_lshl_add_u64 v[242:243], s[34:35], 0, v[190:191]
	s_mov_b32 m0, s41
	s_nop 0
	global_load_lds_dwordx4 v[242:243], off
	s_waitcnt vmcnt(8)
	s_waitcnt lgkmcnt(0)
	s_barrier
	s_setprio 1
	s_waitcnt lgkmcnt(0)
	v_mfma_f32_16x16x32_bf16 v[126:129], v[130:133], v[162:165], v[126:129]
	v_mfma_f32_16x16x32_bf16 v[122:125], v[138:141], v[162:165], v[122:125]
	v_mfma_f32_16x16x32_bf16 v[110:113], v[130:133], v[170:173], v[110:113]
	v_mfma_f32_16x16x32_bf16 v[106:109], v[138:141], v[170:173], v[106:109]
	v_mfma_f32_16x16x32_bf16 v[94:97], v[130:133], v[178:181], v[94:97]
	v_mfma_f32_16x16x32_bf16 v[90:93], v[138:141], v[178:181], v[90:93]
	v_mfma_f32_16x16x32_bf16 v[78:81], v[130:133], v[198:201], v[78:81]
	v_mfma_f32_16x16x32_bf16 v[74:77], v[138:141], v[198:201], v[74:77]
	v_mfma_f32_16x16x32_bf16 v[126:129], v[134:137], v[166:169], v[126:129]
	v_mfma_f32_16x16x32_bf16 v[122:125], v[142:145], v[166:169], v[122:125]
	v_mfma_f32_16x16x32_bf16 v[110:113], v[134:137], v[174:177], v[110:113]
	v_mfma_f32_16x16x32_bf16 v[106:109], v[142:145], v[174:177], v[106:109]
	v_mfma_f32_16x16x32_bf16 v[94:97], v[134:137], v[182:185], v[94:97]
	v_mfma_f32_16x16x32_bf16 v[90:93], v[142:145], v[182:185], v[90:93]
	v_mfma_f32_16x16x32_bf16 v[78:81], v[134:137], v[202:205], v[78:81]
	v_mfma_f32_16x16x32_bf16 v[74:77], v[142:145], v[202:205], v[74:77]
	v_mfma_f32_16x16x32_bf16 v[118:121], v[146:149], v[162:165], v[118:121]
	v_mfma_f32_16x16x32_bf16 v[114:117], v[154:157], v[162:165], v[114:117]
	v_mfma_f32_16x16x32_bf16 v[102:105], v[146:149], v[170:173], v[102:105]
	v_mfma_f32_16x16x32_bf16 v[98:101], v[154:157], v[170:173], v[98:101]
	v_mfma_f32_16x16x32_bf16 v[86:89], v[146:149], v[178:181], v[86:89]
	v_mfma_f32_16x16x32_bf16 v[82:85], v[154:157], v[178:181], v[82:85]
	v_mfma_f32_16x16x32_bf16 v[70:73], v[146:149], v[198:201], v[70:73]
	v_mfma_f32_16x16x32_bf16 v[66:69], v[154:157], v[198:201], v[66:69]
	v_mfma_f32_16x16x32_bf16 v[118:121], v[150:153], v[166:169], v[118:121]
	v_mfma_f32_16x16x32_bf16 v[114:117], v[158:161], v[166:169], v[114:117]
	v_mfma_f32_16x16x32_bf16 v[102:105], v[150:153], v[174:177], v[102:105]
	v_mfma_f32_16x16x32_bf16 v[98:101], v[158:161], v[174:177], v[98:101]
	v_mfma_f32_16x16x32_bf16 v[86:89], v[150:153], v[182:185], v[86:89]
	v_mfma_f32_16x16x32_bf16 v[82:85], v[158:161], v[182:185], v[82:85]
	v_mfma_f32_16x16x32_bf16 v[70:73], v[150:153], v[202:205], v[70:73]
	v_mfma_f32_16x16x32_bf16 v[66:69], v[158:161], v[202:205], v[66:69]
	s_setprio 0
	s_barrier
; #define PG8_STAGE(bufoff, gbase, voff) do { _Pragma("unroll") for (int _i = 0; _i < 2; ++_i) \
;         __builtin_amdgcn_global_load_lds((const unsigned*)((const char*)(gbase) + (voff)[_i]), (PG8_LAS unsigned*)(lds + (bufoff) + ldsw + _i * 8192), 16, 0, 0); } while (0)
; #define PG8_LDA(dst, b, h) do { _Pragma("unroll") for (int m = 0; m < 4; ++m) _Pragma("unroll") for (int k = 0; k < 2; ++k) dst[m][k] = *(const PG8_LAS bf16x8*)(lds + PG8_SA(b, h) + aoff + m * 2048 + k * 1024); } while (0)
; #define PG8_MMA(ai, bj, At, Bt) do { __builtin_amdgcn_s_setprio(1); _Pragma("unroll") for (int m = 0; m < 4; ++m) _Pragma("unroll") for (int n = 0; n < 2; ++n) _Pragma("unroll") for (int k = 0; k < 2; ++k) \
;         acc[ai][bj][m][n] = __builtin_amdgcn_mfma_f32_16x16x32_bf16(Bt[n][k], At[m][k], acc[ai][bj][m][n], 0, 0, 0); __builtin_amdgcn_s_setprio(0); } while (0)
; #define PG8_WAIT_V(n) asm volatile("s_waitcnt vmcnt(" #n ")" ::: "memory")
; #define PG8_WAIT_L(n) asm volatile("s_waitcnt lgkmcnt(" #n ")" ::: "memory")
; #define PG8_BAR __builtin_amdgcn_s_barrier()
; #define PG8_SCHED __builtin_amdgcn_sched_barrier(0)
; template <class Epi, class Sched, bool ALIGN_EPI = false, bool SP2 = false>
; __device__ __forceinline__ void gemm_phase(PG8_LAS unsigned char* lds, const Gemm g, const Sched& S, const Epi& E) {
;     ...
;         for (int t = 0; t < nt; t += 2) {
;             const bool last = (t == nt - 2);
;             const char* a1 = cA + (size_t)(t + 1) * kstep;
;             const char* a2 = last ? nA : cA + (size_t)(t + 2) * kstep; const char* b2 = last ? nB : cB + (size_t)(t + 2) * kstep;
;     ...
;             PG8_LDA(At, 1, 1); PG8_STAGE(PG8_SB(1, 0), b3, voffB); PG8_STAGE(PG8_SB(1, 1), b3 + hstep, voffB); PG8_STAGE(PG8_SA(1, 0), a3, voffA);
;             PG8_WAIT_V(8); PG8_WAIT_L(0); PG8_BAR; PG8_MMA(1, 0, At, B0); PG8_MMA(1, 1, At, B1); PG8_BAR; PG8_SCHED;
	s_add_i32 s34, s62, s37
	v_lshl_add_u64 v[206:207], v[206:207], 0, s[92:93]
	s_mov_b32 m0, s34
	ds_read_b128 v[162:165], v218 offset:49152
	ds_read_b128 v[166:169], v218 offset:50176
	ds_read_b128 v[170:173], v218 offset:51200
	ds_read_b128 v[174:177], v218 offset:52224
	ds_read_b128 v[178:181], v218 offset:53248
	ds_read_b128 v[182:185], v218 offset:54272
	ds_read_b128 v[198:201], v218 offset:55296
	ds_read_b128 v[202:205], v218 offset:56320
	global_load_lds_dwordx4 v[206:207], off
	v_lshl_add_u64 v[206:207], v[208:209], 0, s[92:93]
	s_add_i32 m0, s34, 0x2000
	s_add_i32 s34, s63, s37
	global_load_lds_dwordx4 v[206:207], off
	v_lshl_add_u64 v[206:207], v[210:211], 0, s[92:93]
	s_mov_b32 m0, s34
	s_nop 0
	global_load_lds_dwordx4 v[206:207], off
	v_lshl_add_u64 v[206:207], v[212:213], 0, s[92:93]
	s_add_i32 m0, s34, 0x2000
	s_nop 0
	global_load_lds_dwordx4 v[206:207], off
	v_lshl_add_u64 v[206:207], v[214:215], 0, s[92:93]
	s_mov_b32 m0, s42
	s_nop 0
	global_load_lds_dwordx4 v[206:207], off
	v_lshl_add_u64 v[206:207], v[228:229], 0, s[92:93]
	s_mov_b32 m0, s43
	s_nop 0
	global_load_lds_dwordx4 v[206:207], off
	s_waitcnt vmcnt(8)
	s_waitcnt lgkmcnt(0)
	s_barrier
	s_setprio 1
	s_waitcnt lgkmcnt(0)
	v_mfma_f32_16x16x32_bf16 v[62:65], v[130:133], v[162:165], v[62:65]
	v_mfma_f32_16x16x32_bf16 v[58:61], v[138:141], v[162:165], v[58:61]
	v_mfma_f32_16x16x32_bf16 v[46:49], v[130:133], v[170:173], v[46:49]
	v_mfma_f32_16x16x32_bf16 v[42:45], v[138:141], v[170:173], v[42:45]
	v_mfma_f32_16x16x32_bf16 v[30:33], v[130:133], v[178:181], v[30:33]
	v_mfma_f32_16x16x32_bf16 v[26:29], v[138:141], v[178:181], v[26:29]
	v_mfma_f32_16x16x32_bf16 v[14:17], v[130:133], v[198:201], v[14:17]
	v_mfma_f32_16x16x32_bf16 v[10:13], v[138:141], v[198:201], v[10:13]
	v_mfma_f32_16x16x32_bf16 v[62:65], v[134:137], v[166:169], v[62:65]
	v_mfma_f32_16x16x32_bf16 v[58:61], v[142:145], v[166:169], v[58:61]
	v_mfma_f32_16x16x32_bf16 v[46:49], v[134:137], v[174:177], v[46:49]
	v_mfma_f32_16x16x32_bf16 v[42:45], v[142:145], v[174:177], v[42:45]
	v_mfma_f32_16x16x32_bf16 v[30:33], v[134:137], v[182:185], v[30:33]
	v_mfma_f32_16x16x32_bf16 v[26:29], v[142:145], v[182:185], v[26:29]
	v_mfma_f32_16x16x32_bf16 v[14:17], v[134:137], v[202:205], v[14:17]
	v_mfma_f32_16x16x32_bf16 v[10:13], v[142:145], v[202:205], v[10:13]
	v_mfma_f32_16x16x32_bf16 v[54:57], v[146:149], v[162:165], v[54:57]
	v_mfma_f32_16x16x32_bf16 v[50:53], v[154:157], v[162:165], v[50:53]
	v_mfma_f32_16x16x32_bf16 v[38:41], v[146:149], v[170:173], v[38:41]
	v_mfma_f32_16x16x32_bf16 v[34:37], v[154:157], v[170:173], v[34:37]
	v_mfma_f32_16x16x32_bf16 v[22:25], v[146:149], v[178:181], v[22:25]
	v_mfma_f32_16x16x32_bf16 v[18:21], v[154:157], v[178:181], v[18:21]
	v_mfma_f32_16x16x32_bf16 v[6:9], v[146:149], v[198:201], v[6:9]
	v_mfma_f32_16x16x32_bf16 v[2:5], v[154:157], v[198:201], v[2:5]
	v_mfma_f32_16x16x32_bf16 v[54:57], v[150:153], v[166:169], v[54:57]
	v_mfma_f32_16x16x32_bf16 v[50:53], v[158:161], v[166:169], v[50:53]
	v_mfma_f32_16x16x32_bf16 v[38:41], v[150:153], v[174:177], v[38:41]
	v_mfma_f32_16x16x32_bf16 v[34:37], v[158:161], v[174:177], v[34:37]
	v_mfma_f32_16x16x32_bf16 v[22:25], v[150:153], v[182:185], v[22:25]
	v_mfma_f32_16x16x32_bf16 v[18:21], v[158:161], v[182:185], v[18:21]
	v_mfma_f32_16x16x32_bf16 v[6:9], v[150:153], v[202:205], v[6:9]
	v_mfma_f32_16x16x32_bf16 v[2:5], v[158:161], v[202:205], v[2:5]
	s_setprio 0
	s_barrier
	s_add_u32 s59, s59, 0x100
	s_addc_u32 s60, s60, 0
	s_add_u32 s30, s30, 0x100
	s_addc_u32 s31, s31, 0
	s_cmp_ge_i32 s61, s45
	s_mov_b32 s34, s61
	s_cbranch_scc0 .LBB0_3989

; #define PG8_STAGE(bufoff, gbase, voff) do { _Pragma("unroll") for (int _i = 0; _i < 2; ++_i) \
;         __builtin_amdgcn_global_load_lds((const unsigned*)((const char*)(gbase) + (voff)[_i]), (PG8_LAS unsigned*)(lds + (bufoff) + ldsw + _i * 8192), 16, 0, 0); } while (0)
; #define PG8_LDA(dst, b, h) do { _Pragma("unroll") for (int m = 0; m < 4; ++m) _Pragma("unroll") for (int k = 0; k < 2; ++k) dst[m][k] = *(const PG8_LAS bf16x8*)(lds + PG8_SA(b, h) + aoff + m * 2048 + k * 1024); } while (0)
; #define PG8_LDB(dst, b, h) do { _Pragma("unroll") for (int n = 0; n < 2; ++n) _Pragma("unroll") for (int k = 0; k < 2; ++k) dst[n][k] = *(const PG8_LAS bf16x8*)(lds + PG8_SB(b, h) + boff + n * 2048 + k * 1024); } while (0)
; #define PG8_MMA(ai, bj, At, Bt) do { __builtin_amdgcn_s_setprio(1); _Pragma("unroll") for (int m = 0; m < 4; ++m) _Pragma("unroll") for (int n = 0; n < 2; ++n) _Pragma("unroll") for (int k = 0; k < 2; ++k) \
;         acc[ai][bj][m][n] = __builtin_amdgcn_mfma_f32_16x16x32_bf16(Bt[n][k], At[m][k], acc[ai][bj][m][n], 0, 0, 0); __builtin_amdgcn_s_setprio(0); } while (0)
; #define PG8_WAIT_V(n) asm volatile("s_waitcnt vmcnt(" #n ")" ::: "memory")
; #define PG8_BAR __builtin_amdgcn_s_barrier()
; template <class Epi, class Sched, bool ALIGN_EPI = false, bool SP2 = false>
; __device__ __forceinline__ void gemm_phase(PG8_LAS unsigned char* lds, const Gemm g, const Sched& S, const Epi& E) {
;     ...
;         for (int t = 0; t < nt; t += 2) {
;             const bool last = (t == nt - 2);
;             const char* a1 = cA + (size_t)(t + 1) * kstep;
;             const char* a2 = last ? nA : cA + (size_t)(t + 2) * kstep; const char* b2 = last ? nB : cB + (size_t)(t + 2) * kstep;
;             const char* a3 = a2 + kstep; const char* b3 = b2 + kstep;
;             if (last && has_next) S.a_ready(nxt);
;             if constexpr (SP2) {
;             PG8_LDB(B0, 0, 0); PG8_LDB(B1, 0, 1); PG8_SCHED; PG8_LDA(At, 0, 0); PG8_STAGE(PG8_SA(1, 1), a1 + hstep, voffA);
;             PG8_WAIT_V(8); PG8_WAIT_L(0); PG8_BAR; PG8_MMA(0, 0, At, B0); PG8_MMA(0, 1, At, B1); PG8_BAR; PG8_SCHED;
;             PG8_LDA(At, 0, 1); PG8_STAGE(PG8_SB(0, 0), b2, voffB); PG8_STAGE(PG8_SB(0, 1), b2 + hstep, voffB); PG8_STAGE(PG8_SA(0, 0), a2, voffA);
;             PG8_WAIT_V(8); PG8_WAIT_L(0); PG8_BAR; PG8_MMA(1, 0, At, B0); PG8_MMA(1, 1, At, B1); PG8_BAR; PG8_SCHED;
.LBB0_4164:
	s_add_i32 s57, s28, 2
	s_add_u32 s58, s26, 0x80
	s_addc_u32 s29, s27, 0
	s_add_i32 s60, 0, 0x10000
	s_cmp_eq_u32 s51, s28
	s_cselect_b32 s29, s1, s29
	s_cselect_b32 s28, s0, s58
	v_add_u32_e32 v145, s60, v142
	s_cselect_b32 s59, s25, s56
	s_cselect_b32 s58, s24, s55
	s_add_i32 s61, 0, 0x14000
	ds_read_b128 v[146:149], v145
	ds_read_b128 v[150:153], v145 offset:1024
	ds_read_b128 v[154:157], v145 offset:2048
	ds_read_b128 v[158:161], v145 offset:3072
	v_add_u32_e32 v145, s61, v142
	ds_read_b128 v[162:165], v145
	ds_read_b128 v[166:169], v145 offset:1024
	ds_read_b128 v[170:173], v145 offset:2048
	ds_read_b128 v[174:177], v145 offset:3072
	v_lshl_add_u64 v[210:211], s[26:27], 0, v[140:141]
	s_add_i32 m0, s42, 0xc000
	ds_read_b128 v[178:181], v144
	ds_read_b128 v[182:185], v144 offset:1024
	ds_read_b128 v[186:189], v144 offset:2048
	ds_read_b128 v[190:193], v144 offset:3072
	ds_read_b128 v[194:197], v144 offset:4096
	ds_read_b128 v[198:201], v144 offset:5120
	ds_read_b128 v[202:205], v144 offset:6144
	ds_read_b128 v[206:209], v144 offset:7168
	global_load_lds_dwordx4 v[210:211], off
	v_lshl_add_u64 v[210:211], s[26:27], 0, v[138:139]
	s_add_i32 m0, s42, 0xe000
	s_nop 0
	global_load_lds_dwordx4 v[210:211], off
	s_waitcnt vmcnt(8)
	s_waitcnt lgkmcnt(0)
	s_barrier
	s_setprio 1
	s_waitcnt lgkmcnt(0)
	v_mfma_f32_16x16x32_bf16 v[122:125], v[146:149], v[178:181], v[122:125]
	v_mfma_f32_16x16x32_bf16 v[126:129], v[154:157], v[178:181], v[126:129]
	v_mfma_f32_16x16x32_bf16 v[110:113], v[146:149], v[186:189], v[110:113]
	v_mfma_f32_16x16x32_bf16 v[106:109], v[154:157], v[186:189], v[106:109]
	v_mfma_f32_16x16x32_bf16 v[94:97], v[146:149], v[194:197], v[94:97]
	v_mfma_f32_16x16x32_bf16 v[90:93], v[154:157], v[194:197], v[90:93]
	v_mfma_f32_16x16x32_bf16 v[78:81], v[146:149], v[202:205], v[78:81]
	v_mfma_f32_16x16x32_bf16 v[74:77], v[154:157], v[202:205], v[74:77]
	v_mfma_f32_16x16x32_bf16 v[122:125], v[150:153], v[182:185], v[122:125]
	v_mfma_f32_16x16x32_bf16 v[126:129], v[158:161], v[182:185], v[126:129]
	v_mfma_f32_16x16x32_bf16 v[110:113], v[150:153], v[190:193], v[110:113]
	v_mfma_f32_16x16x32_bf16 v[106:109], v[158:161], v[190:193], v[106:109]
	v_mfma_f32_16x16x32_bf16 v[94:97], v[150:153], v[198:201], v[94:97]
	v_mfma_f32_16x16x32_bf16 v[90:93], v[158:161], v[198:201], v[90:93]
	v_mfma_f32_16x16x32_bf16 v[78:81], v[150:153], v[206:209], v[78:81]
	v_mfma_f32_16x16x32_bf16 v[74:77], v[158:161], v[206:209], v[74:77]
	v_mfma_f32_16x16x32_bf16 v[118:121], v[162:165], v[178:181], v[118:121]
	v_mfma_f32_16x16x32_bf16 v[114:117], v[170:173], v[178:181], v[114:117]
	v_mfma_f32_16x16x32_bf16 v[102:105], v[162:165], v[186:189], v[102:105]
	v_mfma_f32_16x16x32_bf16 v[98:101], v[170:173], v[186:189], v[98:101]
	v_mfma_f32_16x16x32_bf16 v[86:89], v[162:165], v[194:197], v[86:89]
	v_mfma_f32_16x16x32_bf16 v[82:85], v[170:173], v[194:197], v[82:85]
	v_mfma_f32_16x16x32_bf16 v[70:73], v[162:165], v[202:205], v[70:73]
	v_mfma_f32_16x16x32_bf16 v[66:69], v[170:173], v[202:205], v[66:69]
	v_mfma_f32_16x16x32_bf16 v[118:121], v[166:169], v[182:185], v[118:121]
	v_mfma_f32_16x16x32_bf16 v[114:117], v[174:177], v[182:185], v[114:117]
	v_mfma_f32_16x16x32_bf16 v[102:105], v[166:169], v[190:193], v[102:105]
	v_mfma_f32_16x16x32_bf16 v[98:101], v[174:177], v[190:193], v[98:101]
	v_mfma_f32_16x16x32_bf16 v[86:89], v[166:169], v[198:201], v[86:89]
	v_mfma_f32_16x16x32_bf16 v[82:85], v[174:177], v[198:201], v[82:85]
	v_mfma_f32_16x16x32_bf16 v[70:73], v[166:169], v[206:209], v[70:73]
	v_mfma_f32_16x16x32_bf16 v[66:69], v[174:177], v[206:209], v[66:69]
	s_setprio 0
	s_barrier
	s_add_i32 s60, s60, s37
	v_lshl_add_u64 v[210:211], s[58:59], 0, v[132:133]
	s_mov_b32 m0, s60
	ds_read_b128 v[178:181], v144 offset:16384
	ds_read_b128 v[182:185], v144 offset:17408
	ds_read_b128 v[186:189], v144 offset:18432
	ds_read_b128 v[190:193], v144 offset:19456
	ds_read_b128 v[194:197], v144 offset:20480
	ds_read_b128 v[198:201], v144 offset:21504
	ds_read_b128 v[202:205], v144 offset:22528
	ds_read_b128 v[206:209], v144 offset:23552
	global_load_lds_dwordx4 v[210:211], off
	s_add_i32 m0, s60, 0x2000
	v_lshl_add_u64 v[212:213], s[58:59], 0, v[136:137]
	s_add_u32 s58, s58, s12
	s_addc_u32 s59, s59, s13
	s_add_i32 s60, s61, s37
	global_load_lds_dwordx4 v[212:213], off
	v_lshl_add_u64 v[214:215], s[58:59], 0, v[132:133]
	s_mov_b32 m0, s60
	v_lshl_add_u64 v[216:217], s[58:59], 0, v[136:137]
	global_load_lds_dwordx4 v[214:215], off
	s_add_i32 m0, s60, 0x2000
	v_lshl_add_u64 v[218:219], s[28:29], 0, v[130:131]
	global_load_lds_dwordx4 v[216:217], off
	s_mov_b32 m0, s42
	v_lshl_add_u64 v[228:229], s[28:29], 0, v[134:135]
	global_load_lds_dwordx4 v[218:219], off
	s_mov_b32 m0, s43
	s_nop 0
	global_load_lds_dwordx4 v[228:229], off
	s_waitcnt vmcnt(8)
	s_waitcnt lgkmcnt(0)
	s_barrier
; #define PG8_STAGE(bufoff, gbase, voff) do { _Pragma("unroll") for (int _i = 0; _i < 2; ++_i) \
;         __builtin_amdgcn_global_load_lds((const unsigned*)((const char*)(gbase) + (voff)[_i]), (PG8_LAS unsigned*)(lds + (bufoff) + ldsw + _i * 8192), 16, 0, 0); } while (0)
; #define PG8_LDA(dst, b, h) do { _Pragma("unroll") for (int m = 0; m < 4; ++m) _Pragma("unroll") for (int k = 0; k < 2; ++k) dst[m][k] = *(const PG8_LAS bf16x8*)(lds + PG8_SA(b, h) + aoff + m * 2048 + k * 1024); } while (0)
; #define PG8_LDB(dst, b, h) do { _Pragma("unroll") for (int n = 0; n < 2; ++n) _Pragma("unroll") for (int k = 0; k < 2; ++k) dst[n][k] = *(const PG8_LAS bf16x8*)(lds + PG8_SB(b, h) + boff + n * 2048 + k * 1024); } while (0)
; #define PG8_MMA(ai, bj, At, Bt) do { __builtin_amdgcn_s_setprio(1); _Pragma("unroll") for (int m = 0; m < 4; ++m) _Pragma("unroll") for (int n = 0; n < 2; ++n) _Pragma("unroll") for (int k = 0; k < 2; ++k) \
;         acc[ai][bj][m][n] = __builtin_amdgcn_mfma_f32_16x16x32_bf16(Bt[n][k], At[m][k], acc[ai][bj][m][n], 0, 0, 0); __builtin_amdgcn_s_setprio(0); } while (0)
; #define PG8_WAIT_V(n) asm volatile("s_waitcnt vmcnt(" #n ")" ::: "memory")
; #define PG8_WAIT_L(n) asm volatile("s_waitcnt lgkmcnt(" #n ")" ::: "memory")
; #define PG8_BAR __builtin_amdgcn_s_barrier()
; #define PG8_SCHED __builtin_amdgcn_sched_barrier(0)
; template <class Epi, class Sched, bool ALIGN_EPI = false, bool SP2 = false>
; __device__ __forceinline__ void gemm_phase(PG8_LAS unsigned char* lds, const Gemm g, const Sched& S, const Epi& E) {
;     ...
;             PG8_WAIT_V(8); PG8_WAIT_L(0); PG8_BAR; PG8_MMA(1, 0, At, B0); PG8_MMA(1, 1, At, B1); PG8_BAR; PG8_SCHED;
;             PG8_LDB(B0, 1, 0); PG8_LDB(B1, 1, 1); PG8_SCHED; PG8_LDA(At, 1, 0); PG8_STAGE(PG8_SA(0, 1), a2 + hstep, voffA);
;             PG8_WAIT_V(8); PG8_WAIT_L(0); PG8_BAR; PG8_MMA(0, 0, At, B0); PG8_MMA(0, 1, At, B1); PG8_BAR; PG8_SCHED;
	s_setprio 1
	s_waitcnt lgkmcnt(0)
	v_mfma_f32_16x16x32_bf16 v[62:65], v[146:149], v[178:181], v[62:65]
	v_mfma_f32_16x16x32_bf16 v[58:61], v[154:157], v[178:181], v[58:61]
	v_mfma_f32_16x16x32_bf16 v[46:49], v[146:149], v[186:189], v[46:49]
	v_mfma_f32_16x16x32_bf16 v[42:45], v[154:157], v[186:189], v[42:45]
	v_mfma_f32_16x16x32_bf16 v[30:33], v[146:149], v[194:197], v[30:33]
	v_mfma_f32_16x16x32_bf16 v[26:29], v[154:157], v[194:197], v[26:29]
	v_mfma_f32_16x16x32_bf16 v[14:17], v[146:149], v[202:205], v[14:17]
	v_mfma_f32_16x16x32_bf16 v[10:13], v[154:157], v[202:205], v[10:13]
	v_mfma_f32_16x16x32_bf16 v[62:65], v[150:153], v[182:185], v[62:65]
	v_mfma_f32_16x16x32_bf16 v[58:61], v[158:161], v[182:185], v[58:61]
	v_mfma_f32_16x16x32_bf16 v[46:49], v[150:153], v[190:193], v[46:49]
	v_mfma_f32_16x16x32_bf16 v[42:45], v[158:161], v[190:193], v[42:45]
	v_mfma_f32_16x16x32_bf16 v[30:33], v[150:153], v[198:201], v[30:33]
	v_mfma_f32_16x16x32_bf16 v[26:29], v[158:161], v[198:201], v[26:29]
	v_mfma_f32_16x16x32_bf16 v[14:17], v[150:153], v[206:209], v[14:17]
	v_mfma_f32_16x16x32_bf16 v[10:13], v[158:161], v[206:209], v[10:13]
	v_mfma_f32_16x16x32_bf16 v[54:57], v[162:165], v[178:181], v[54:57]
	v_mfma_f32_16x16x32_bf16 v[50:53], v[170:173], v[178:181], v[50:53]
	v_mfma_f32_16x16x32_bf16 v[38:41], v[162:165], v[186:189], v[38:41]
	v_mfma_f32_16x16x32_bf16 v[34:37], v[170:173], v[186:189], v[34:37]
	v_mfma_f32_16x16x32_bf16 v[22:25], v[162:165], v[194:197], v[22:25]
	v_mfma_f32_16x16x32_bf16 v[18:21], v[170:173], v[194:197], v[18:21]
	v_mfma_f32_16x16x32_bf16 v[6:9], v[162:165], v[202:205], v[6:9]
	v_mfma_f32_16x16x32_bf16 v[2:5], v[170:173], v[202:205], v[2:5]
	v_mfma_f32_16x16x32_bf16 v[54:57], v[166:169], v[182:185], v[54:57]
	v_mfma_f32_16x16x32_bf16 v[50:53], v[174:177], v[182:185], v[50:53]
	v_mfma_f32_16x16x32_bf16 v[38:41], v[166:169], v[190:193], v[38:41]
	v_mfma_f32_16x16x32_bf16 v[34:37], v[174:177], v[190:193], v[34:37]
	v_mfma_f32_16x16x32_bf16 v[22:25], v[166:169], v[198:201], v[22:25]
	v_mfma_f32_16x16x32_bf16 v[18:21], v[174:177], v[198:201], v[18:21]
	v_mfma_f32_16x16x32_bf16 v[6:9], v[166:169], v[206:209], v[6:9]
	v_mfma_f32_16x16x32_bf16 v[2:5], v[174:177], v[206:209], v[2:5]
	s_setprio 0
	s_barrier
	s_add_i32 s58, 0, 0x18000
	v_add_u32_e32 v145, s58, v142
	s_add_i32 s59, 0, 0x1c000
	ds_read_b128 v[146:149], v145
	ds_read_b128 v[150:153], v145 offset:1024
	ds_read_b128 v[154:157], v145 offset:2048
	ds_read_b128 v[158:161], v145 offset:3072
	v_add_u32_e32 v145, s59, v142
	ds_read_b128 v[162:165], v145
	ds_read_b128 v[166:169], v145 offset:1024
	ds_read_b128 v[170:173], v145 offset:2048
	ds_read_b128 v[174:177], v145 offset:3072
	s_add_u32 s28, s28, s12
	s_addc_u32 s29, s29, s13
	s_mov_b32 m0, s44
	v_lshl_add_u64 v[242:243], s[28:29], 0, v[130:131]
	ds_read_b128 v[178:181], v144 offset:32768
	ds_read_b128 v[182:185], v144 offset:33792
	ds_read_b128 v[186:189], v144 offset:34816
	ds_read_b128 v[190:193], v144 offset:35840
	ds_read_b128 v[194:197], v144 offset:36864
	ds_read_b128 v[198:201], v144 offset:37888
	ds_read_b128 v[202:205], v144 offset:38912
	ds_read_b128 v[206:209], v144 offset:39936
	global_load_lds_dwordx4 v[242:243], off
	v_lshl_add_u64 v[242:243], s[28:29], 0, v[134:135]
	s_mov_b32 m0, s45
	s_nop 0
	global_load_lds_dwordx4 v[242:243], off
	s_waitcnt vmcnt(8)
	s_waitcnt lgkmcnt(0)
	s_barrier
	s_setprio 1
	s_waitcnt lgkmcnt(0)
	v_mfma_f32_16x16x32_bf16 v[122:125], v[146:149], v[178:181], v[122:125]
	v_mfma_f32_16x16x32_bf16 v[126:129], v[154:157], v[178:181], v[126:129]
	v_mfma_f32_16x16x32_bf16 v[110:113], v[146:149], v[186:189], v[110:113]
	v_mfma_f32_16x16x32_bf16 v[106:109], v[154:157], v[186:189], v[106:109]
	v_mfma_f32_16x16x32_bf16 v[94:97], v[146:149], v[194:197], v[94:97]
	v_mfma_f32_16x16x32_bf16 v[90:93], v[154:157], v[194:197], v[90:93]
	v_mfma_f32_16x16x32_bf16 v[78:81], v[146:149], v[202:205], v[78:81]
	v_mfma_f32_16x16x32_bf16 v[74:77], v[154:157], v[202:205], v[74:77]
	v_mfma_f32_16x16x32_bf16 v[122:125], v[150:153], v[182:185], v[122:125]
	v_mfma_f32_16x16x32_bf16 v[126:129], v[158:161], v[182:185], v[126:129]
	v_mfma_f32_16x16x32_bf16 v[110:113], v[150:153], v[190:193], v[110:113]
	v_mfma_f32_16x16x32_bf16 v[106:109], v[158:161], v[190:193], v[106:109]
	v_mfma_f32_16x16x32_bf16 v[94:97], v[150:153], v[198:201], v[94:97]
	v_mfma_f32_16x16x32_bf16 v[90:93], v[158:161], v[198:201], v[90:93]
	v_mfma_f32_16x16x32_bf16 v[78:81], v[150:153], v[206:209], v[78:81]
	v_mfma_f32_16x16x32_bf16 v[74:77], v[158:161], v[206:209], v[74:77]
	v_mfma_f32_16x16x32_bf16 v[118:121], v[162:165], v[178:181], v[118:121]
	v_mfma_f32_16x16x32_bf16 v[114:117], v[170:173], v[178:181], v[114:117]
	v_mfma_f32_16x16x32_bf16 v[102:105], v[162:165], v[186:189], v[102:105]
	v_mfma_f32_16x16x32_bf16 v[98:101], v[170:173], v[186:189], v[98:101]
	v_mfma_f32_16x16x32_bf16 v[86:89], v[162:165], v[194:197], v[86:89]
	v_mfma_f32_16x16x32_bf16 v[82:85], v[170:173], v[194:197], v[82:85]
	v_mfma_f32_16x16x32_bf16 v[70:73], v[162:165], v[202:205], v[70:73]
	v_mfma_f32_16x16x32_bf16 v[66:69], v[170:173], v[202:205], v[66:69]
	v_mfma_f32_16x16x32_bf16 v[118:121], v[166:169], v[182:185], v[118:121]
	v_mfma_f32_16x16x32_bf16 v[114:117], v[174:177], v[182:185], v[114:117]
	v_mfma_f32_16x16x32_bf16 v[102:105], v[166:169], v[190:193], v[102:105]
	v_mfma_f32_16x16x32_bf16 v[98:101], v[174:177], v[190:193], v[98:101]
	v_mfma_f32_16x16x32_bf16 v[86:89], v[166:169], v[198:201], v[86:89]
	v_mfma_f32_16x16x32_bf16 v[82:85], v[174:177], v[198:201], v[82:85]
	v_mfma_f32_16x16x32_bf16 v[70:73], v[166:169], v[206:209], v[70:73]
	v_mfma_f32_16x16x32_bf16 v[66:69], v[174:177], v[206:209], v[66:69]
	s_setprio 0
	s_barrier
; #define PG8_STAGE(bufoff, gbase, voff) do { _Pragma("unroll") for (int _i = 0; _i < 2; ++_i) \
;         __builtin_amdgcn_global_load_lds((const unsigned*)((const char*)(gbase) + (voff)[_i]), (PG8_LAS unsigned*)(lds + (bufoff) + ldsw + _i * 8192), 16, 0, 0); } while (0)
; #define PG8_LDA(dst, b, h) do { _Pragma("unroll") for (int m = 0; m < 4; ++m) _Pragma("unroll") for (int k = 0; k < 2; ++k) dst[m][k] = *(const PG8_LAS bf16x8*)(lds + PG8_SA(b, h) + aoff + m * 2048 + k * 1024); } while (0)
; #define PG8_MMA(ai, bj, At, Bt) do { __builtin_amdgcn_s_setprio(1); _Pragma("unroll") for (int m = 0; m < 4; ++m) _Pragma("unroll") for (int n = 0; n < 2; ++n) _Pragma("unroll") for (int k = 0; k < 2; ++k) \
;         acc[ai][bj][m][n] = __builtin_amdgcn_mfma_f32_16x16x32_bf16(Bt[n][k], At[m][k], acc[ai][bj][m][n], 0, 0, 0); __builtin_amdgcn_s_setprio(0); } while (0)
; #define PG8_WAIT_V(n) asm volatile("s_waitcnt vmcnt(" #n ")" ::: "memory")
; #define PG8_WAIT_L(n) asm volatile("s_waitcnt lgkmcnt(" #n ")" ::: "memory")
; #define PG8_BAR __builtin_amdgcn_s_barrier()
; #define PG8_SCHED __builtin_amdgcn_sched_barrier(0)
; template <class Epi, class Sched, bool ALIGN_EPI = false, bool SP2 = false>
; __device__ __forceinline__ void gemm_phase(PG8_LAS unsigned char* lds, const Gemm g, const Sched& S, const Epi& E) {
;     ...
;         for (int t = 0; t < nt; t += 2) {
;             const bool last = (t == nt - 2);
;             const char* a1 = cA + (size_t)(t + 1) * kstep;
;             const char* a2 = last ? nA : cA + (size_t)(t + 2) * kstep; const char* b2 = last ? nB : cB + (size_t)(t + 2) * kstep;
;     ...
;             PG8_LDA(At, 1, 1); PG8_STAGE(PG8_SB(1, 0), b3, voffB); PG8_STAGE(PG8_SB(1, 1), b3 + hstep, voffB); PG8_STAGE(PG8_SA(1, 0), a3, voffA);
;             PG8_WAIT_V(8); PG8_WAIT_L(0); PG8_BAR; PG8_MMA(1, 0, At, B0); PG8_MMA(1, 1, At, B1); PG8_BAR; PG8_SCHED;
	s_add_i32 s28, s58, s37
	v_lshl_add_u64 v[210:211], v[210:211], 0, s[92:93]
	s_mov_b32 m0, s28
	ds_read_b128 v[178:181], v144 offset:49152
	ds_read_b128 v[182:185], v144 offset:50176
	ds_read_b128 v[186:189], v144 offset:51200
	ds_read_b128 v[190:193], v144 offset:52224
	ds_read_b128 v[194:197], v144 offset:53248
	ds_read_b128 v[198:201], v144 offset:54272
	ds_read_b128 v[202:205], v144 offset:55296
	ds_read_b128 v[206:209], v144 offset:56320
	global_load_lds_dwordx4 v[210:211], off
	v_lshl_add_u64 v[210:211], v[212:213], 0, s[92:93]
	s_add_i32 m0, s28, 0x2000
	s_add_i32 s28, s59, s37
	global_load_lds_dwordx4 v[210:211], off
	v_lshl_add_u64 v[210:211], v[214:215], 0, s[92:93]
	s_mov_b32 m0, s28
	s_nop 0
	global_load_lds_dwordx4 v[210:211], off
	v_lshl_add_u64 v[210:211], v[216:217], 0, s[92:93]
	s_add_i32 m0, s28, 0x2000
	s_nop 0
	global_load_lds_dwordx4 v[210:211], off
	v_lshl_add_u64 v[210:211], v[218:219], 0, s[92:93]
	s_mov_b32 m0, s46
	s_nop 0
	global_load_lds_dwordx4 v[210:211], off
	v_lshl_add_u64 v[210:211], v[228:229], 0, s[92:93]
	s_mov_b32 m0, s48
	s_nop 0
	global_load_lds_dwordx4 v[210:211], off
	s_waitcnt vmcnt(8)
	s_waitcnt lgkmcnt(0)
	s_barrier
	s_setprio 1
	s_waitcnt lgkmcnt(0)
	v_mfma_f32_16x16x32_bf16 v[62:65], v[146:149], v[178:181], v[62:65]
	v_mfma_f32_16x16x32_bf16 v[58:61], v[154:157], v[178:181], v[58:61]
	v_mfma_f32_16x16x32_bf16 v[46:49], v[146:149], v[186:189], v[46:49]
	v_mfma_f32_16x16x32_bf16 v[42:45], v[154:157], v[186:189], v[42:45]
	v_mfma_f32_16x16x32_bf16 v[30:33], v[146:149], v[194:197], v[30:33]
	v_mfma_f32_16x16x32_bf16 v[26:29], v[154:157], v[194:197], v[26:29]
	v_mfma_f32_16x16x32_bf16 v[14:17], v[146:149], v[202:205], v[14:17]
	v_mfma_f32_16x16x32_bf16 v[10:13], v[154:157], v[202:205], v[10:13]
	v_mfma_f32_16x16x32_bf16 v[62:65], v[150:153], v[182:185], v[62:65]
	v_mfma_f32_16x16x32_bf16 v[58:61], v[158:161], v[182:185], v[58:61]
	v_mfma_f32_16x16x32_bf16 v[46:49], v[150:153], v[190:193], v[46:49]
	v_mfma_f32_16x16x32_bf16 v[42:45], v[158:161], v[190:193], v[42:45]
	v_mfma_f32_16x16x32_bf16 v[30:33], v[150:153], v[198:201], v[30:33]
	v_mfma_f32_16x16x32_bf16 v[26:29], v[158:161], v[198:201], v[26:29]
	v_mfma_f32_16x16x32_bf16 v[14:17], v[150:153], v[206:209], v[14:17]
	v_mfma_f32_16x16x32_bf16 v[10:13], v[158:161], v[206:209], v[10:13]
	v_mfma_f32_16x16x32_bf16 v[54:57], v[162:165], v[178:181], v[54:57]
	v_mfma_f32_16x16x32_bf16 v[50:53], v[170:173], v[178:181], v[50:53]
	v_mfma_f32_16x16x32_bf16 v[38:41], v[162:165], v[186:189], v[38:41]
	v_mfma_f32_16x16x32_bf16 v[34:37], v[170:173], v[186:189], v[34:37]
	v_mfma_f32_16x16x32_bf16 v[22:25], v[162:165], v[194:197], v[22:25]
	v_mfma_f32_16x16x32_bf16 v[18:21], v[170:173], v[194:197], v[18:21]
	v_mfma_f32_16x16x32_bf16 v[6:9], v[162:165], v[202:205], v[6:9]
	v_mfma_f32_16x16x32_bf16 v[2:5], v[170:173], v[202:205], v[2:5]
	v_mfma_f32_16x16x32_bf16 v[54:57], v[166:169], v[182:185], v[54:57]
	v_mfma_f32_16x16x32_bf16 v[50:53], v[174:177], v[182:185], v[50:53]
	v_mfma_f32_16x16x32_bf16 v[38:41], v[166:169], v[190:193], v[38:41]
	v_mfma_f32_16x16x32_bf16 v[34:37], v[174:177], v[190:193], v[34:37]
	v_mfma_f32_16x16x32_bf16 v[22:25], v[166:169], v[198:201], v[22:25]
	v_mfma_f32_16x16x32_bf16 v[18:21], v[174:177], v[198:201], v[18:21]
	v_mfma_f32_16x16x32_bf16 v[6:9], v[166:169], v[206:209], v[6:9]
	v_mfma_f32_16x16x32_bf16 v[2:5], v[174:177], v[206:209], v[2:5]
	s_setprio 0
	s_barrier
	s_add_u32 s55, s55, 0x100
	s_addc_u32 s56, s56, 0
	s_add_u32 s26, s26, 0x100
	s_addc_u32 s27, s27, 0
	s_cmp_ge_i32 s57, s50
	s_mov_b32 s28, s57
	s_cbranch_scc0 .LBB0_4164

; #define PG8_STAGE(bufoff, gbase, voff) do { _Pragma("unroll") for (int _i = 0; _i < 2; ++_i) \
;         __builtin_amdgcn_global_load_lds((const unsigned*)((const char*)(gbase) + (voff)[_i]), (PG8_LAS unsigned*)(lds + (bufoff) + ldsw + _i * 8192), 16, 0, 0); } while (0)
; #define PG8_LDA(dst, b, h) do { _Pragma("unroll") for (int m = 0; m < 4; ++m) _Pragma("unroll") for (int k = 0; k < 2; ++k) dst[m][k] = *(const PG8_LAS bf16x8*)(lds + PG8_SA(b, h) + aoff + m * 2048 + k * 1024); } while (0)
; #define PG8_LDB(dst, b, h) do { _Pragma("unroll") for (int n = 0; n < 2; ++n) _Pragma("unroll") for (int k = 0; k < 2; ++k) dst[n][k] = *(const PG8_LAS bf16x8*)(lds + PG8_SB(b, h) + boff + n * 2048 + k * 1024); } while (0)
; #define PG8_MMA(ai, bj, At, Bt) do { __builtin_amdgcn_s_setprio(1); _Pragma("unroll") for (int m = 0; m < 4; ++m) _Pragma("unroll") for (int n = 0; n < 2; ++n) _Pragma("unroll") for (int k = 0; k < 2; ++k) \
;         acc[ai][bj][m][n] = __builtin_amdgcn_mfma_f32_16x16x32_bf16(Bt[n][k], At[m][k], acc[ai][bj][m][n], 0, 0, 0); __builtin_amdgcn_s_setprio(0); } while (0)
; #define PG8_WAIT_V(n) asm volatile("s_waitcnt vmcnt(" #n ")" ::: "memory")
; #define PG8_BAR __builtin_amdgcn_s_barrier()
; template <class Epi, class Sched, bool ALIGN_EPI = false, bool SP2 = false>
; __device__ __forceinline__ void gemm_phase(PG8_LAS unsigned char* lds, const Gemm g, const Sched& S, const Epi& E) {
;     ...
;         for (int t = 0; t < nt; t += 2) {
;             const bool last = (t == nt - 2);
;             const char* a1 = cA + (size_t)(t + 1) * kstep;
;             const char* a2 = last ? nA : cA + (size_t)(t + 2) * kstep; const char* b2 = last ? nB : cB + (size_t)(t + 2) * kstep;
;             const char* a3 = a2 + kstep; const char* b3 = b2 + kstep;
;             if (last && has_next) S.a_ready(nxt);
;             if constexpr (SP2) {
;             PG8_LDB(B0, 0, 0); PG8_LDB(B1, 0, 1); PG8_SCHED; PG8_LDA(At, 0, 0); PG8_STAGE(PG8_SA(1, 1), a1 + hstep, voffA);
;             PG8_WAIT_V(8); PG8_WAIT_L(0); PG8_BAR; PG8_MMA(0, 0, At, B0); PG8_MMA(0, 1, At, B1); PG8_BAR; PG8_SCHED;
;             PG8_LDA(At, 0, 1); PG8_STAGE(PG8_SB(0, 0), b2, voffB); PG8_STAGE(PG8_SB(0, 1), b2 + hstep, voffB); PG8_STAGE(PG8_SA(0, 0), a2, voffA);
;             PG8_WAIT_V(8); PG8_WAIT_L(0); PG8_BAR; PG8_MMA(1, 0, At, B0); PG8_MMA(1, 1, At, B1); PG8_BAR; PG8_SCHED;
.LBB0_4580:
	s_add_i32 s55, s26, 2
	s_add_u32 s56, s24, 0x80
	s_addc_u32 s27, s25, 0
	s_add_i32 s58, 0, 0x10000
	s_cmp_eq_u32 s47, s26
	s_cselect_b32 s27, s1, s27
	s_cselect_b32 s26, s0, s56
	v_add_u32_e32 v148, s58, v149
	s_cselect_b32 s57, s23, s54
	s_cselect_b32 s56, s22, s53
	s_add_i32 s59, 0, 0x14000
	ds_read_b128 v[130:133], v148
	ds_read_b128 v[154:157], v148 offset:1024
	ds_read_b128 v[158:161], v148 offset:2048
	ds_read_b128 v[162:165], v148 offset:3072
	v_add_u32_e32 v148, s59, v149
	ds_read_b128 v[166:169], v148
	ds_read_b128 v[170:173], v148 offset:1024
	ds_read_b128 v[174:177], v148 offset:2048
	ds_read_b128 v[178:181], v148 offset:3072
	v_lshl_add_u64 v[214:215], s[24:25], 0, v[146:147]
	s_add_i32 m0, s40, 0xc000
	ds_read_b128 v[182:185], v153
	ds_read_b128 v[186:189], v153 offset:1024
	ds_read_b128 v[190:193], v153 offset:2048
	ds_read_b128 v[194:197], v153 offset:3072
	ds_read_b128 v[198:201], v153 offset:4096
	ds_read_b128 v[202:205], v153 offset:5120
	ds_read_b128 v[206:209], v153 offset:6144
	ds_read_b128 v[210:213], v153 offset:7168
	global_load_lds_dwordx4 v[214:215], off
	v_lshl_add_u64 v[214:215], s[24:25], 0, v[144:145]
	s_add_i32 m0, s40, 0xe000
	s_nop 0
	global_load_lds_dwordx4 v[214:215], off
	s_waitcnt vmcnt(8)
	s_waitcnt lgkmcnt(0)
	s_barrier
	s_setprio 1
	s_waitcnt lgkmcnt(0)
	v_mfma_f32_16x16x32_bf16 v[126:129], v[130:133], v[182:185], v[126:129]
	v_mfma_f32_16x16x32_bf16 v[122:125], v[158:161], v[182:185], v[122:125]
	v_mfma_f32_16x16x32_bf16 v[110:113], v[130:133], v[190:193], v[110:113]
	v_mfma_f32_16x16x32_bf16 v[106:109], v[158:161], v[190:193], v[106:109]
	v_mfma_f32_16x16x32_bf16 v[94:97], v[130:133], v[198:201], v[94:97]
	v_mfma_f32_16x16x32_bf16 v[90:93], v[158:161], v[198:201], v[90:93]
	v_mfma_f32_16x16x32_bf16 v[78:81], v[130:133], v[206:209], v[78:81]
	v_mfma_f32_16x16x32_bf16 v[74:77], v[158:161], v[206:209], v[74:77]
	v_mfma_f32_16x16x32_bf16 v[126:129], v[154:157], v[186:189], v[126:129]
	v_mfma_f32_16x16x32_bf16 v[122:125], v[162:165], v[186:189], v[122:125]
	v_mfma_f32_16x16x32_bf16 v[110:113], v[154:157], v[194:197], v[110:113]
	v_mfma_f32_16x16x32_bf16 v[106:109], v[162:165], v[194:197], v[106:109]
	v_mfma_f32_16x16x32_bf16 v[94:97], v[154:157], v[202:205], v[94:97]
	v_mfma_f32_16x16x32_bf16 v[90:93], v[162:165], v[202:205], v[90:93]
	v_mfma_f32_16x16x32_bf16 v[78:81], v[154:157], v[210:213], v[78:81]
	v_mfma_f32_16x16x32_bf16 v[74:77], v[162:165], v[210:213], v[74:77]
	v_mfma_f32_16x16x32_bf16 v[118:121], v[166:169], v[182:185], v[118:121]
	v_mfma_f32_16x16x32_bf16 v[114:117], v[174:177], v[182:185], v[114:117]
	v_mfma_f32_16x16x32_bf16 v[102:105], v[166:169], v[190:193], v[102:105]
	v_mfma_f32_16x16x32_bf16 v[98:101], v[174:177], v[190:193], v[98:101]
	v_mfma_f32_16x16x32_bf16 v[86:89], v[166:169], v[198:201], v[86:89]
	v_mfma_f32_16x16x32_bf16 v[82:85], v[174:177], v[198:201], v[82:85]
	v_mfma_f32_16x16x32_bf16 v[70:73], v[166:169], v[206:209], v[70:73]
	v_mfma_f32_16x16x32_bf16 v[66:69], v[174:177], v[206:209], v[66:69]
	v_mfma_f32_16x16x32_bf16 v[118:121], v[170:173], v[186:189], v[118:121]
	v_mfma_f32_16x16x32_bf16 v[114:117], v[178:181], v[186:189], v[114:117]
	v_mfma_f32_16x16x32_bf16 v[102:105], v[170:173], v[194:197], v[102:105]
	v_mfma_f32_16x16x32_bf16 v[98:101], v[178:181], v[194:197], v[98:101]
	v_mfma_f32_16x16x32_bf16 v[86:89], v[170:173], v[202:205], v[86:89]
	v_mfma_f32_16x16x32_bf16 v[82:85], v[178:181], v[202:205], v[82:85]
	v_mfma_f32_16x16x32_bf16 v[70:73], v[170:173], v[210:213], v[70:73]
	v_mfma_f32_16x16x32_bf16 v[66:69], v[178:181], v[210:213], v[66:69]
	s_setprio 0
	s_barrier
	s_add_i32 s58, s58, s35
	v_lshl_add_u64 v[214:215], s[56:57], 0, v[136:137]
	s_mov_b32 m0, s58
	ds_read_b128 v[182:185], v153 offset:16384
	ds_read_b128 v[186:189], v153 offset:17408
	ds_read_b128 v[190:193], v153 offset:18432
	ds_read_b128 v[194:197], v153 offset:19456
	ds_read_b128 v[198:201], v153 offset:20480
	ds_read_b128 v[202:205], v153 offset:21504
	ds_read_b128 v[206:209], v153 offset:22528
	ds_read_b128 v[210:213], v153 offset:23552
	global_load_lds_dwordx4 v[214:215], off
	s_add_i32 m0, s58, 0x2000
	v_lshl_add_u64 v[216:217], s[56:57], 0, v[140:141]
	s_add_u32 s56, s56, s10
	s_addc_u32 s57, s57, s11
	s_add_i32 s58, s59, s35
	global_load_lds_dwordx4 v[216:217], off
	v_lshl_add_u64 v[218:219], s[56:57], 0, v[136:137]
	s_mov_b32 m0, s58
	v_lshl_add_u64 v[228:229], s[56:57], 0, v[140:141]
	global_load_lds_dwordx4 v[218:219], off
	s_add_i32 m0, s58, 0x2000
	v_lshl_add_u64 v[242:243], s[26:27], 0, v[134:135]
	global_load_lds_dwordx4 v[228:229], off
	s_mov_b32 m0, s40
	v_lshl_add_u64 v[244:245], s[26:27], 0, v[138:139]
	global_load_lds_dwordx4 v[242:243], off
	s_mov_b32 m0, s41
	s_nop 0
	global_load_lds_dwordx4 v[244:245], off
	s_waitcnt vmcnt(8)
	s_waitcnt lgkmcnt(0)
	s_barrier
; #define PG8_STAGE(bufoff, gbase, voff) do { _Pragma("unroll") for (int _i = 0; _i < 2; ++_i) \
;         __builtin_amdgcn_global_load_lds((const unsigned*)((const char*)(gbase) + (voff)[_i]), (PG8_LAS unsigned*)(lds + (bufoff) + ldsw + _i * 8192), 16, 0, 0); } while (0)
; #define PG8_LDA(dst, b, h) do { _Pragma("unroll") for (int m = 0; m < 4; ++m) _Pragma("unroll") for (int k = 0; k < 2; ++k) dst[m][k] = *(const PG8_LAS bf16x8*)(lds + PG8_SA(b, h) + aoff + m * 2048 + k * 1024); } while (0)
; #define PG8_LDB(dst, b, h) do { _Pragma("unroll") for (int n = 0; n < 2; ++n) _Pragma("unroll") for (int k = 0; k < 2; ++k) dst[n][k] = *(const PG8_LAS bf16x8*)(lds + PG8_SB(b, h) + boff + n * 2048 + k * 1024); } while (0)
; #define PG8_MMA(ai, bj, At, Bt) do { __builtin_amdgcn_s_setprio(1); _Pragma("unroll") for (int m = 0; m < 4; ++m) _Pragma("unroll") for (int n = 0; n < 2; ++n) _Pragma("unroll") for (int k = 0; k < 2; ++k) \
;         acc[ai][bj][m][n] = __builtin_amdgcn_mfma_f32_16x16x32_bf16(Bt[n][k], At[m][k], acc[ai][bj][m][n], 0, 0, 0); __builtin_amdgcn_s_setprio(0); } while (0)
; #define PG8_WAIT_V(n) asm volatile("s_waitcnt vmcnt(" #n ")" ::: "memory")
; #define PG8_WAIT_L(n) asm volatile("s_waitcnt lgkmcnt(" #n ")" ::: "memory")
; #define PG8_BAR __builtin_amdgcn_s_barrier()
; #define PG8_SCHED __builtin_amdgcn_sched_barrier(0)
; template <class Epi, class Sched, bool ALIGN_EPI = false, bool SP2 = false>
; __device__ __forceinline__ void gemm_phase(PG8_LAS unsigned char* lds, const Gemm g, const Sched& S, const Epi& E) {
;     ...
;             PG8_WAIT_V(8); PG8_WAIT_L(0); PG8_BAR; PG8_MMA(1, 0, At, B0); PG8_MMA(1, 1, At, B1); PG8_BAR; PG8_SCHED;
;             PG8_LDB(B0, 1, 0); PG8_LDB(B1, 1, 1); PG8_SCHED; PG8_LDA(At, 1, 0); PG8_STAGE(PG8_SA(0, 1), a2 + hstep, voffA);
;             PG8_WAIT_V(8); PG8_WAIT_L(0); PG8_BAR; PG8_MMA(0, 0, At, B0); PG8_MMA(0, 1, At, B1); PG8_BAR; PG8_SCHED;
	s_setprio 1
	s_waitcnt lgkmcnt(0)
	v_mfma_f32_16x16x32_bf16 v[62:65], v[130:133], v[182:185], v[62:65]
	v_mfma_f32_16x16x32_bf16 v[58:61], v[158:161], v[182:185], v[58:61]
	v_mfma_f32_16x16x32_bf16 v[46:49], v[130:133], v[190:193], v[46:49]
	v_mfma_f32_16x16x32_bf16 v[42:45], v[158:161], v[190:193], v[42:45]
	v_mfma_f32_16x16x32_bf16 v[30:33], v[130:133], v[198:201], v[30:33]
	v_mfma_f32_16x16x32_bf16 v[26:29], v[158:161], v[198:201], v[26:29]
	v_mfma_f32_16x16x32_bf16 v[14:17], v[130:133], v[206:209], v[14:17]
	v_mfma_f32_16x16x32_bf16 v[10:13], v[158:161], v[206:209], v[10:13]
	v_mfma_f32_16x16x32_bf16 v[62:65], v[154:157], v[186:189], v[62:65]
	v_mfma_f32_16x16x32_bf16 v[58:61], v[162:165], v[186:189], v[58:61]
	v_mfma_f32_16x16x32_bf16 v[46:49], v[154:157], v[194:197], v[46:49]
	v_mfma_f32_16x16x32_bf16 v[42:45], v[162:165], v[194:197], v[42:45]
	v_mfma_f32_16x16x32_bf16 v[30:33], v[154:157], v[202:205], v[30:33]
	v_mfma_f32_16x16x32_bf16 v[26:29], v[162:165], v[202:205], v[26:29]
	v_mfma_f32_16x16x32_bf16 v[14:17], v[154:157], v[210:213], v[14:17]
	v_mfma_f32_16x16x32_bf16 v[10:13], v[162:165], v[210:213], v[10:13]
	v_mfma_f32_16x16x32_bf16 v[54:57], v[166:169], v[182:185], v[54:57]
	v_mfma_f32_16x16x32_bf16 v[50:53], v[174:177], v[182:185], v[50:53]
	v_mfma_f32_16x16x32_bf16 v[38:41], v[166:169], v[190:193], v[38:41]
	v_mfma_f32_16x16x32_bf16 v[34:37], v[174:177], v[190:193], v[34:37]
	v_mfma_f32_16x16x32_bf16 v[22:25], v[166:169], v[198:201], v[22:25]
	v_mfma_f32_16x16x32_bf16 v[18:21], v[174:177], v[198:201], v[18:21]
	v_mfma_f32_16x16x32_bf16 v[6:9], v[166:169], v[206:209], v[6:9]
	v_mfma_f32_16x16x32_bf16 v[2:5], v[174:177], v[206:209], v[2:5]
	v_mfma_f32_16x16x32_bf16 v[54:57], v[170:173], v[186:189], v[54:57]
	v_mfma_f32_16x16x32_bf16 v[50:53], v[178:181], v[186:189], v[50:53]
	v_mfma_f32_16x16x32_bf16 v[38:41], v[170:173], v[194:197], v[38:41]
	v_mfma_f32_16x16x32_bf16 v[34:37], v[178:181], v[194:197], v[34:37]
	v_mfma_f32_16x16x32_bf16 v[22:25], v[170:173], v[202:205], v[22:25]
	v_mfma_f32_16x16x32_bf16 v[18:21], v[178:181], v[202:205], v[18:21]
	v_mfma_f32_16x16x32_bf16 v[6:9], v[170:173], v[210:213], v[6:9]
	v_mfma_f32_16x16x32_bf16 v[2:5], v[178:181], v[210:213], v[2:5]
	s_setprio 0
	s_barrier
	s_add_i32 s56, 0, 0x18000
	v_add_u32_e32 v148, s56, v149
	s_add_i32 s57, 0, 0x1c000
	ds_read_b128 v[130:133], v148
	ds_read_b128 v[154:157], v148 offset:1024
	ds_read_b128 v[158:161], v148 offset:2048
	ds_read_b128 v[162:165], v148 offset:3072
	v_add_u32_e32 v148, s57, v149
	ds_read_b128 v[166:169], v148
	ds_read_b128 v[170:173], v148 offset:1024
	ds_read_b128 v[174:177], v148 offset:2048
	ds_read_b128 v[178:181], v148 offset:3072
	s_add_u32 s26, s26, s10
	s_addc_u32 s27, s27, s11
	s_mov_b32 m0, s42
	v_lshl_add_u64 v[246:247], s[26:27], 0, v[134:135]
	ds_read_b128 v[182:185], v153 offset:32768
	ds_read_b128 v[186:189], v153 offset:33792
	ds_read_b128 v[190:193], v153 offset:34816
	ds_read_b128 v[194:197], v153 offset:35840
	ds_read_b128 v[198:201], v153 offset:36864
	ds_read_b128 v[202:205], v153 offset:37888
	ds_read_b128 v[206:209], v153 offset:38912
	ds_read_b128 v[210:213], v153 offset:39936
	global_load_lds_dwordx4 v[246:247], off
	v_lshl_add_u64 v[246:247], s[26:27], 0, v[138:139]
	s_mov_b32 m0, s43
	s_nop 0
	global_load_lds_dwordx4 v[246:247], off
	s_waitcnt vmcnt(8)
	s_waitcnt lgkmcnt(0)
	s_barrier
	s_setprio 1
	s_waitcnt lgkmcnt(0)
	v_mfma_f32_16x16x32_bf16 v[126:129], v[130:133], v[182:185], v[126:129]
	v_mfma_f32_16x16x32_bf16 v[122:125], v[158:161], v[182:185], v[122:125]
	v_mfma_f32_16x16x32_bf16 v[110:113], v[130:133], v[190:193], v[110:113]
	v_mfma_f32_16x16x32_bf16 v[106:109], v[158:161], v[190:193], v[106:109]
	v_mfma_f32_16x16x32_bf16 v[94:97], v[130:133], v[198:201], v[94:97]
	v_mfma_f32_16x16x32_bf16 v[90:93], v[158:161], v[198:201], v[90:93]
	v_mfma_f32_16x16x32_bf16 v[78:81], v[130:133], v[206:209], v[78:81]
	v_mfma_f32_16x16x32_bf16 v[74:77], v[158:161], v[206:209], v[74:77]
	v_mfma_f32_16x16x32_bf16 v[126:129], v[154:157], v[186:189], v[126:129]
	v_mfma_f32_16x16x32_bf16 v[122:125], v[162:165], v[186:189], v[122:125]
	v_mfma_f32_16x16x32_bf16 v[110:113], v[154:157], v[194:197], v[110:113]
	v_mfma_f32_16x16x32_bf16 v[106:109], v[162:165], v[194:197], v[106:109]
	v_mfma_f32_16x16x32_bf16 v[94:97], v[154:157], v[202:205], v[94:97]
	v_mfma_f32_16x16x32_bf16 v[90:93], v[162:165], v[202:205], v[90:93]
	v_mfma_f32_16x16x32_bf16 v[78:81], v[154:157], v[210:213], v[78:81]
	v_mfma_f32_16x16x32_bf16 v[74:77], v[162:165], v[210:213], v[74:77]
	v_mfma_f32_16x16x32_bf16 v[118:121], v[166:169], v[182:185], v[118:121]
	v_mfma_f32_16x16x32_bf16 v[114:117], v[174:177], v[182:185], v[114:117]
	v_mfma_f32_16x16x32_bf16 v[102:105], v[166:169], v[190:193], v[102:105]
	v_mfma_f32_16x16x32_bf16 v[98:101], v[174:177], v[190:193], v[98:101]
	v_mfma_f32_16x16x32_bf16 v[86:89], v[166:169], v[198:201], v[86:89]
	v_mfma_f32_16x16x32_bf16 v[82:85], v[174:177], v[198:201], v[82:85]
	v_mfma_f32_16x16x32_bf16 v[70:73], v[166:169], v[206:209], v[70:73]
	v_mfma_f32_16x16x32_bf16 v[66:69], v[174:177], v[206:209], v[66:69]
	v_mfma_f32_16x16x32_bf16 v[118:121], v[170:173], v[186:189], v[118:121]
	v_mfma_f32_16x16x32_bf16 v[114:117], v[178:181], v[186:189], v[114:117]
	v_mfma_f32_16x16x32_bf16 v[102:105], v[170:173], v[194:197], v[102:105]
	v_mfma_f32_16x16x32_bf16 v[98:101], v[178:181], v[194:197], v[98:101]
	v_mfma_f32_16x16x32_bf16 v[86:89], v[170:173], v[202:205], v[86:89]
	v_mfma_f32_16x16x32_bf16 v[82:85], v[178:181], v[202:205], v[82:85]
	v_mfma_f32_16x16x32_bf16 v[70:73], v[170:173], v[210:213], v[70:73]
	v_mfma_f32_16x16x32_bf16 v[66:69], v[178:181], v[210:213], v[66:69]
	s_setprio 0
	s_barrier
; #define PG8_STAGE(bufoff, gbase, voff) do { _Pragma("unroll") for (int _i = 0; _i < 2; ++_i) \
;         __builtin_amdgcn_global_load_lds((const unsigned*)((const char*)(gbase) + (voff)[_i]), (PG8_LAS unsigned*)(lds + (bufoff) + ldsw + _i * 8192), 16, 0, 0); } while (0)
; #define PG8_LDA(dst, b, h) do { _Pragma("unroll") for (int m = 0; m < 4; ++m) _Pragma("unroll") for (int k = 0; k < 2; ++k) dst[m][k] = *(const PG8_LAS bf16x8*)(lds + PG8_SA(b, h) + aoff + m * 2048 + k * 1024); } while (0)
; #define PG8_MMA(ai, bj, At, Bt) do { __builtin_amdgcn_s_setprio(1); _Pragma("unroll") for (int m = 0; m < 4; ++m) _Pragma("unroll") for (int n = 0; n < 2; ++n) _Pragma("unroll") for (int k = 0; k < 2; ++k) \
;         acc[ai][bj][m][n] = __builtin_amdgcn_mfma_f32_16x16x32_bf16(Bt[n][k], At[m][k], acc[ai][bj][m][n], 0, 0, 0); __builtin_amdgcn_s_setprio(0); } while (0)
; #define PG8_WAIT_V(n) asm volatile("s_waitcnt vmcnt(" #n ")" ::: "memory")
; #define PG8_WAIT_L(n) asm volatile("s_waitcnt lgkmcnt(" #n ")" ::: "memory")
; #define PG8_BAR __builtin_amdgcn_s_barrier()
; #define PG8_SCHED __builtin_amdgcn_sched_barrier(0)
; template <class Epi, class Sched, bool ALIGN_EPI = false, bool SP2 = false>
; __device__ __forceinline__ void gemm_phase(PG8_LAS unsigned char* lds, const Gemm g, const Sched& S, const Epi& E) {
;     ...
;         for (int t = 0; t < nt; t += 2) {
;             const bool last = (t == nt - 2);
;             const char* a1 = cA + (size_t)(t + 1) * kstep;
;             const char* a2 = last ? nA : cA + (size_t)(t + 2) * kstep; const char* b2 = last ? nB : cB + (size_t)(t + 2) * kstep;
;     ...
;             PG8_LDA(At, 1, 1); PG8_STAGE(PG8_SB(1, 0), b3, voffB); PG8_STAGE(PG8_SB(1, 1), b3 + hstep, voffB); PG8_STAGE(PG8_SA(1, 0), a3, voffA);
;             PG8_WAIT_V(8); PG8_WAIT_L(0); PG8_BAR; PG8_MMA(1, 0, At, B0); PG8_MMA(1, 1, At, B1); PG8_BAR; PG8_SCHED;
	s_add_i32 s26, s56, s35
	v_lshl_add_u64 v[214:215], v[214:215], 0, s[92:93]
	s_mov_b32 m0, s26
	ds_read_b128 v[182:185], v153 offset:49152
	ds_read_b128 v[186:189], v153 offset:50176
	ds_read_b128 v[190:193], v153 offset:51200
	ds_read_b128 v[194:197], v153 offset:52224
	ds_read_b128 v[198:201], v153 offset:53248
	ds_read_b128 v[202:205], v153 offset:54272
	ds_read_b128 v[206:209], v153 offset:55296
	ds_read_b128 v[210:213], v153 offset:56320
	global_load_lds_dwordx4 v[214:215], off
	v_lshl_add_u64 v[214:215], v[216:217], 0, s[92:93]
	s_add_i32 m0, s26, 0x2000
	s_add_i32 s26, s57, s35
	global_load_lds_dwordx4 v[214:215], off
	v_lshl_add_u64 v[214:215], v[218:219], 0, s[92:93]
	s_mov_b32 m0, s26
	s_nop 0
	global_load_lds_dwordx4 v[214:215], off
	v_lshl_add_u64 v[214:215], v[228:229], 0, s[92:93]
	s_add_i32 m0, s26, 0x2000
	s_nop 0
	global_load_lds_dwordx4 v[214:215], off
	v_lshl_add_u64 v[214:215], v[242:243], 0, s[92:93]
	s_mov_b32 m0, s44
	s_nop 0
	global_load_lds_dwordx4 v[214:215], off
	v_lshl_add_u64 v[214:215], v[244:245], 0, s[92:93]
	s_mov_b32 m0, s45
	s_nop 0
	global_load_lds_dwordx4 v[214:215], off
	s_waitcnt vmcnt(8)
	s_waitcnt lgkmcnt(0)
	s_barrier
	s_setprio 1
	s_waitcnt lgkmcnt(0)
	v_mfma_f32_16x16x32_bf16 v[62:65], v[130:133], v[182:185], v[62:65]
	v_mfma_f32_16x16x32_bf16 v[58:61], v[158:161], v[182:185], v[58:61]
	v_mfma_f32_16x16x32_bf16 v[46:49], v[130:133], v[190:193], v[46:49]
	v_mfma_f32_16x16x32_bf16 v[42:45], v[158:161], v[190:193], v[42:45]
	v_mfma_f32_16x16x32_bf16 v[30:33], v[130:133], v[198:201], v[30:33]
	v_mfma_f32_16x16x32_bf16 v[26:29], v[158:161], v[198:201], v[26:29]
	v_mfma_f32_16x16x32_bf16 v[14:17], v[130:133], v[206:209], v[14:17]
	v_mfma_f32_16x16x32_bf16 v[10:13], v[158:161], v[206:209], v[10:13]
	v_mfma_f32_16x16x32_bf16 v[62:65], v[154:157], v[186:189], v[62:65]
	v_mfma_f32_16x16x32_bf16 v[58:61], v[162:165], v[186:189], v[58:61]
	v_mfma_f32_16x16x32_bf16 v[46:49], v[154:157], v[194:197], v[46:49]
	v_mfma_f32_16x16x32_bf16 v[42:45], v[162:165], v[194:197], v[42:45]
	v_mfma_f32_16x16x32_bf16 v[30:33], v[154:157], v[202:205], v[30:33]
	v_mfma_f32_16x16x32_bf16 v[26:29], v[162:165], v[202:205], v[26:29]
	v_mfma_f32_16x16x32_bf16 v[14:17], v[154:157], v[210:213], v[14:17]
	v_mfma_f32_16x16x32_bf16 v[10:13], v[162:165], v[210:213], v[10:13]
	v_mfma_f32_16x16x32_bf16 v[54:57], v[166:169], v[182:185], v[54:57]
	v_mfma_f32_16x16x32_bf16 v[50:53], v[174:177], v[182:185], v[50:53]
	v_mfma_f32_16x16x32_bf16 v[38:41], v[166:169], v[190:193], v[38:41]
	v_mfma_f32_16x16x32_bf16 v[34:37], v[174:177], v[190:193], v[34:37]
	v_mfma_f32_16x16x32_bf16 v[22:25], v[166:169], v[198:201], v[22:25]
	v_mfma_f32_16x16x32_bf16 v[18:21], v[174:177], v[198:201], v[18:21]
	v_mfma_f32_16x16x32_bf16 v[6:9], v[166:169], v[206:209], v[6:9]
	v_mfma_f32_16x16x32_bf16 v[2:5], v[174:177], v[206:209], v[2:5]
	v_mfma_f32_16x16x32_bf16 v[54:57], v[170:173], v[186:189], v[54:57]
	v_mfma_f32_16x16x32_bf16 v[50:53], v[178:181], v[186:189], v[50:53]
	v_mfma_f32_16x16x32_bf16 v[38:41], v[170:173], v[194:197], v[38:41]
	v_mfma_f32_16x16x32_bf16 v[34:37], v[178:181], v[194:197], v[34:37]
	v_mfma_f32_16x16x32_bf16 v[22:25], v[170:173], v[202:205], v[22:25]
	v_mfma_f32_16x16x32_bf16 v[18:21], v[178:181], v[202:205], v[18:21]
	v_mfma_f32_16x16x32_bf16 v[6:9], v[170:173], v[210:213], v[6:9]
	v_mfma_f32_16x16x32_bf16 v[2:5], v[178:181], v[210:213], v[2:5]
	s_setprio 0
	s_barrier
	s_add_u32 s53, s53, 0x100
	s_addc_u32 s54, s54, 0
	s_add_u32 s24, s24, 0x100
	s_addc_u32 s25, s25, 0
	s_cmp_ge_i32 s55, s46
	s_mov_b32 s26, s55
	s_cbranch_scc0 .LBB0_4580

; #define PG8_STAGE(bufoff, gbase, voff) do { _Pragma("unroll") for (int _i = 0; _i < 2; ++_i) \
;         __builtin_amdgcn_global_load_lds((const unsigned*)((const char*)(gbase) + (voff)[_i]), (PG8_LAS unsigned*)(lds + (bufoff) + ldsw + _i * 8192), 16, 0, 0); } while (0)
; #define PG8_LDA(dst, b, h) do { _Pragma("unroll") for (int m = 0; m < 4; ++m) _Pragma("unroll") for (int k = 0; k < 2; ++k) dst[m][k] = *(const PG8_LAS bf16x8*)(lds + PG8_SA(b, h) + aoff + m * 2048 + k * 1024); } while (0)
; #define PG8_LDB(dst, b, h) do { _Pragma("unroll") for (int n = 0; n < 2; ++n) _Pragma("unroll") for (int k = 0; k < 2; ++k) dst[n][k] = *(const PG8_LAS bf16x8*)(lds + PG8_SB(b, h) + boff + n * 2048 + k * 1024); } while (0)
; #define PG8_MMA(ai, bj, At, Bt) do { __builtin_amdgcn_s_setprio(1); _Pragma("unroll") for (int m = 0; m < 4; ++m) _Pragma("unroll") for (int n = 0; n < 2; ++n) _Pragma("unroll") for (int k = 0; k < 2; ++k) \
;         acc[ai][bj][m][n] = __builtin_amdgcn_mfma_f32_16x16x32_bf16(Bt[n][k], At[m][k], acc[ai][bj][m][n], 0, 0, 0); __builtin_amdgcn_s_setprio(0); } while (0)
; #define PG8_WAIT_V(n) asm volatile("s_waitcnt vmcnt(" #n ")" ::: "memory")
; #define PG8_BAR __builtin_amdgcn_s_barrier()
; template <class Epi, class Sched, bool ALIGN_EPI = false, bool SP2 = false>
; __device__ __forceinline__ void gemm_phase(PG8_LAS unsigned char* lds, const Gemm g, const Sched& S, const Epi& E) {
;     ...
;         for (int t = 0; t < nt; t += 2) {
;             const bool last = (t == nt - 2);
;             const char* a1 = cA + (size_t)(t + 1) * kstep;
;             const char* a2 = last ? nA : cA + (size_t)(t + 2) * kstep; const char* b2 = last ? nB : cB + (size_t)(t + 2) * kstep;
;             const char* a3 = a2 + kstep; const char* b3 = b2 + kstep;
;             if (last && has_next) S.a_ready(nxt);
;             if constexpr (SP2) {
;             PG8_LDB(B0, 0, 0); PG8_LDB(B1, 0, 1); PG8_SCHED; PG8_LDA(At, 0, 0); PG8_STAGE(PG8_SA(1, 1), a1 + hstep, voffA);
;             PG8_WAIT_V(8); PG8_WAIT_L(0); PG8_BAR; PG8_MMA(0, 0, At, B0); PG8_MMA(0, 1, At, B1); PG8_BAR; PG8_SCHED;
;             PG8_LDA(At, 0, 1); PG8_STAGE(PG8_SB(0, 0), b2, voffB); PG8_STAGE(PG8_SB(0, 1), b2 + hstep, voffB); PG8_STAGE(PG8_SA(0, 0), a2, voffA);
;             PG8_WAIT_V(8); PG8_WAIT_L(0); PG8_BAR; PG8_MMA(1, 0, At, B0); PG8_MMA(1, 1, At, B1); PG8_BAR; PG8_SCHED;
.LBB0_4845:
	s_add_i32 s55, s26, 2
	s_add_u32 s56, s24, 0x80
	s_addc_u32 s27, s25, 0
	s_add_i32 s58, 0, 0x10000
	s_cmp_eq_u32 s47, s26
	s_cselect_b32 s27, s1, s27
	s_cselect_b32 s26, s0, s56
	v_add_u32_e32 v148, s58, v151
	s_cselect_b32 s57, s23, s54
	s_cselect_b32 s56, s22, s53
	s_add_i32 s59, 0, 0x14000
	ds_read_b128 v[130:133], v148
	ds_read_b128 v[156:159], v148 offset:1024
	ds_read_b128 v[162:165], v148 offset:2048
	ds_read_b128 v[166:169], v148 offset:3072
	v_add_u32_e32 v148, s59, v151
	ds_read_b128 v[170:173], v148
	ds_read_b128 v[174:177], v148 offset:1024
	ds_read_b128 v[178:181], v148 offset:2048
	ds_read_b128 v[182:185], v148 offset:3072
	v_lshl_add_u64 v[148:149], s[24:25], 0, v[146:147]
	s_add_i32 m0, s40, 0xc000
	ds_read_b128 v[186:189], v161
	ds_read_b128 v[190:193], v161 offset:1024
	ds_read_b128 v[194:197], v161 offset:2048
	ds_read_b128 v[198:201], v161 offset:3072
	ds_read_b128 v[202:205], v161 offset:4096
	ds_read_b128 v[206:209], v161 offset:5120
	ds_read_b128 v[210:213], v161 offset:6144
	ds_read_b128 v[214:217], v161 offset:7168
	global_load_lds_dwordx4 v[148:149], off
	v_lshl_add_u64 v[148:149], s[24:25], 0, v[144:145]
	s_add_i32 m0, s40, 0xe000
	s_nop 0
	global_load_lds_dwordx4 v[148:149], off
	s_waitcnt vmcnt(8)
	s_waitcnt lgkmcnt(0)
	s_barrier
	s_setprio 1
	s_waitcnt lgkmcnt(0)
	v_mfma_f32_16x16x32_bf16 v[122:125], v[130:133], v[186:189], v[122:125]
	v_mfma_f32_16x16x32_bf16 v[126:129], v[162:165], v[186:189], v[126:129]
	v_mfma_f32_16x16x32_bf16 v[110:113], v[130:133], v[194:197], v[110:113]
	v_mfma_f32_16x16x32_bf16 v[106:109], v[162:165], v[194:197], v[106:109]
	v_mfma_f32_16x16x32_bf16 v[94:97], v[130:133], v[202:205], v[94:97]
	v_mfma_f32_16x16x32_bf16 v[90:93], v[162:165], v[202:205], v[90:93]
	v_mfma_f32_16x16x32_bf16 v[78:81], v[130:133], v[210:213], v[78:81]
	v_mfma_f32_16x16x32_bf16 v[74:77], v[162:165], v[210:213], v[74:77]
	v_mfma_f32_16x16x32_bf16 v[122:125], v[156:159], v[190:193], v[122:125]
	v_mfma_f32_16x16x32_bf16 v[126:129], v[166:169], v[190:193], v[126:129]
	v_mfma_f32_16x16x32_bf16 v[110:113], v[156:159], v[198:201], v[110:113]
	v_mfma_f32_16x16x32_bf16 v[106:109], v[166:169], v[198:201], v[106:109]
	v_mfma_f32_16x16x32_bf16 v[94:97], v[156:159], v[206:209], v[94:97]
	v_mfma_f32_16x16x32_bf16 v[90:93], v[166:169], v[206:209], v[90:93]
	v_mfma_f32_16x16x32_bf16 v[78:81], v[156:159], v[214:217], v[78:81]
	v_mfma_f32_16x16x32_bf16 v[74:77], v[166:169], v[214:217], v[74:77]
	v_mfma_f32_16x16x32_bf16 v[118:121], v[170:173], v[186:189], v[118:121]
	v_mfma_f32_16x16x32_bf16 v[114:117], v[178:181], v[186:189], v[114:117]
	v_mfma_f32_16x16x32_bf16 v[102:105], v[170:173], v[194:197], v[102:105]
	v_mfma_f32_16x16x32_bf16 v[98:101], v[178:181], v[194:197], v[98:101]
	v_mfma_f32_16x16x32_bf16 v[86:89], v[170:173], v[202:205], v[86:89]
	v_mfma_f32_16x16x32_bf16 v[82:85], v[178:181], v[202:205], v[82:85]
	v_mfma_f32_16x16x32_bf16 v[70:73], v[170:173], v[210:213], v[70:73]
	v_mfma_f32_16x16x32_bf16 v[66:69], v[178:181], v[210:213], v[66:69]
	v_mfma_f32_16x16x32_bf16 v[118:121], v[174:177], v[190:193], v[118:121]
	v_mfma_f32_16x16x32_bf16 v[114:117], v[182:185], v[190:193], v[114:117]
	v_mfma_f32_16x16x32_bf16 v[102:105], v[174:177], v[198:201], v[102:105]
	v_mfma_f32_16x16x32_bf16 v[98:101], v[182:185], v[198:201], v[98:101]
	v_mfma_f32_16x16x32_bf16 v[86:89], v[174:177], v[206:209], v[86:89]
	v_mfma_f32_16x16x32_bf16 v[82:85], v[182:185], v[206:209], v[82:85]
	v_mfma_f32_16x16x32_bf16 v[70:73], v[174:177], v[214:217], v[70:73]
	v_mfma_f32_16x16x32_bf16 v[66:69], v[182:185], v[214:217], v[66:69]
	s_setprio 0
	s_barrier
	s_add_i32 s58, s58, s35
	v_lshl_add_u64 v[148:149], s[56:57], 0, v[136:137]
	s_mov_b32 m0, s58
	ds_read_b128 v[186:189], v161 offset:16384
	ds_read_b128 v[190:193], v161 offset:17408
	ds_read_b128 v[194:197], v161 offset:18432
	ds_read_b128 v[198:201], v161 offset:19456
	ds_read_b128 v[202:205], v161 offset:20480
	ds_read_b128 v[206:209], v161 offset:21504
	ds_read_b128 v[210:213], v161 offset:22528
	ds_read_b128 v[214:217], v161 offset:23552
	global_load_lds_dwordx4 v[148:149], off
	s_add_i32 m0, s58, 0x2000
	v_lshl_add_u64 v[152:153], s[56:57], 0, v[140:141]
	s_add_u32 s56, s56, s10
	s_addc_u32 s57, s57, s11
	s_add_i32 s58, s59, s35
	global_load_lds_dwordx4 v[152:153], off
	v_lshl_add_u64 v[218:219], s[56:57], 0, v[136:137]
	s_mov_b32 m0, s58
	v_lshl_add_u64 v[228:229], s[56:57], 0, v[140:141]
	global_load_lds_dwordx4 v[218:219], off
	s_add_i32 m0, s58, 0x2000
	v_lshl_add_u64 v[242:243], s[26:27], 0, v[134:135]
	global_load_lds_dwordx4 v[228:229], off
	s_mov_b32 m0, s40
	v_lshl_add_u64 v[244:245], s[26:27], 0, v[138:139]
	global_load_lds_dwordx4 v[242:243], off
	s_mov_b32 m0, s41
	s_nop 0
	global_load_lds_dwordx4 v[244:245], off
	s_waitcnt vmcnt(8)
	s_waitcnt lgkmcnt(0)
	s_barrier
; #define PG8_STAGE(bufoff, gbase, voff) do { _Pragma("unroll") for (int _i = 0; _i < 2; ++_i) \
;         __builtin_amdgcn_global_load_lds((const unsigned*)((const char*)(gbase) + (voff)[_i]), (PG8_LAS unsigned*)(lds + (bufoff) + ldsw + _i * 8192), 16, 0, 0); } while (0)
; #define PG8_LDA(dst, b, h) do { _Pragma("unroll") for (int m = 0; m < 4; ++m) _Pragma("unroll") for (int k = 0; k < 2; ++k) dst[m][k] = *(const PG8_LAS bf16x8*)(lds + PG8_SA(b, h) + aoff + m * 2048 + k * 1024); } while (0)
; #define PG8_LDB(dst, b, h) do { _Pragma("unroll") for (int n = 0; n < 2; ++n) _Pragma("unroll") for (int k = 0; k < 2; ++k) dst[n][k] = *(const PG8_LAS bf16x8*)(lds + PG8_SB(b, h) + boff + n * 2048 + k * 1024); } while (0)
; #define PG8_MMA(ai, bj, At, Bt) do { __builtin_amdgcn_s_setprio(1); _Pragma("unroll") for (int m = 0; m < 4; ++m) _Pragma("unroll") for (int n = 0; n < 2; ++n) _Pragma("unroll") for (int k = 0; k < 2; ++k) \
;         acc[ai][bj][m][n] = __builtin_amdgcn_mfma_f32_16x16x32_bf16(Bt[n][k], At[m][k], acc[ai][bj][m][n], 0, 0, 0); __builtin_amdgcn_s_setprio(0); } while (0)
; #define PG8_WAIT_V(n) asm volatile("s_waitcnt vmcnt(" #n ")" ::: "memory")
; #define PG8_WAIT_L(n) asm volatile("s_waitcnt lgkmcnt(" #n ")" ::: "memory")
; #define PG8_BAR __builtin_amdgcn_s_barrier()
; #define PG8_SCHED __builtin_amdgcn_sched_barrier(0)
; template <class Epi, class Sched, bool ALIGN_EPI = false, bool SP2 = false>
; __device__ __forceinline__ void gemm_phase(PG8_LAS unsigned char* lds, const Gemm g, const Sched& S, const Epi& E) {
;     ...
;             PG8_WAIT_V(8); PG8_WAIT_L(0); PG8_BAR; PG8_MMA(1, 0, At, B0); PG8_MMA(1, 1, At, B1); PG8_BAR; PG8_SCHED;
;             PG8_LDB(B0, 1, 0); PG8_LDB(B1, 1, 1); PG8_SCHED; PG8_LDA(At, 1, 0); PG8_STAGE(PG8_SA(0, 1), a2 + hstep, voffA);
;             PG8_WAIT_V(8); PG8_WAIT_L(0); PG8_BAR; PG8_MMA(0, 0, At, B0); PG8_MMA(0, 1, At, B1); PG8_BAR; PG8_SCHED;
	s_setprio 1
	s_waitcnt lgkmcnt(0)
	v_mfma_f32_16x16x32_bf16 v[62:65], v[130:133], v[186:189], v[62:65]
	v_mfma_f32_16x16x32_bf16 v[58:61], v[162:165], v[186:189], v[58:61]
	v_mfma_f32_16x16x32_bf16 v[46:49], v[130:133], v[194:197], v[46:49]
	v_mfma_f32_16x16x32_bf16 v[42:45], v[162:165], v[194:197], v[42:45]
	v_mfma_f32_16x16x32_bf16 v[30:33], v[130:133], v[202:205], v[30:33]
	v_mfma_f32_16x16x32_bf16 v[26:29], v[162:165], v[202:205], v[26:29]
	v_mfma_f32_16x16x32_bf16 v[14:17], v[130:133], v[210:213], v[14:17]
	v_mfma_f32_16x16x32_bf16 v[10:13], v[162:165], v[210:213], v[10:13]
	v_mfma_f32_16x16x32_bf16 v[62:65], v[156:159], v[190:193], v[62:65]
	v_mfma_f32_16x16x32_bf16 v[58:61], v[166:169], v[190:193], v[58:61]
	v_mfma_f32_16x16x32_bf16 v[46:49], v[156:159], v[198:201], v[46:49]
	v_mfma_f32_16x16x32_bf16 v[42:45], v[166:169], v[198:201], v[42:45]
	v_mfma_f32_16x16x32_bf16 v[30:33], v[156:159], v[206:209], v[30:33]
	v_mfma_f32_16x16x32_bf16 v[26:29], v[166:169], v[206:209], v[26:29]
	v_mfma_f32_16x16x32_bf16 v[14:17], v[156:159], v[214:217], v[14:17]
	v_mfma_f32_16x16x32_bf16 v[10:13], v[166:169], v[214:217], v[10:13]
	v_mfma_f32_16x16x32_bf16 v[54:57], v[170:173], v[186:189], v[54:57]
	v_mfma_f32_16x16x32_bf16 v[50:53], v[178:181], v[186:189], v[50:53]
	v_mfma_f32_16x16x32_bf16 v[38:41], v[170:173], v[194:197], v[38:41]
	v_mfma_f32_16x16x32_bf16 v[34:37], v[178:181], v[194:197], v[34:37]
	v_mfma_f32_16x16x32_bf16 v[22:25], v[170:173], v[202:205], v[22:25]
	v_mfma_f32_16x16x32_bf16 v[18:21], v[178:181], v[202:205], v[18:21]
	v_mfma_f32_16x16x32_bf16 v[6:9], v[170:173], v[210:213], v[6:9]
	v_mfma_f32_16x16x32_bf16 v[2:5], v[178:181], v[210:213], v[2:5]
	v_mfma_f32_16x16x32_bf16 v[54:57], v[174:177], v[190:193], v[54:57]
	v_mfma_f32_16x16x32_bf16 v[50:53], v[182:185], v[190:193], v[50:53]
	v_mfma_f32_16x16x32_bf16 v[38:41], v[174:177], v[198:201], v[38:41]
	v_mfma_f32_16x16x32_bf16 v[34:37], v[182:185], v[198:201], v[34:37]
	v_mfma_f32_16x16x32_bf16 v[22:25], v[174:177], v[206:209], v[22:25]
	v_mfma_f32_16x16x32_bf16 v[18:21], v[182:185], v[206:209], v[18:21]
	v_mfma_f32_16x16x32_bf16 v[6:9], v[174:177], v[214:217], v[6:9]
	v_mfma_f32_16x16x32_bf16 v[2:5], v[182:185], v[214:217], v[2:5]
	s_setprio 0
	s_barrier
	s_add_i32 s56, 0, 0x18000
	v_add_u32_e32 v150, s56, v151
	s_add_i32 s57, 0, 0x1c000
	ds_read_b128 v[130:133], v150
	ds_read_b128 v[156:159], v150 offset:1024
	ds_read_b128 v[162:165], v150 offset:2048
	ds_read_b128 v[166:169], v150 offset:3072
	v_add_u32_e32 v150, s57, v151
	ds_read_b128 v[170:173], v150
	ds_read_b128 v[174:177], v150 offset:1024
	ds_read_b128 v[178:181], v150 offset:2048
	ds_read_b128 v[182:185], v150 offset:3072
	s_add_u32 s26, s26, s10
	s_addc_u32 s27, s27, s11
	s_mov_b32 m0, s42
	v_lshl_add_u64 v[246:247], s[26:27], 0, v[134:135]
	ds_read_b128 v[186:189], v161 offset:32768
	ds_read_b128 v[190:193], v161 offset:33792
	ds_read_b128 v[194:197], v161 offset:34816
	ds_read_b128 v[198:201], v161 offset:35840
	ds_read_b128 v[202:205], v161 offset:36864
	ds_read_b128 v[206:209], v161 offset:37888
	ds_read_b128 v[210:213], v161 offset:38912
	ds_read_b128 v[214:217], v161 offset:39936
	global_load_lds_dwordx4 v[246:247], off
	v_lshl_add_u64 v[246:247], s[26:27], 0, v[138:139]
	s_mov_b32 m0, s43
	s_nop 0
	global_load_lds_dwordx4 v[246:247], off
	s_waitcnt vmcnt(8)
	s_waitcnt lgkmcnt(0)
	s_barrier
	s_setprio 1
	s_waitcnt lgkmcnt(0)
	v_mfma_f32_16x16x32_bf16 v[122:125], v[130:133], v[186:189], v[122:125]
	v_mfma_f32_16x16x32_bf16 v[126:129], v[162:165], v[186:189], v[126:129]
	v_mfma_f32_16x16x32_bf16 v[110:113], v[130:133], v[194:197], v[110:113]
	v_mfma_f32_16x16x32_bf16 v[106:109], v[162:165], v[194:197], v[106:109]
	v_mfma_f32_16x16x32_bf16 v[94:97], v[130:133], v[202:205], v[94:97]
	v_mfma_f32_16x16x32_bf16 v[90:93], v[162:165], v[202:205], v[90:93]
	v_mfma_f32_16x16x32_bf16 v[78:81], v[130:133], v[210:213], v[78:81]
	v_mfma_f32_16x16x32_bf16 v[74:77], v[162:165], v[210:213], v[74:77]
	v_mfma_f32_16x16x32_bf16 v[122:125], v[156:159], v[190:193], v[122:125]
	v_mfma_f32_16x16x32_bf16 v[126:129], v[166:169], v[190:193], v[126:129]
	v_mfma_f32_16x16x32_bf16 v[110:113], v[156:159], v[198:201], v[110:113]
	v_mfma_f32_16x16x32_bf16 v[106:109], v[166:169], v[198:201], v[106:109]
	v_mfma_f32_16x16x32_bf16 v[94:97], v[156:159], v[206:209], v[94:97]
	v_mfma_f32_16x16x32_bf16 v[90:93], v[166:169], v[206:209], v[90:93]
	v_mfma_f32_16x16x32_bf16 v[78:81], v[156:159], v[214:217], v[78:81]
	v_mfma_f32_16x16x32_bf16 v[74:77], v[166:169], v[214:217], v[74:77]
	v_mfma_f32_16x16x32_bf16 v[118:121], v[170:173], v[186:189], v[118:121]
	v_mfma_f32_16x16x32_bf16 v[114:117], v[178:181], v[186:189], v[114:117]
	v_mfma_f32_16x16x32_bf16 v[102:105], v[170:173], v[194:197], v[102:105]
	v_mfma_f32_16x16x32_bf16 v[98:101], v[178:181], v[194:197], v[98:101]
	v_mfma_f32_16x16x32_bf16 v[86:89], v[170:173], v[202:205], v[86:89]
	v_mfma_f32_16x16x32_bf16 v[82:85], v[178:181], v[202:205], v[82:85]
	v_mfma_f32_16x16x32_bf16 v[70:73], v[170:173], v[210:213], v[70:73]
	v_mfma_f32_16x16x32_bf16 v[66:69], v[178:181], v[210:213], v[66:69]
	v_mfma_f32_16x16x32_bf16 v[118:121], v[174:177], v[190:193], v[118:121]
	v_mfma_f32_16x16x32_bf16 v[114:117], v[182:185], v[190:193], v[114:117]
	v_mfma_f32_16x16x32_bf16 v[102:105], v[174:177], v[198:201], v[102:105]
	v_mfma_f32_16x16x32_bf16 v[98:101], v[182:185], v[198:201], v[98:101]
	v_mfma_f32_16x16x32_bf16 v[86:89], v[174:177], v[206:209], v[86:89]
	v_mfma_f32_16x16x32_bf16 v[82:85], v[182:185], v[206:209], v[82:85]
	v_mfma_f32_16x16x32_bf16 v[70:73], v[174:177], v[214:217], v[70:73]
	v_mfma_f32_16x16x32_bf16 v[66:69], v[182:185], v[214:217], v[66:69]
	s_setprio 0
	s_barrier
; #define PG8_STAGE(bufoff, gbase, voff) do { _Pragma("unroll") for (int _i = 0; _i < 2; ++_i) \
;         __builtin_amdgcn_global_load_lds((const unsigned*)((const char*)(gbase) + (voff)[_i]), (PG8_LAS unsigned*)(lds + (bufoff) + ldsw + _i * 8192), 16, 0, 0); } while (0)
; #define PG8_LDA(dst, b, h) do { _Pragma("unroll") for (int m = 0; m < 4; ++m) _Pragma("unroll") for (int k = 0; k < 2; ++k) dst[m][k] = *(const PG8_LAS bf16x8*)(lds + PG8_SA(b, h) + aoff + m * 2048 + k * 1024); } while (0)
; #define PG8_MMA(ai, bj, At, Bt) do { __builtin_amdgcn_s_setprio(1); _Pragma("unroll") for (int m = 0; m < 4; ++m) _Pragma("unroll") for (int n = 0; n < 2; ++n) _Pragma("unroll") for (int k = 0; k < 2; ++k) \
;         acc[ai][bj][m][n] = __builtin_amdgcn_mfma_f32_16x16x32_bf16(Bt[n][k], At[m][k], acc[ai][bj][m][n], 0, 0, 0); __builtin_amdgcn_s_setprio(0); } while (0)
; #define PG8_WAIT_V(n) asm volatile("s_waitcnt vmcnt(" #n ")" ::: "memory")
; #define PG8_WAIT_L(n) asm volatile("s_waitcnt lgkmcnt(" #n ")" ::: "memory")
; #define PG8_BAR __builtin_amdgcn_s_barrier()
; #define PG8_SCHED __builtin_amdgcn_sched_barrier(0)
; template <class Epi, class Sched, bool ALIGN_EPI = false, bool SP2 = false>
; __device__ __forceinline__ void gemm_phase(PG8_LAS unsigned char* lds, const Gemm g, const Sched& S, const Epi& E) {
;     ...
;         for (int t = 0; t < nt; t += 2) {
;             const bool last = (t == nt - 2);
;             const char* a1 = cA + (size_t)(t + 1) * kstep;
;             const char* a2 = last ? nA : cA + (size_t)(t + 2) * kstep; const char* b2 = last ? nB : cB + (size_t)(t + 2) * kstep;
;     ...
;             PG8_LDA(At, 1, 1); PG8_STAGE(PG8_SB(1, 0), b3, voffB); PG8_STAGE(PG8_SB(1, 1), b3 + hstep, voffB); PG8_STAGE(PG8_SA(1, 0), a3, voffA);
;             PG8_WAIT_V(8); PG8_WAIT_L(0); PG8_BAR; PG8_MMA(1, 0, At, B0); PG8_MMA(1, 1, At, B1); PG8_BAR; PG8_SCHED;
	s_add_i32 s26, s56, s35
	v_lshl_add_u64 v[148:149], v[148:149], 0, s[92:93]
	s_mov_b32 m0, s26
	ds_read_b128 v[186:189], v161 offset:49152
	ds_read_b128 v[190:193], v161 offset:50176
	ds_read_b128 v[194:197], v161 offset:51200
	ds_read_b128 v[198:201], v161 offset:52224
	ds_read_b128 v[202:205], v161 offset:53248
	ds_read_b128 v[206:209], v161 offset:54272
	ds_read_b128 v[210:213], v161 offset:55296
	ds_read_b128 v[214:217], v161 offset:56320
	global_load_lds_dwordx4 v[148:149], off
	v_lshl_add_u64 v[148:149], v[152:153], 0, s[92:93]
	s_add_i32 m0, s26, 0x2000
	s_add_i32 s26, s57, s35
	global_load_lds_dwordx4 v[148:149], off
	v_lshl_add_u64 v[148:149], v[218:219], 0, s[92:93]
	s_mov_b32 m0, s26
	s_nop 0
	global_load_lds_dwordx4 v[148:149], off
	v_lshl_add_u64 v[148:149], v[228:229], 0, s[92:93]
	s_add_i32 m0, s26, 0x2000
	s_nop 0
	global_load_lds_dwordx4 v[148:149], off
	v_lshl_add_u64 v[148:149], v[242:243], 0, s[92:93]
	s_mov_b32 m0, s44
	s_nop 0
	global_load_lds_dwordx4 v[148:149], off
	v_lshl_add_u64 v[148:149], v[244:245], 0, s[92:93]
	s_mov_b32 m0, s45
	s_nop 0
	global_load_lds_dwordx4 v[148:149], off
	s_waitcnt vmcnt(8)
	s_waitcnt lgkmcnt(0)
	s_barrier
	s_setprio 1
	s_waitcnt lgkmcnt(0)
	v_mfma_f32_16x16x32_bf16 v[62:65], v[130:133], v[186:189], v[62:65]
	v_mfma_f32_16x16x32_bf16 v[58:61], v[162:165], v[186:189], v[58:61]
	v_mfma_f32_16x16x32_bf16 v[46:49], v[130:133], v[194:197], v[46:49]
	v_mfma_f32_16x16x32_bf16 v[42:45], v[162:165], v[194:197], v[42:45]
	v_mfma_f32_16x16x32_bf16 v[30:33], v[130:133], v[202:205], v[30:33]
	v_mfma_f32_16x16x32_bf16 v[26:29], v[162:165], v[202:205], v[26:29]
	v_mfma_f32_16x16x32_bf16 v[14:17], v[130:133], v[210:213], v[14:17]
	v_mfma_f32_16x16x32_bf16 v[10:13], v[162:165], v[210:213], v[10:13]
	v_mfma_f32_16x16x32_bf16 v[62:65], v[156:159], v[190:193], v[62:65]
	v_mfma_f32_16x16x32_bf16 v[58:61], v[166:169], v[190:193], v[58:61]
	v_mfma_f32_16x16x32_bf16 v[46:49], v[156:159], v[198:201], v[46:49]
	v_mfma_f32_16x16x32_bf16 v[42:45], v[166:169], v[198:201], v[42:45]
	v_mfma_f32_16x16x32_bf16 v[30:33], v[156:159], v[206:209], v[30:33]
	v_mfma_f32_16x16x32_bf16 v[26:29], v[166:169], v[206:209], v[26:29]
	v_mfma_f32_16x16x32_bf16 v[14:17], v[156:159], v[214:217], v[14:17]
	v_mfma_f32_16x16x32_bf16 v[10:13], v[166:169], v[214:217], v[10:13]
	v_mfma_f32_16x16x32_bf16 v[54:57], v[170:173], v[186:189], v[54:57]
	v_mfma_f32_16x16x32_bf16 v[50:53], v[178:181], v[186:189], v[50:53]
	v_mfma_f32_16x16x32_bf16 v[38:41], v[170:173], v[194:197], v[38:41]
	v_mfma_f32_16x16x32_bf16 v[34:37], v[178:181], v[194:197], v[34:37]
	v_mfma_f32_16x16x32_bf16 v[22:25], v[170:173], v[202:205], v[22:25]
	v_mfma_f32_16x16x32_bf16 v[18:21], v[178:181], v[202:205], v[18:21]
	v_mfma_f32_16x16x32_bf16 v[6:9], v[170:173], v[210:213], v[6:9]
	v_mfma_f32_16x16x32_bf16 v[2:5], v[178:181], v[210:213], v[2:5]
	v_mfma_f32_16x16x32_bf16 v[54:57], v[174:177], v[190:193], v[54:57]
	v_mfma_f32_16x16x32_bf16 v[50:53], v[182:185], v[190:193], v[50:53]
	v_mfma_f32_16x16x32_bf16 v[38:41], v[174:177], v[198:201], v[38:41]
	v_mfma_f32_16x16x32_bf16 v[34:37], v[182:185], v[198:201], v[34:37]
	v_mfma_f32_16x16x32_bf16 v[22:25], v[174:177], v[206:209], v[22:25]
	v_mfma_f32_16x16x32_bf16 v[18:21], v[182:185], v[206:209], v[18:21]
	v_mfma_f32_16x16x32_bf16 v[6:9], v[174:177], v[214:217], v[6:9]
	v_mfma_f32_16x16x32_bf16 v[2:5], v[182:185], v[214:217], v[2:5]
	s_setprio 0
	s_barrier
	s_add_u32 s53, s53, 0x100
	s_addc_u32 s54, s54, 0
	s_add_u32 s24, s24, 0x100
	s_addc_u32 s25, s25, 0
	s_cmp_ge_i32 s55, s46
	s_mov_b32 s26, s55
	s_cbranch_scc0 .LBB0_4845

; #define PG8_STAGE(bufoff, gbase, voff) do { _Pragma("unroll") for (int _i = 0; _i < 2; ++_i) \
;         __builtin_amdgcn_global_load_lds((const unsigned*)((const char*)(gbase) + (voff)[_i]), (PG8_LAS unsigned*)(lds + (bufoff) + ldsw + _i * 8192), 16, 0, 0); } while (0)
; #define PG8_LDA(dst, b, h) do { _Pragma("unroll") for (int m = 0; m < 4; ++m) _Pragma("unroll") for (int k = 0; k < 2; ++k) dst[m][k] = *(const PG8_LAS bf16x8*)(lds + PG8_SA(b, h) + aoff + m * 2048 + k * 1024); } while (0)
; #define PG8_LDB(dst, b, h) do { _Pragma("unroll") for (int n = 0; n < 2; ++n) _Pragma("unroll") for (int k = 0; k < 2; ++k) dst[n][k] = *(const PG8_LAS bf16x8*)(lds + PG8_SB(b, h) + boff + n * 2048 + k * 1024); } while (0)
; #define PG8_MMA(ai, bj, At, Bt) do { __builtin_amdgcn_s_setprio(1); _Pragma("unroll") for (int m = 0; m < 4; ++m) _Pragma("unroll") for (int n = 0; n < 2; ++n) _Pragma("unroll") for (int k = 0; k < 2; ++k) \
;         acc[ai][bj][m][n] = __builtin_amdgcn_mfma_f32_16x16x32_bf16(Bt[n][k], At[m][k], acc[ai][bj][m][n], 0, 0, 0); __builtin_amdgcn_s_setprio(0); } while (0)
; #define PG8_WAIT_V(n) asm volatile("s_waitcnt vmcnt(" #n ")" ::: "memory")
; #define PG8_BAR __builtin_amdgcn_s_barrier()
; template <class Epi, class Sched, bool ALIGN_EPI = false, bool SP2 = false>
; __device__ __forceinline__ void gemm_phase(PG8_LAS unsigned char* lds, const Gemm g, const Sched& S, const Epi& E) {
;     ...
;         for (int t = 0; t < nt; t += 2) {
;             const bool last = (t == nt - 2);
;             const char* a1 = cA + (size_t)(t + 1) * kstep;
;             const char* a2 = last ? nA : cA + (size_t)(t + 2) * kstep; const char* b2 = last ? nB : cB + (size_t)(t + 2) * kstep;
;             const char* a3 = a2 + kstep; const char* b3 = b2 + kstep;
;             if (last && has_next) S.a_ready(nxt);
;             if constexpr (SP2) {
;             PG8_LDB(B0, 0, 0); PG8_LDB(B1, 0, 1); PG8_SCHED; PG8_LDA(At, 0, 0); PG8_STAGE(PG8_SA(1, 1), a1 + hstep, voffA);
;             PG8_WAIT_V(8); PG8_WAIT_L(0); PG8_BAR; PG8_MMA(0, 0, At, B0); PG8_MMA(0, 1, At, B1); PG8_BAR; PG8_SCHED;
;             PG8_LDA(At, 0, 1); PG8_STAGE(PG8_SB(0, 0), b2, voffB); PG8_STAGE(PG8_SB(0, 1), b2 + hstep, voffB); PG8_STAGE(PG8_SA(0, 0), a2, voffA);
;             PG8_WAIT_V(8); PG8_WAIT_L(0); PG8_BAR; PG8_MMA(1, 0, At, B0); PG8_MMA(1, 1, At, B1); PG8_BAR; PG8_SCHED;
.LBB0_4928:
	s_add_i32 s61, s34, 2
	s_add_u32 s62, s30, 0x80
	s_addc_u32 s35, s31, 0
	s_add_i32 s64, 0, 0x10000
	s_cmp_eq_u32 s46, s34
	s_cselect_b32 s35, s1, s35
	s_cselect_b32 s34, s0, s62
	s_cselect_b32 s63, s29, s60
	s_cselect_b32 s62, s28, s59
	s_add_i32 s65, 0, 0x14000
	v_add_u32_e32 v154, s64, v242
	v_add_u32_e32 v170, s65, v242
	ds_read_b128 v[142:145], v154
	ds_read_b128 v[146:149], v154 offset:1024
	ds_read_b128 v[150:153], v154 offset:2048
	ds_read_b128 v[154:157], v154 offset:3072
	ds_read_b128 v[158:161], v170
	ds_read_b128 v[162:165], v170 offset:1024
	ds_read_b128 v[166:169], v170 offset:2048
	ds_read_b128 v[170:173], v170 offset:3072
	v_lshl_add_u64 v[206:207], s[30:31], 0, v[140:141]
	s_add_i32 m0, s38, 0xc000
	ds_read_b128 v[174:177], v244
	ds_read_b128 v[178:181], v244 offset:1024
	ds_read_b128 v[182:185], v244 offset:2048
	ds_read_b128 v[186:189], v244 offset:3072
	ds_read_b128 v[190:193], v244 offset:4096
	ds_read_b128 v[194:197], v244 offset:5120
	ds_read_b128 v[198:201], v244 offset:6144
	ds_read_b128 v[202:205], v244 offset:7168
	global_load_lds_dwordx4 v[206:207], off
	v_lshl_add_u64 v[206:207], s[30:31], 0, v[138:139]
	s_add_i32 m0, s38, 0xe000
	s_nop 0
	global_load_lds_dwordx4 v[206:207], off
	s_waitcnt vmcnt(8)
	s_waitcnt lgkmcnt(0)
	s_barrier
	s_setprio 1
	s_waitcnt lgkmcnt(0)
	v_mfma_f32_16x16x32_bf16 v[126:129], v[142:145], v[174:177], v[126:129]
	v_mfma_f32_16x16x32_bf16 v[122:125], v[150:153], v[174:177], v[122:125]
	v_mfma_f32_16x16x32_bf16 v[118:121], v[142:145], v[182:185], v[118:121]
	v_mfma_f32_16x16x32_bf16 v[114:117], v[150:153], v[182:185], v[114:117]
	v_mfma_f32_16x16x32_bf16 v[106:109], v[142:145], v[190:193], v[106:109]
	v_mfma_f32_16x16x32_bf16 v[98:101], v[150:153], v[190:193], v[98:101]
	v_mfma_f32_16x16x32_bf16 v[90:93], v[142:145], v[198:201], v[90:93]
	v_mfma_f32_16x16x32_bf16 v[82:85], v[150:153], v[198:201], v[82:85]
	v_mfma_f32_16x16x32_bf16 v[126:129], v[146:149], v[178:181], v[126:129]
	v_mfma_f32_16x16x32_bf16 v[122:125], v[154:157], v[178:181], v[122:125]
	v_mfma_f32_16x16x32_bf16 v[118:121], v[146:149], v[186:189], v[118:121]
	v_mfma_f32_16x16x32_bf16 v[114:117], v[154:157], v[186:189], v[114:117]
	v_mfma_f32_16x16x32_bf16 v[106:109], v[146:149], v[194:197], v[106:109]
	v_mfma_f32_16x16x32_bf16 v[98:101], v[154:157], v[194:197], v[98:101]
	v_mfma_f32_16x16x32_bf16 v[90:93], v[146:149], v[202:205], v[90:93]
	v_mfma_f32_16x16x32_bf16 v[82:85], v[154:157], v[202:205], v[82:85]
	v_mfma_f32_16x16x32_bf16 v[110:113], v[158:161], v[174:177], v[110:113]
	v_mfma_f32_16x16x32_bf16 v[102:105], v[166:169], v[174:177], v[102:105]
	v_mfma_f32_16x16x32_bf16 v[94:97], v[158:161], v[182:185], v[94:97]
	v_mfma_f32_16x16x32_bf16 v[86:89], v[166:169], v[182:185], v[86:89]
	v_mfma_f32_16x16x32_bf16 v[78:81], v[158:161], v[190:193], v[78:81]
	v_mfma_f32_16x16x32_bf16 v[74:77], v[166:169], v[190:193], v[74:77]
	v_mfma_f32_16x16x32_bf16 v[70:73], v[158:161], v[198:201], v[70:73]
	v_mfma_f32_16x16x32_bf16 v[66:69], v[166:169], v[198:201], v[66:69]
	v_mfma_f32_16x16x32_bf16 v[110:113], v[162:165], v[178:181], v[110:113]
	v_mfma_f32_16x16x32_bf16 v[102:105], v[170:173], v[178:181], v[102:105]
	v_mfma_f32_16x16x32_bf16 v[94:97], v[162:165], v[186:189], v[94:97]
	v_mfma_f32_16x16x32_bf16 v[86:89], v[170:173], v[186:189], v[86:89]
	v_mfma_f32_16x16x32_bf16 v[78:81], v[162:165], v[194:197], v[78:81]
	v_mfma_f32_16x16x32_bf16 v[74:77], v[170:173], v[194:197], v[74:77]
	v_mfma_f32_16x16x32_bf16 v[70:73], v[162:165], v[202:205], v[70:73]
	v_mfma_f32_16x16x32_bf16 v[66:69], v[170:173], v[202:205], v[66:69]
	s_setprio 0
	s_barrier
	s_add_i32 s64, s64, s37
	v_lshl_add_u64 v[206:207], s[62:63], 0, v[132:133]
	s_mov_b32 m0, s64
	ds_read_b128 v[174:177], v244 offset:16384
	ds_read_b128 v[178:181], v244 offset:17408
	ds_read_b128 v[182:185], v244 offset:18432
	ds_read_b128 v[186:189], v244 offset:19456
	ds_read_b128 v[190:193], v244 offset:20480
	ds_read_b128 v[194:197], v244 offset:21504
	ds_read_b128 v[198:201], v244 offset:22528
	ds_read_b128 v[202:205], v244 offset:23552
	global_load_lds_dwordx4 v[206:207], off
	s_add_i32 m0, s64, 0x2000
	v_lshl_add_u64 v[208:209], s[62:63], 0, v[136:137]
	s_add_u32 s62, s62, s16
	s_addc_u32 s63, s63, s17
	s_add_i32 s64, s65, s37
	global_load_lds_dwordx4 v[208:209], off
	v_lshl_add_u64 v[210:211], s[62:63], 0, v[132:133]
	s_mov_b32 m0, s64
	v_lshl_add_u64 v[212:213], s[62:63], 0, v[136:137]
	global_load_lds_dwordx4 v[210:211], off
	s_add_i32 m0, s64, 0x2000
	v_lshl_add_u64 v[214:215], s[34:35], 0, v[130:131]
	global_load_lds_dwordx4 v[212:213], off
	s_mov_b32 m0, s38
	v_lshl_add_u64 v[216:217], s[34:35], 0, v[134:135]
	global_load_lds_dwordx4 v[214:215], off
	s_mov_b32 m0, s39
	s_nop 0
	global_load_lds_dwordx4 v[216:217], off
	s_waitcnt vmcnt(8)
	s_waitcnt lgkmcnt(0)
	s_barrier
; #define PG8_STAGE(bufoff, gbase, voff) do { _Pragma("unroll") for (int _i = 0; _i < 2; ++_i) \
;         __builtin_amdgcn_global_load_lds((const unsigned*)((const char*)(gbase) + (voff)[_i]), (PG8_LAS unsigned*)(lds + (bufoff) + ldsw + _i * 8192), 16, 0, 0); } while (0)
; #define PG8_LDA(dst, b, h) do { _Pragma("unroll") for (int m = 0; m < 4; ++m) _Pragma("unroll") for (int k = 0; k < 2; ++k) dst[m][k] = *(const PG8_LAS bf16x8*)(lds + PG8_SA(b, h) + aoff + m * 2048 + k * 1024); } while (0)
; #define PG8_LDB(dst, b, h) do { _Pragma("unroll") for (int n = 0; n < 2; ++n) _Pragma("unroll") for (int k = 0; k < 2; ++k) dst[n][k] = *(const PG8_LAS bf16x8*)(lds + PG8_SB(b, h) + boff + n * 2048 + k * 1024); } while (0)
; #define PG8_MMA(ai, bj, At, Bt) do { __builtin_amdgcn_s_setprio(1); _Pragma("unroll") for (int m = 0; m < 4; ++m) _Pragma("unroll") for (int n = 0; n < 2; ++n) _Pragma("unroll") for (int k = 0; k < 2; ++k) \
;         acc[ai][bj][m][n] = __builtin_amdgcn_mfma_f32_16x16x32_bf16(Bt[n][k], At[m][k], acc[ai][bj][m][n], 0, 0, 0); __builtin_amdgcn_s_setprio(0); } while (0)
; #define PG8_WAIT_V(n) asm volatile("s_waitcnt vmcnt(" #n ")" ::: "memory")
; #define PG8_WAIT_L(n) asm volatile("s_waitcnt lgkmcnt(" #n ")" ::: "memory")
; #define PG8_BAR __builtin_amdgcn_s_barrier()
; #define PG8_SCHED __builtin_amdgcn_sched_barrier(0)
; template <class Epi, class Sched, bool ALIGN_EPI = false, bool SP2 = false>
; __device__ __forceinline__ void gemm_phase(PG8_LAS unsigned char* lds, const Gemm g, const Sched& S, const Epi& E) {
;     ...
;             PG8_WAIT_V(8); PG8_WAIT_L(0); PG8_BAR; PG8_MMA(1, 0, At, B0); PG8_MMA(1, 1, At, B1); PG8_BAR; PG8_SCHED;
;             PG8_LDB(B0, 1, 0); PG8_LDB(B1, 1, 1); PG8_SCHED; PG8_LDA(At, 1, 0); PG8_STAGE(PG8_SA(0, 1), a2 + hstep, voffA);
;             PG8_WAIT_V(8); PG8_WAIT_L(0); PG8_BAR; PG8_MMA(0, 0, At, B0); PG8_MMA(0, 1, At, B1); PG8_BAR; PG8_SCHED;
	s_setprio 1
	s_waitcnt lgkmcnt(0)
	v_mfma_f32_16x16x32_bf16 v[62:65], v[142:145], v[174:177], v[62:65]
	v_mfma_f32_16x16x32_bf16 v[58:61], v[150:153], v[174:177], v[58:61]
	v_mfma_f32_16x16x32_bf16 v[54:57], v[142:145], v[182:185], v[54:57]
	v_mfma_f32_16x16x32_bf16 v[50:53], v[150:153], v[182:185], v[50:53]
	v_mfma_f32_16x16x32_bf16 v[42:45], v[142:145], v[190:193], v[42:45]
	v_mfma_f32_16x16x32_bf16 v[34:37], v[150:153], v[190:193], v[34:37]
	v_mfma_f32_16x16x32_bf16 v[26:29], v[142:145], v[198:201], v[26:29]
	v_mfma_f32_16x16x32_bf16 v[18:21], v[150:153], v[198:201], v[18:21]
	v_mfma_f32_16x16x32_bf16 v[62:65], v[146:149], v[178:181], v[62:65]
	v_mfma_f32_16x16x32_bf16 v[58:61], v[154:157], v[178:181], v[58:61]
	v_mfma_f32_16x16x32_bf16 v[54:57], v[146:149], v[186:189], v[54:57]
	v_mfma_f32_16x16x32_bf16 v[50:53], v[154:157], v[186:189], v[50:53]
	v_mfma_f32_16x16x32_bf16 v[42:45], v[146:149], v[194:197], v[42:45]
	v_mfma_f32_16x16x32_bf16 v[34:37], v[154:157], v[194:197], v[34:37]
	v_mfma_f32_16x16x32_bf16 v[26:29], v[146:149], v[202:205], v[26:29]
	v_mfma_f32_16x16x32_bf16 v[18:21], v[154:157], v[202:205], v[18:21]
	v_mfma_f32_16x16x32_bf16 v[46:49], v[158:161], v[174:177], v[46:49]
	v_mfma_f32_16x16x32_bf16 v[38:41], v[166:169], v[174:177], v[38:41]
	v_mfma_f32_16x16x32_bf16 v[30:33], v[158:161], v[182:185], v[30:33]
	v_mfma_f32_16x16x32_bf16 v[22:25], v[166:169], v[182:185], v[22:25]
	v_mfma_f32_16x16x32_bf16 v[14:17], v[158:161], v[190:193], v[14:17]
	v_mfma_f32_16x16x32_bf16 v[10:13], v[166:169], v[190:193], v[10:13]
	v_mfma_f32_16x16x32_bf16 v[6:9], v[158:161], v[198:201], v[6:9]
	v_mfma_f32_16x16x32_bf16 v[2:5], v[166:169], v[198:201], v[2:5]
	v_mfma_f32_16x16x32_bf16 v[46:49], v[162:165], v[178:181], v[46:49]
	v_mfma_f32_16x16x32_bf16 v[38:41], v[170:173], v[178:181], v[38:41]
	v_mfma_f32_16x16x32_bf16 v[30:33], v[162:165], v[186:189], v[30:33]
	v_mfma_f32_16x16x32_bf16 v[22:25], v[170:173], v[186:189], v[22:25]
	v_mfma_f32_16x16x32_bf16 v[14:17], v[162:165], v[194:197], v[14:17]
	v_mfma_f32_16x16x32_bf16 v[10:13], v[170:173], v[194:197], v[10:13]
	v_mfma_f32_16x16x32_bf16 v[6:9], v[162:165], v[202:205], v[6:9]
	v_mfma_f32_16x16x32_bf16 v[2:5], v[170:173], v[202:205], v[2:5]
	s_setprio 0
	s_barrier
	s_add_i32 s62, 0, 0x18000
	s_add_i32 s63, 0, 0x1c000
	v_add_u32_e32 v154, s62, v242
	v_add_u32_e32 v170, s63, v242
	ds_read_b128 v[142:145], v154
	ds_read_b128 v[146:149], v154 offset:1024
	ds_read_b128 v[150:153], v154 offset:2048
	ds_read_b128 v[154:157], v154 offset:3072
	ds_read_b128 v[158:161], v170
	ds_read_b128 v[162:165], v170 offset:1024
	ds_read_b128 v[166:169], v170 offset:2048
	ds_read_b128 v[170:173], v170 offset:3072
	s_add_u32 s34, s34, s16
	s_addc_u32 s35, s35, s17
	s_mov_b32 m0, s40
	v_lshl_add_u64 v[218:219], s[34:35], 0, v[130:131]
	ds_read_b128 v[174:177], v244 offset:32768
	ds_read_b128 v[178:181], v244 offset:33792
	ds_read_b128 v[182:185], v244 offset:34816
	ds_read_b128 v[186:189], v244 offset:35840
	ds_read_b128 v[190:193], v244 offset:36864
	ds_read_b128 v[194:197], v244 offset:37888
	ds_read_b128 v[198:201], v244 offset:38912
	ds_read_b128 v[202:205], v244 offset:39936
	global_load_lds_dwordx4 v[218:219], off
	v_lshl_add_u64 v[218:219], s[34:35], 0, v[134:135]
	s_mov_b32 m0, s41
	s_nop 0
	global_load_lds_dwordx4 v[218:219], off
	s_waitcnt vmcnt(8)
	s_waitcnt lgkmcnt(0)
	s_barrier
	s_setprio 1
	s_waitcnt lgkmcnt(0)
	v_mfma_f32_16x16x32_bf16 v[126:129], v[142:145], v[174:177], v[126:129]
	v_mfma_f32_16x16x32_bf16 v[122:125], v[150:153], v[174:177], v[122:125]
	v_mfma_f32_16x16x32_bf16 v[118:121], v[142:145], v[182:185], v[118:121]
	v_mfma_f32_16x16x32_bf16 v[114:117], v[150:153], v[182:185], v[114:117]
	v_mfma_f32_16x16x32_bf16 v[106:109], v[142:145], v[190:193], v[106:109]
	v_mfma_f32_16x16x32_bf16 v[98:101], v[150:153], v[190:193], v[98:101]
	v_mfma_f32_16x16x32_bf16 v[90:93], v[142:145], v[198:201], v[90:93]
	v_mfma_f32_16x16x32_bf16 v[82:85], v[150:153], v[198:201], v[82:85]
	v_mfma_f32_16x16x32_bf16 v[126:129], v[146:149], v[178:181], v[126:129]
	v_mfma_f32_16x16x32_bf16 v[122:125], v[154:157], v[178:181], v[122:125]
	v_mfma_f32_16x16x32_bf16 v[118:121], v[146:149], v[186:189], v[118:121]
	v_mfma_f32_16x16x32_bf16 v[114:117], v[154:157], v[186:189], v[114:117]
	v_mfma_f32_16x16x32_bf16 v[106:109], v[146:149], v[194:197], v[106:109]
	v_mfma_f32_16x16x32_bf16 v[98:101], v[154:157], v[194:197], v[98:101]
	v_mfma_f32_16x16x32_bf16 v[90:93], v[146:149], v[202:205], v[90:93]
	v_mfma_f32_16x16x32_bf16 v[82:85], v[154:157], v[202:205], v[82:85]
	v_mfma_f32_16x16x32_bf16 v[110:113], v[158:161], v[174:177], v[110:113]
	v_mfma_f32_16x16x32_bf16 v[102:105], v[166:169], v[174:177], v[102:105]
	v_mfma_f32_16x16x32_bf16 v[94:97], v[158:161], v[182:185], v[94:97]
	v_mfma_f32_16x16x32_bf16 v[86:89], v[166:169], v[182:185], v[86:89]
	v_mfma_f32_16x16x32_bf16 v[78:81], v[158:161], v[190:193], v[78:81]
	v_mfma_f32_16x16x32_bf16 v[74:77], v[166:169], v[190:193], v[74:77]
	v_mfma_f32_16x16x32_bf16 v[70:73], v[158:161], v[198:201], v[70:73]
	v_mfma_f32_16x16x32_bf16 v[66:69], v[166:169], v[198:201], v[66:69]
	v_mfma_f32_16x16x32_bf16 v[110:113], v[162:165], v[178:181], v[110:113]
	v_mfma_f32_16x16x32_bf16 v[102:105], v[170:173], v[178:181], v[102:105]
	v_mfma_f32_16x16x32_bf16 v[94:97], v[162:165], v[186:189], v[94:97]
	v_mfma_f32_16x16x32_bf16 v[86:89], v[170:173], v[186:189], v[86:89]
	v_mfma_f32_16x16x32_bf16 v[78:81], v[162:165], v[194:197], v[78:81]
	v_mfma_f32_16x16x32_bf16 v[74:77], v[170:173], v[194:197], v[74:77]
	v_mfma_f32_16x16x32_bf16 v[70:73], v[162:165], v[202:205], v[70:73]
	v_mfma_f32_16x16x32_bf16 v[66:69], v[170:173], v[202:205], v[66:69]
	s_setprio 0
	s_barrier
; #define PG8_STAGE(bufoff, gbase, voff) do { _Pragma("unroll") for (int _i = 0; _i < 2; ++_i) \
;         __builtin_amdgcn_global_load_lds((const unsigned*)((const char*)(gbase) + (voff)[_i]), (PG8_LAS unsigned*)(lds + (bufoff) + ldsw + _i * 8192), 16, 0, 0); } while (0)
; #define PG8_LDA(dst, b, h) do { _Pragma("unroll") for (int m = 0; m < 4; ++m) _Pragma("unroll") for (int k = 0; k < 2; ++k) dst[m][k] = *(const PG8_LAS bf16x8*)(lds + PG8_SA(b, h) + aoff + m * 2048 + k * 1024); } while (0)
; #define PG8_MMA(ai, bj, At, Bt) do { __builtin_amdgcn_s_setprio(1); _Pragma("unroll") for (int m = 0; m < 4; ++m) _Pragma("unroll") for (int n = 0; n < 2; ++n) _Pragma("unroll") for (int k = 0; k < 2; ++k) \
;         acc[ai][bj][m][n] = __builtin_amdgcn_mfma_f32_16x16x32_bf16(Bt[n][k], At[m][k], acc[ai][bj][m][n], 0, 0, 0); __builtin_amdgcn_s_setprio(0); } while (0)
; #define PG8_WAIT_V(n) asm volatile("s_waitcnt vmcnt(" #n ")" ::: "memory")
; #define PG8_WAIT_L(n) asm volatile("s_waitcnt lgkmcnt(" #n ")" ::: "memory")
; #define PG8_BAR __builtin_amdgcn_s_barrier()
; #define PG8_SCHED __builtin_amdgcn_sched_barrier(0)
; template <class Epi, class Sched, bool ALIGN_EPI = false, bool SP2 = false>
; __device__ __forceinline__ void gemm_phase(PG8_LAS unsigned char* lds, const Gemm g, const Sched& S, const Epi& E) {
;     ...
;         for (int t = 0; t < nt; t += 2) {
;             const bool last = (t == nt - 2);
;             const char* a1 = cA + (size_t)(t + 1) * kstep;
;             const char* a2 = last ? nA : cA + (size_t)(t + 2) * kstep; const char* b2 = last ? nB : cB + (size_t)(t + 2) * kstep;
;             const char* a3 = a2 + kstep; const char* b3 = b2 + kstep;
;     ...
;             PG8_LDA(At, 1, 1); PG8_STAGE(PG8_SB(1, 0), b3, voffB); PG8_STAGE(PG8_SB(1, 1), b3 + hstep, voffB); PG8_STAGE(PG8_SA(1, 0), a3, voffA);
;             PG8_WAIT_V(8); PG8_WAIT_L(0); PG8_BAR; PG8_MMA(1, 0, At, B0); PG8_MMA(1, 1, At, B1); PG8_BAR; PG8_SCHED;
	s_add_i32 s34, s62, s37
	v_lshl_add_u64 v[206:207], v[206:207], 0, s[92:93]
	s_mov_b32 m0, s34
	ds_read_b128 v[174:177], v244 offset:49152
	ds_read_b128 v[178:181], v244 offset:50176
	ds_read_b128 v[182:185], v244 offset:51200
	ds_read_b128 v[186:189], v244 offset:52224
	ds_read_b128 v[190:193], v244 offset:53248
	ds_read_b128 v[194:197], v244 offset:54272
	ds_read_b128 v[198:201], v244 offset:55296
	ds_read_b128 v[202:205], v244 offset:56320
	global_load_lds_dwordx4 v[206:207], off
	v_lshl_add_u64 v[206:207], v[208:209], 0, s[92:93]
	s_add_i32 m0, s34, 0x2000
	s_add_i32 s34, s63, s37
	global_load_lds_dwordx4 v[206:207], off
	v_lshl_add_u64 v[206:207], v[210:211], 0, s[92:93]
	s_mov_b32 m0, s34
	s_nop 0
	global_load_lds_dwordx4 v[206:207], off
	v_lshl_add_u64 v[206:207], v[212:213], 0, s[92:93]
	s_add_i32 m0, s34, 0x2000
	s_nop 0
	global_load_lds_dwordx4 v[206:207], off
	v_lshl_add_u64 v[206:207], v[214:215], 0, s[92:93]
	s_mov_b32 m0, s42
	s_nop 0
	global_load_lds_dwordx4 v[206:207], off
	v_lshl_add_u64 v[206:207], v[216:217], 0, s[92:93]
	s_mov_b32 m0, s43
	s_nop 0
	global_load_lds_dwordx4 v[206:207], off
	s_waitcnt vmcnt(8)
	s_waitcnt lgkmcnt(0)
	s_barrier
	s_setprio 1
	s_waitcnt lgkmcnt(0)
	v_mfma_f32_16x16x32_bf16 v[62:65], v[142:145], v[174:177], v[62:65]
	v_mfma_f32_16x16x32_bf16 v[58:61], v[150:153], v[174:177], v[58:61]
	v_mfma_f32_16x16x32_bf16 v[54:57], v[142:145], v[182:185], v[54:57]
	v_mfma_f32_16x16x32_bf16 v[50:53], v[150:153], v[182:185], v[50:53]
	v_mfma_f32_16x16x32_bf16 v[42:45], v[142:145], v[190:193], v[42:45]
	v_mfma_f32_16x16x32_bf16 v[34:37], v[150:153], v[190:193], v[34:37]
	v_mfma_f32_16x16x32_bf16 v[26:29], v[142:145], v[198:201], v[26:29]
	v_mfma_f32_16x16x32_bf16 v[18:21], v[150:153], v[198:201], v[18:21]
	v_mfma_f32_16x16x32_bf16 v[62:65], v[146:149], v[178:181], v[62:65]
	v_mfma_f32_16x16x32_bf16 v[58:61], v[154:157], v[178:181], v[58:61]
	v_mfma_f32_16x16x32_bf16 v[54:57], v[146:149], v[186:189], v[54:57]
	v_mfma_f32_16x16x32_bf16 v[50:53], v[154:157], v[186:189], v[50:53]
	v_mfma_f32_16x16x32_bf16 v[42:45], v[146:149], v[194:197], v[42:45]
	v_mfma_f32_16x16x32_bf16 v[34:37], v[154:157], v[194:197], v[34:37]
	v_mfma_f32_16x16x32_bf16 v[26:29], v[146:149], v[202:205], v[26:29]
	v_mfma_f32_16x16x32_bf16 v[18:21], v[154:157], v[202:205], v[18:21]
	v_mfma_f32_16x16x32_bf16 v[46:49], v[158:161], v[174:177], v[46:49]
	v_mfma_f32_16x16x32_bf16 v[38:41], v[166:169], v[174:177], v[38:41]
	v_mfma_f32_16x16x32_bf16 v[30:33], v[158:161], v[182:185], v[30:33]
	v_mfma_f32_16x16x32_bf16 v[22:25], v[166:169], v[182:185], v[22:25]
	v_mfma_f32_16x16x32_bf16 v[14:17], v[158:161], v[190:193], v[14:17]
	v_mfma_f32_16x16x32_bf16 v[10:13], v[166:169], v[190:193], v[10:13]
	v_mfma_f32_16x16x32_bf16 v[6:9], v[158:161], v[198:201], v[6:9]
	v_mfma_f32_16x16x32_bf16 v[2:5], v[166:169], v[198:201], v[2:5]
	v_mfma_f32_16x16x32_bf16 v[46:49], v[162:165], v[178:181], v[46:49]
	v_mfma_f32_16x16x32_bf16 v[38:41], v[170:173], v[178:181], v[38:41]
	v_mfma_f32_16x16x32_bf16 v[30:33], v[162:165], v[186:189], v[30:33]
	v_mfma_f32_16x16x32_bf16 v[22:25], v[170:173], v[186:189], v[22:25]
	v_mfma_f32_16x16x32_bf16 v[14:17], v[162:165], v[194:197], v[14:17]
	v_mfma_f32_16x16x32_bf16 v[10:13], v[170:173], v[194:197], v[10:13]
	v_mfma_f32_16x16x32_bf16 v[6:9], v[162:165], v[202:205], v[6:9]
	v_mfma_f32_16x16x32_bf16 v[2:5], v[170:173], v[202:205], v[2:5]
	s_setprio 0
	s_barrier
	s_add_u32 s59, s59, 0x100
	s_addc_u32 s60, s60, 0
	s_add_u32 s30, s30, 0x100
	s_addc_u32 s31, s31, 0
	s_cmp_ge_i32 s61, s45
	s_mov_b32 s34, s61
	s_cbranch_scc0 .LBB0_4928
; __device__ __forceinline__ unsigned cvt_pk_bf16(float lo, float hi) { unsigned r; asm volatile("v_cvt_pk_bf16_f32 %0, %1, %2" : "=v"(r) : "v"(lo), "v"(hi)); return r; }
;     __device__ __forceinline__ void operator()(const f32x4 (&acc)[2][2][4][2], const Unit& u, int wr, int wc, int fr, int fq) const {
;     ...
;                 for (int bj = 0; bj < 2; ++bj) {
;                     f32x4* p = (f32x4*)(xr + bj * HALF);
;                     const f32x4 o0 = xv[g & 1][rr][bj][0] + acc[ai][bj][m][0] * scale, o1 = xv[g & 1][rr][bj][1] + acc[ai][bj][m][1] * scale;
;                     p[0] = o0; p[1] = o1;
;                     u32x4 w; w.x = cvt_pk_bf16(o0[0], o0[1]); w.y = cvt_pk_bf16(o0[2], o0[3]); w.z = cvt_pk_bf16(o1[0], o1[1]); w.w = cvt_pk_bf16(o1[2], o1[3]);
;                     *(u32x4*)(br + bj * HALF) = w;
;                     ss += (o0[0] * o0[0] + o0[1] * o0[1]) + (o0[2] * o0[2] + o0[3] * o0[3]) + (o1[0] * o1[0] + o1[1] * o1[1]) + (o1[2] * o1[2] + o1[3] * o1[3]);
	v_pk_mul_f32 v[206:207], v[128:129], 0.5 op_sel_hi:[1,0]
	v_pk_mul_f32 v[212:213], v[126:127], 0.5 op_sel_hi:[1,0]
	v_pk_mul_f32 v[210:211], v[124:125], 0.5 op_sel_hi:[1,0]
	v_pk_mul_f32 v[208:209], v[122:123], 0.5 op_sel_hi:[1,0]
	v_pk_mul_f32 v[202:203], v[112:113], 0.5 op_sel_hi:[1,0]
	v_pk_mul_f32 v[200:201], v[110:111], 0.5 op_sel_hi:[1,0]
	v_pk_mul_f32 v[198:199], v[104:105], 0.5 op_sel_hi:[1,0]
	v_pk_mul_f32 v[196:197], v[102:103], 0.5 op_sel_hi:[1,0]
	v_pk_mul_f32 v[190:191], v[120:121], 0.5 op_sel_hi:[1,0]
	v_pk_mul_f32 v[188:189], v[118:119], 0.5 op_sel_hi:[1,0]
	v_pk_mul_f32 v[186:187], v[116:117], 0.5 op_sel_hi:[1,0]
	v_pk_mul_f32 v[184:185], v[114:115], 0.5 op_sel_hi:[1,0]
	v_pk_mul_f32 v[182:183], v[96:97], 0.5 op_sel_hi:[1,0]
	v_pk_mul_f32 v[180:181], v[94:95], 0.5 op_sel_hi:[1,0]
	v_pk_mul_f32 v[178:179], v[88:89], 0.5 op_sel_hi:[1,0]
	v_pk_mul_f32 v[176:177], v[86:87], 0.5 op_sel_hi:[1,0]
	v_pk_mul_f32 v[174:175], v[108:109], 0.5 op_sel_hi:[1,0]
	v_pk_mul_f32 v[172:173], v[106:107], 0.5 op_sel_hi:[1,0]
	v_pk_mul_f32 v[170:171], v[100:101], 0.5 op_sel_hi:[1,0]
	v_pk_mul_f32 v[168:169], v[98:99], 0.5 op_sel_hi:[1,0]
	v_pk_mul_f32 v[166:167], v[80:81], 0.5 op_sel_hi:[1,0]
	v_pk_mul_f32 v[164:165], v[78:79], 0.5 op_sel_hi:[1,0]
	v_pk_mul_f32 v[162:163], v[76:77], 0.5 op_sel_hi:[1,0]
	v_pk_mul_f32 v[160:161], v[74:75], 0.5 op_sel_hi:[1,0]
	v_pk_mul_f32 v[158:159], v[92:93], 0.5 op_sel_hi:[1,0]
	v_pk_mul_f32 v[156:157], v[90:91], 0.5 op_sel_hi:[1,0]
	v_pk_mul_f32 v[154:155], v[84:85], 0.5 op_sel_hi:[1,0]
	v_pk_mul_f32 v[152:153], v[82:83], 0.5 op_sel_hi:[1,0]
	v_pk_mul_f32 v[150:151], v[72:73], 0.5 op_sel_hi:[1,0]
	v_pk_mul_f32 v[148:149], v[70:71], 0.5 op_sel_hi:[1,0]
	v_pk_mul_f32 v[146:147], v[68:69], 0.5 op_sel_hi:[1,0]
	v_pk_mul_f32 v[144:145], v[66:67], 0.5 op_sel_hi:[1,0]
	v_pk_mul_f32 v[128:129], v[64:65], 0.5 op_sel_hi:[1,0]
	v_pk_mul_f32 v[126:127], v[62:63], 0.5 op_sel_hi:[1,0]
	v_pk_mul_f32 v[124:125], v[60:61], 0.5 op_sel_hi:[1,0]
	v_pk_mul_f32 v[122:123], v[58:59], 0.5 op_sel_hi:[1,0]
	v_pk_mul_f32 v[120:121], v[48:49], 0.5 op_sel_hi:[1,0]
	v_pk_mul_f32 v[118:119], v[46:47], 0.5 op_sel_hi:[1,0]
	v_pk_mul_f32 v[116:117], v[40:41], 0.5 op_sel_hi:[1,0]
	v_pk_mul_f32 v[114:115], v[38:39], 0.5 op_sel_hi:[1,0]
	v_pk_mul_f32 v[112:113], v[56:57], 0.5 op_sel_hi:[1,0]
	v_pk_mul_f32 v[110:111], v[54:55], 0.5 op_sel_hi:[1,0]
	v_pk_mul_f32 v[108:109], v[52:53], 0.5 op_sel_hi:[1,0]
	v_pk_mul_f32 v[106:107], v[50:51], 0.5 op_sel_hi:[1,0]
	v_pk_mul_f32 v[104:105], v[32:33], 0.5 op_sel_hi:[1,0]
	v_pk_mul_f32 v[102:103], v[30:31], 0.5 op_sel_hi:[1,0]
	v_pk_mul_f32 v[100:101], v[24:25], 0.5 op_sel_hi:[1,0]
	v_pk_mul_f32 v[98:99], v[22:23], 0.5 op_sel_hi:[1,0]
	v_pk_mul_f32 v[96:97], v[44:45], 0.5 op_sel_hi:[1,0]
	v_pk_mul_f32 v[94:95], v[42:43], 0.5 op_sel_hi:[1,0]
	v_pk_mul_f32 v[92:93], v[36:37], 0.5 op_sel_hi:[1,0]
	v_pk_mul_f32 v[90:91], v[34:35], 0.5 op_sel_hi:[1,0]
	v_pk_mul_f32 v[88:89], v[16:17], 0.5 op_sel_hi:[1,0]
	v_pk_mul_f32 v[86:87], v[14:15], 0.5 op_sel_hi:[1,0]
	v_pk_mul_f32 v[84:85], v[12:13], 0.5 op_sel_hi:[1,0]
	v_pk_mul_f32 v[82:83], v[10:11], 0.5 op_sel_hi:[1,0]
	v_pk_mul_f32 v[80:81], v[28:29], 0.5 op_sel_hi:[1,0]
	v_pk_mul_f32 v[78:79], v[26:27], 0.5 op_sel_hi:[1,0]
	v_pk_mul_f32 v[76:77], v[20:21], 0.5 op_sel_hi:[1,0]
	v_pk_mul_f32 v[74:75], v[18:19], 0.5 op_sel_hi:[1,0]
	v_pk_mul_f32 v[72:73], v[8:9], 0.5 op_sel_hi:[1,0]
	v_pk_mul_f32 v[70:71], v[6:7], 0.5 op_sel_hi:[1,0]
	v_pk_mul_f32 v[68:69], v[4:5], 0.5 op_sel_hi:[1,0]
	v_pk_mul_f32 v[66:67], v[2:3], 0.5 op_sel_hi:[1,0]
